# phase 4 out-proj GEMM also on the shared-A tile-pair ring; in all three pair GEMMs the fragment ds_reads are issued before the LDS-DMA burst
# speedup vs baseline: 1.1400x; 1.0210x over previous
.Lfin3_tile:
	s_load_dwordx2 s[44:45], s[12:13], 0x180
	s_load_dwordx2 s[46:47], s[12:13], 0x138
	s_bfe_u32 s53, s21, 0x30006
	s_lshl_b32 s53, s53, 3
	s_and_b32 s56, s21, 7
	s_or_b32 s53, s53, s56
	s_lshl_b32 s53, s53, 7
	s_bfe_u32 s54, s21, 0x30003
	s_lshl_b32 s54, s54, 7
	v_lshrrev_b32_e32 v241, 6, v131
	v_and_b32_e32 v242, 63, v131
	s_nop 0
	v_readfirstlane_b32 s50, v241
	v_lshrrev_b32_e32 v241, 3, v242
	v_lshrrev_b32_e32 v243, 4, v242
	v_and_b32_e32 v244, 7, v242
	s_movk_i32 s56, 0x2c80
	v_xor_b32_e32 v245, v244, v243
	v_lshlrev_b32_e32 v245, 4, v245
	v_mad_u32_u24 v228, v241, s56, v245
	v_or_b32_e32 v243, 4, v243
	v_xor_b32_e32 v245, v244, v243
	v_lshlrev_b32_e32 v245, 4, v245
	v_add_u32_e32 v241, 8, v241
	v_mad_u32_u24 v230, v241, s56, v245
	v_add_u32_e32 v229, 0xb2000, v228
	v_add_u32_e32 v231, 0xb2000, v230
	v_and_b32_e32 v241, 15, v242
	v_lshrrev_b32_e32 v243, 4, v242
	v_bfe_u32 v244, v242, 1, 3
	v_xor_b32_e32 v244, v243, v244
	v_lshlrev_b32_e32 v244, 4, v244
	v_lshl_or_b32 v232, v241, 7, v244
	v_xor_b32_e32 v233, 64, v232
	s_lshr_b32 s56, s50, 1
	s_and_b32 s57, s50, 1
	s_mul_i32 s0, s56, 64*528
	s_lshl_b32 s52, s57, 8
	s_add_i32 s0, s0, s52
	s_add_i32 s0, s0, 16
	v_mul_u32_u24_e32 v243, 4*528, v243
	v_lshl_add_u32 v243, v241, 2, v243
	v_add_u32_e32 v238, s0, v243
	s_add_i32 s22, s56, 0
	s_lshl_b32 s22, s22, 13
	s_add_i32 s22, s22, 16
	s_add_i32 s28, s57, 2
	s_lshl_b32 s28, s28, 13
	s_add_i32 s28, s28, 16
	s_add_i32 s40, s57, 4
	s_lshl_b32 s40, s40, 13
	s_add_i32 s40, s40, 16
	s_add_i32 s23, s56, 6
	s_lshl_b32 s23, s23, 13
	s_add_i32 s23, s23, 16
	s_add_i32 s29, s57, 8
	s_cmp_ge_u32 s29, 9
	s_cselect_b32 s0, 9, 0
	s_sub_i32 s29, s29, s0
	s_lshl_b32 s29, s29, 13
	s_add_i32 s29, s29, 16
	s_add_i32 s41, s57, 1
	s_lshl_b32 s41, s41, 13
	s_add_i32 s41, s41, 16
	s_add_i32 s24, s56, 3
	s_lshl_b32 s24, s24, 13
	s_add_i32 s24, s24, 16
	s_add_i32 s30, s57, 5
	s_lshl_b32 s30, s30, 13
	s_add_i32 s30, s30, 16
	s_add_i32 s42, s57, 7
	s_lshl_b32 s42, s42, 13
	s_add_i32 s42, s42, 16
	s_lshl_b32 s56, s50, 4
	s_add_i32 s57, s53, s56
	s_add_i32 s56, s54, s56
	s_mul_i32 s57, s57, 0x2c80
	s_mul_i32 s56, s56, 0x2c80
	s_waitcnt lgkmcnt(0)
	s_add_u32 s44, s44, s57
	s_addc_u32 s45, s45, 0
	s_add_u32 s46, s46, s56
	s_addc_u32 s47, s47, 0
	s_add_u32 s48, s46, 0xb20000
	s_addc_u32 s49, s47, 0
	s_lshl_b32 s51, s50, 11
	s_add_i32 s51, s51, 16
	v_mov_b32_e32 v2, 0
	v_mov_b32_e32 v3, 0
	v_mov_b32_e32 v4, 0
	v_mov_b32_e32 v5, 0
	v_mov_b32_e32 v6, 0
	v_mov_b32_e32 v7, 0
	v_mov_b32_e32 v8, 0
	v_mov_b32_e32 v9, 0
	v_mov_b32_e32 v10, 0
	v_mov_b32_e32 v11, 0
	v_mov_b32_e32 v12, 0
	v_mov_b32_e32 v13, 0
	v_mov_b32_e32 v14, 0
	v_mov_b32_e32 v15, 0
	v_mov_b32_e32 v16, 0
	v_mov_b32_e32 v17, 0
	v_mov_b32_e32 v18, 0
	v_mov_b32_e32 v19, 0
	v_mov_b32_e32 v20, 0
	v_mov_b32_e32 v21, 0
	v_mov_b32_e32 v22, 0
	v_mov_b32_e32 v23, 0
	v_mov_b32_e32 v24, 0
	v_mov_b32_e32 v25, 0
	v_mov_b32_e32 v26, 0
	v_mov_b32_e32 v27, 0
	v_mov_b32_e32 v28, 0
	v_mov_b32_e32 v29, 0
	v_mov_b32_e32 v30, 0
	v_mov_b32_e32 v31, 0
	v_mov_b32_e32 v32, 0
	v_mov_b32_e32 v33, 0
	v_mov_b32_e32 v34, 0
	v_mov_b32_e32 v35, 0
	v_mov_b32_e32 v36, 0
	v_mov_b32_e32 v37, 0
	v_mov_b32_e32 v38, 0
	v_mov_b32_e32 v39, 0
	v_mov_b32_e32 v40, 0
	v_mov_b32_e32 v41, 0
	v_mov_b32_e32 v42, 0
	v_mov_b32_e32 v43, 0
	v_mov_b32_e32 v44, 0
	v_mov_b32_e32 v45, 0
	v_mov_b32_e32 v46, 0
	v_mov_b32_e32 v47, 0
	v_mov_b32_e32 v48, 0
	v_mov_b32_e32 v49, 0
	v_mov_b32_e32 v50, 0
	v_mov_b32_e32 v51, 0
	v_mov_b32_e32 v52, 0
	v_mov_b32_e32 v53, 0
	v_mov_b32_e32 v54, 0
	v_mov_b32_e32 v55, 0
	v_mov_b32_e32 v56, 0
	v_mov_b32_e32 v57, 0
	v_mov_b32_e32 v58, 0
	v_mov_b32_e32 v59, 0
	v_mov_b32_e32 v60, 0
	v_mov_b32_e32 v61, 0
	v_mov_b32_e32 v62, 0
	v_mov_b32_e32 v63, 0
	v_mov_b32_e32 v64, 0
	v_mov_b32_e32 v65, 0
	v_mov_b32_e32 v66, 0
	v_mov_b32_e32 v67, 0
	v_mov_b32_e32 v68, 0
	v_mov_b32_e32 v69, 0
	v_mov_b32_e32 v70, 0
	v_mov_b32_e32 v71, 0
	v_mov_b32_e32 v72, 0
	v_mov_b32_e32 v73, 0
	v_mov_b32_e32 v74, 0
	v_mov_b32_e32 v75, 0
	v_mov_b32_e32 v76, 0
	v_mov_b32_e32 v77, 0
	v_mov_b32_e32 v78, 0
	v_mov_b32_e32 v79, 0
	v_mov_b32_e32 v80, 0
	v_mov_b32_e32 v81, 0
	v_mov_b32_e32 v82, 0
	v_mov_b32_e32 v83, 0
	v_mov_b32_e32 v84, 0
	v_mov_b32_e32 v85, 0
	v_mov_b32_e32 v86, 0
	v_mov_b32_e32 v87, 0
	v_mov_b32_e32 v88, 0
	v_mov_b32_e32 v89, 0
	v_mov_b32_e32 v90, 0
	v_mov_b32_e32 v91, 0
	v_mov_b32_e32 v92, 0
	v_mov_b32_e32 v93, 0
	v_mov_b32_e32 v94, 0
	v_mov_b32_e32 v95, 0
	v_mov_b32_e32 v96, 0
	v_mov_b32_e32 v97, 0
	v_mov_b32_e32 v98, 0
	v_mov_b32_e32 v99, 0
	v_mov_b32_e32 v100, 0
	v_mov_b32_e32 v101, 0
	v_mov_b32_e32 v102, 0
	v_mov_b32_e32 v103, 0
	v_mov_b32_e32 v104, 0
	v_mov_b32_e32 v105, 0
	v_mov_b32_e32 v106, 0
	v_mov_b32_e32 v107, 0
	v_mov_b32_e32 v108, 0
	v_mov_b32_e32 v109, 0
	v_mov_b32_e32 v110, 0
	v_mov_b32_e32 v111, 0
	v_mov_b32_e32 v112, 0
	v_mov_b32_e32 v113, 0
	v_mov_b32_e32 v114, 0
	v_mov_b32_e32 v115, 0
	v_mov_b32_e32 v116, 0
	v_mov_b32_e32 v117, 0
	v_mov_b32_e32 v118, 0
	v_mov_b32_e32 v119, 0
	v_mov_b32_e32 v120, 0
	v_mov_b32_e32 v121, 0
	v_mov_b32_e32 v122, 0
	v_mov_b32_e32 v123, 0
	v_mov_b32_e32 v124, 0
	v_mov_b32_e32 v125, 0
	v_mov_b32_e32 v126, 0
	v_mov_b32_e32 v127, 0
	v_mov_b32_e32 v128, 0
	v_mov_b32_e32 v129, 0
	s_barrier
	s_mov_b32 m0, s51
	s_nop 0
	global_load_lds_dwordx4 v228, s[44:45]
	s_add_i32 m0, s51, 0x400
	s_nop 0
	global_load_lds_dwordx4 v230, s[44:45]
	s_add_i32 m0, s51, 0x2000
	s_nop 0
	global_load_lds_dwordx4 v229, s[44:45]
	s_add_i32 m0, s51, 0x2400
	s_nop 0
	global_load_lds_dwordx4 v231, s[44:45]
	s_add_i32 m0, s51, 0x4000
	s_nop 0
	global_load_lds_dwordx4 v228, s[46:47]
	s_add_i32 m0, s51, 0x4400
	s_nop 0
	global_load_lds_dwordx4 v230, s[46:47]
	s_add_i32 m0, s51, 0x6000
	s_nop 0
	global_load_lds_dwordx4 v229, s[46:47]
	s_add_i32 m0, s51, 0x6400
	s_nop 0
	global_load_lds_dwordx4 v231, s[46:47]
	s_add_i32 m0, s51, 0x8000
	s_nop 0
	global_load_lds_dwordx4 v228, s[48:49]
	s_add_i32 m0, s51, 0x8400
	s_nop 0
	global_load_lds_dwordx4 v230, s[48:49]
	s_add_i32 m0, s51, 0xa000
	s_nop 0
	global_load_lds_dwordx4 v229, s[48:49]
	s_add_i32 m0, s51, 0xa400
	s_nop 0
	global_load_lds_dwordx4 v231, s[48:49]
	v_add_u32_e32 v228, 0x80, v228
	v_add_u32_e32 v229, 0x80, v229
	v_add_u32_e32 v230, 0x80, v230
	v_add_u32_e32 v231, 0x80, v231
	s_waitcnt vmcnt(4)
	s_barrier
	s_mov_b32 s52, 0
.Lfin3_loop:
	v_add_u32_e32 v234, s22, v232
	v_add_u32_e32 v236, s28, v232
	v_add_u32_e32 v235, s22, v233
	v_add_u32_e32 v237, s28, v233
	ds_read_b128 v[136:139], v234
	ds_read_b128 v[140:143], v234 offset:2048
	ds_read_b128 v[144:147], v234 offset:4096
	ds_read_b128 v[148:151], v234 offset:6144
	ds_read_b128 v[188:191], v236
	ds_read_b128 v[196:199], v236 offset:2048
	ds_read_b128 v[200:203], v236 offset:4096
	ds_read_b128 v[204:207], v236 offset:6144
	ds_read_b128 v[172:175], v235
	ds_read_b128 v[176:179], v235 offset:2048
	ds_read_b128 v[180:183], v235 offset:4096
	ds_read_b128 v[184:187], v235 offset:6144
	ds_read_b128 v[212:215], v237
	ds_read_b128 v[216:219], v237 offset:2048
	ds_read_b128 v[220:223], v237 offset:4096
	ds_read_b128 v[224:227], v237 offset:6144
	s_add_i32 m0, s51, 0xc000
	s_nop 0
	global_load_lds_dwordx4 v228, s[44:45]
	s_add_i32 m0, s51, 0xc400
	s_nop 0
	global_load_lds_dwordx4 v230, s[44:45]
	s_add_i32 m0, s51, 0xe000
	s_nop 0
	global_load_lds_dwordx4 v229, s[44:45]
	s_add_i32 m0, s51, 0xe400
	s_nop 0
	global_load_lds_dwordx4 v231, s[44:45]
	s_add_i32 m0, s51, 0x10000
	s_nop 0
	global_load_lds_dwordx4 v228, s[46:47]
	s_add_i32 m0, s51, 0x10400
	s_nop 0
	global_load_lds_dwordx4 v230, s[46:47]
	s_waitcnt lgkmcnt(8)
	v_mfma_f32_16x16x32_bf16 v[2:5], v[136:139], v[188:191], v[2:5]
	v_mfma_f32_16x16x32_bf16 v[6:9], v[136:139], v[196:199], v[6:9]
	v_mfma_f32_16x16x32_bf16 v[10:13], v[136:139], v[200:203], v[10:13]
	v_mfma_f32_16x16x32_bf16 v[14:17], v[136:139], v[204:207], v[14:17]
	v_mfma_f32_16x16x32_bf16 v[18:21], v[140:143], v[188:191], v[18:21]
	v_mfma_f32_16x16x32_bf16 v[22:25], v[140:143], v[196:199], v[22:25]
	v_mfma_f32_16x16x32_bf16 v[26:29], v[140:143], v[200:203], v[26:29]
	v_mfma_f32_16x16x32_bf16 v[30:33], v[140:143], v[204:207], v[30:33]
	v_mfma_f32_16x16x32_bf16 v[34:37], v[144:147], v[188:191], v[34:37]
	v_mfma_f32_16x16x32_bf16 v[38:41], v[144:147], v[196:199], v[38:41]
	v_mfma_f32_16x16x32_bf16 v[42:45], v[144:147], v[200:203], v[42:45]
	v_mfma_f32_16x16x32_bf16 v[46:49], v[144:147], v[204:207], v[46:49]
	v_mfma_f32_16x16x32_bf16 v[50:53], v[148:151], v[188:191], v[50:53]
	v_mfma_f32_16x16x32_bf16 v[54:57], v[148:151], v[196:199], v[54:57]
	v_mfma_f32_16x16x32_bf16 v[58:61], v[148:151], v[200:203], v[58:61]
	v_mfma_f32_16x16x32_bf16 v[62:65], v[148:151], v[204:207], v[62:65]
	s_waitcnt lgkmcnt(0)
	v_mfma_f32_16x16x32_bf16 v[2:5], v[172:175], v[212:215], v[2:5]
	v_mfma_f32_16x16x32_bf16 v[6:9], v[172:175], v[216:219], v[6:9]
	v_mfma_f32_16x16x32_bf16 v[10:13], v[172:175], v[220:223], v[10:13]
	v_mfma_f32_16x16x32_bf16 v[14:17], v[172:175], v[224:227], v[14:17]
	v_mfma_f32_16x16x32_bf16 v[18:21], v[176:179], v[212:215], v[18:21]
	v_mfma_f32_16x16x32_bf16 v[22:25], v[176:179], v[216:219], v[22:25]
	v_mfma_f32_16x16x32_bf16 v[26:29], v[176:179], v[220:223], v[26:29]
	v_mfma_f32_16x16x32_bf16 v[30:33], v[176:179], v[224:227], v[30:33]
	v_mfma_f32_16x16x32_bf16 v[34:37], v[180:183], v[212:215], v[34:37]
	v_mfma_f32_16x16x32_bf16 v[38:41], v[180:183], v[216:219], v[38:41]
	v_mfma_f32_16x16x32_bf16 v[42:45], v[180:183], v[220:223], v[42:45]
	v_mfma_f32_16x16x32_bf16 v[46:49], v[180:183], v[224:227], v[46:49]
	v_mfma_f32_16x16x32_bf16 v[50:53], v[184:187], v[212:215], v[50:53]
	v_mfma_f32_16x16x32_bf16 v[54:57], v[184:187], v[216:219], v[54:57]
	v_mfma_f32_16x16x32_bf16 v[58:61], v[184:187], v[220:223], v[58:61]
	v_mfma_f32_16x16x32_bf16 v[62:65], v[184:187], v[224:227], v[62:65]
	s_waitcnt vmcnt(6)
	s_barrier
	v_add_u32_e32 v236, s40, v232
	v_add_u32_e32 v237, s40, v233
	ds_read_b128 v[188:191], v236
	ds_read_b128 v[196:199], v236 offset:2048
	ds_read_b128 v[200:203], v236 offset:4096
	ds_read_b128 v[204:207], v236 offset:6144
	ds_read_b128 v[212:215], v237
	ds_read_b128 v[216:219], v237 offset:2048
	ds_read_b128 v[220:223], v237 offset:4096
	ds_read_b128 v[224:227], v237 offset:6144
	s_mov_b32 m0, s51
	s_nop 0
	global_load_lds_dwordx4 v229, s[46:47]
	s_add_i32 m0, s51, 0x400
	s_nop 0
	global_load_lds_dwordx4 v231, s[46:47]
	s_add_i32 m0, s51, 0x2000
	s_nop 0
	global_load_lds_dwordx4 v228, s[48:49]
	s_add_i32 m0, s51, 0x2400
	s_nop 0
	global_load_lds_dwordx4 v230, s[48:49]
	s_add_i32 m0, s51, 0x4000
	s_nop 0
	global_load_lds_dwordx4 v229, s[48:49]
	s_add_i32 m0, s51, 0x4400
	s_nop 0
	global_load_lds_dwordx4 v231, s[48:49]
	s_waitcnt lgkmcnt(4)
	v_mfma_f32_16x16x32_bf16 v[66:69], v[136:139], v[188:191], v[66:69]
	v_mfma_f32_16x16x32_bf16 v[70:73], v[136:139], v[196:199], v[70:73]
	v_mfma_f32_16x16x32_bf16 v[74:77], v[136:139], v[200:203], v[74:77]
	v_mfma_f32_16x16x32_bf16 v[78:81], v[136:139], v[204:207], v[78:81]
	v_mfma_f32_16x16x32_bf16 v[82:85], v[140:143], v[188:191], v[82:85]
	v_mfma_f32_16x16x32_bf16 v[86:89], v[140:143], v[196:199], v[86:89]
	v_mfma_f32_16x16x32_bf16 v[90:93], v[140:143], v[200:203], v[90:93]
	v_mfma_f32_16x16x32_bf16 v[94:97], v[140:143], v[204:207], v[94:97]
	v_mfma_f32_16x16x32_bf16 v[98:101], v[144:147], v[188:191], v[98:101]
	v_mfma_f32_16x16x32_bf16 v[102:105], v[144:147], v[196:199], v[102:105]
	v_mfma_f32_16x16x32_bf16 v[106:109], v[144:147], v[200:203], v[106:109]
	v_mfma_f32_16x16x32_bf16 v[110:113], v[144:147], v[204:207], v[110:113]
	v_mfma_f32_16x16x32_bf16 v[114:117], v[148:151], v[188:191], v[114:117]
	v_mfma_f32_16x16x32_bf16 v[118:121], v[148:151], v[196:199], v[118:121]
	v_mfma_f32_16x16x32_bf16 v[122:125], v[148:151], v[200:203], v[122:125]
	v_mfma_f32_16x16x32_bf16 v[126:129], v[148:151], v[204:207], v[126:129]
	s_waitcnt lgkmcnt(0)
	v_mfma_f32_16x16x32_bf16 v[66:69], v[172:175], v[212:215], v[66:69]
	v_mfma_f32_16x16x32_bf16 v[70:73], v[172:175], v[216:219], v[70:73]
	v_mfma_f32_16x16x32_bf16 v[74:77], v[172:175], v[220:223], v[74:77]
	v_mfma_f32_16x16x32_bf16 v[78:81], v[172:175], v[224:227], v[78:81]
	v_mfma_f32_16x16x32_bf16 v[82:85], v[176:179], v[212:215], v[82:85]
	v_mfma_f32_16x16x32_bf16 v[86:89], v[176:179], v[216:219], v[86:89]
	v_mfma_f32_16x16x32_bf16 v[90:93], v[176:179], v[220:223], v[90:93]
	v_mfma_f32_16x16x32_bf16 v[94:97], v[176:179], v[224:227], v[94:97]
	v_mfma_f32_16x16x32_bf16 v[98:101], v[180:183], v[212:215], v[98:101]
	v_mfma_f32_16x16x32_bf16 v[102:105], v[180:183], v[216:219], v[102:105]
	v_mfma_f32_16x16x32_bf16 v[106:109], v[180:183], v[220:223], v[106:109]
	v_mfma_f32_16x16x32_bf16 v[110:113], v[180:183], v[224:227], v[110:113]
	v_mfma_f32_16x16x32_bf16 v[114:117], v[184:187], v[212:215], v[114:117]
	v_mfma_f32_16x16x32_bf16 v[118:121], v[184:187], v[216:219], v[118:121]
	v_mfma_f32_16x16x32_bf16 v[122:125], v[184:187], v[220:223], v[122:125]
	v_mfma_f32_16x16x32_bf16 v[126:129], v[184:187], v[224:227], v[126:129]
	v_add_u32_e32 v228, 0x80, v228
	v_add_u32_e32 v229, 0x80, v229
	v_add_u32_e32 v230, 0x80, v230
	v_add_u32_e32 v231, 0x80, v231
	s_waitcnt vmcnt(4)
	s_barrier
	v_add_u32_e32 v234, s23, v232
	v_add_u32_e32 v236, s29, v232
	v_add_u32_e32 v235, s23, v233
	v_add_u32_e32 v237, s29, v233
	ds_read_b128 v[136:139], v234
	ds_read_b128 v[140:143], v234 offset:2048
	ds_read_b128 v[144:147], v234 offset:4096
	ds_read_b128 v[148:151], v234 offset:6144
	ds_read_b128 v[188:191], v236
	ds_read_b128 v[196:199], v236 offset:2048
	ds_read_b128 v[200:203], v236 offset:4096
	ds_read_b128 v[204:207], v236 offset:6144
	ds_read_b128 v[172:175], v235
	ds_read_b128 v[176:179], v235 offset:2048
	ds_read_b128 v[180:183], v235 offset:4096
	ds_read_b128 v[184:187], v235 offset:6144
	ds_read_b128 v[212:215], v237
	ds_read_b128 v[216:219], v237 offset:2048
	ds_read_b128 v[220:223], v237 offset:4096
	ds_read_b128 v[224:227], v237 offset:6144
	s_add_i32 m0, s51, 0x6000
	s_nop 0
	global_load_lds_dwordx4 v228, s[44:45]
	s_add_i32 m0, s51, 0x6400
	s_nop 0
	global_load_lds_dwordx4 v230, s[44:45]
	s_add_i32 m0, s51, 0x8000
	s_nop 0
	global_load_lds_dwordx4 v229, s[44:45]
	s_add_i32 m0, s51, 0x8400
	s_nop 0
	global_load_lds_dwordx4 v231, s[44:45]
	s_add_i32 m0, s51, 0xa000
	s_nop 0
	global_load_lds_dwordx4 v228, s[46:47]
	s_add_i32 m0, s51, 0xa400
	s_nop 0
	global_load_lds_dwordx4 v230, s[46:47]
	s_waitcnt lgkmcnt(8)
	v_mfma_f32_16x16x32_bf16 v[2:5], v[136:139], v[188:191], v[2:5]
	v_mfma_f32_16x16x32_bf16 v[6:9], v[136:139], v[196:199], v[6:9]
	v_mfma_f32_16x16x32_bf16 v[10:13], v[136:139], v[200:203], v[10:13]
	v_mfma_f32_16x16x32_bf16 v[14:17], v[136:139], v[204:207], v[14:17]
	v_mfma_f32_16x16x32_bf16 v[18:21], v[140:143], v[188:191], v[18:21]
	v_mfma_f32_16x16x32_bf16 v[22:25], v[140:143], v[196:199], v[22:25]
	v_mfma_f32_16x16x32_bf16 v[26:29], v[140:143], v[200:203], v[26:29]
	v_mfma_f32_16x16x32_bf16 v[30:33], v[140:143], v[204:207], v[30:33]
	v_mfma_f32_16x16x32_bf16 v[34:37], v[144:147], v[188:191], v[34:37]
	v_mfma_f32_16x16x32_bf16 v[38:41], v[144:147], v[196:199], v[38:41]
	v_mfma_f32_16x16x32_bf16 v[42:45], v[144:147], v[200:203], v[42:45]
	v_mfma_f32_16x16x32_bf16 v[46:49], v[144:147], v[204:207], v[46:49]
	v_mfma_f32_16x16x32_bf16 v[50:53], v[148:151], v[188:191], v[50:53]
	v_mfma_f32_16x16x32_bf16 v[54:57], v[148:151], v[196:199], v[54:57]
	v_mfma_f32_16x16x32_bf16 v[58:61], v[148:151], v[200:203], v[58:61]
	v_mfma_f32_16x16x32_bf16 v[62:65], v[148:151], v[204:207], v[62:65]
	s_waitcnt lgkmcnt(0)
	v_mfma_f32_16x16x32_bf16 v[2:5], v[172:175], v[212:215], v[2:5]
	v_mfma_f32_16x16x32_bf16 v[6:9], v[172:175], v[216:219], v[6:9]
	v_mfma_f32_16x16x32_bf16 v[10:13], v[172:175], v[220:223], v[10:13]
	v_mfma_f32_16x16x32_bf16 v[14:17], v[172:175], v[224:227], v[14:17]
	v_mfma_f32_16x16x32_bf16 v[18:21], v[176:179], v[212:215], v[18:21]
	v_mfma_f32_16x16x32_bf16 v[22:25], v[176:179], v[216:219], v[22:25]
	v_mfma_f32_16x16x32_bf16 v[26:29], v[176:179], v[220:223], v[26:29]
	v_mfma_f32_16x16x32_bf16 v[30:33], v[176:179], v[224:227], v[30:33]
	v_mfma_f32_16x16x32_bf16 v[34:37], v[180:183], v[212:215], v[34:37]
	v_mfma_f32_16x16x32_bf16 v[38:41], v[180:183], v[216:219], v[38:41]
	v_mfma_f32_16x16x32_bf16 v[42:45], v[180:183], v[220:223], v[42:45]
	v_mfma_f32_16x16x32_bf16 v[46:49], v[180:183], v[224:227], v[46:49]
	v_mfma_f32_16x16x32_bf16 v[50:53], v[184:187], v[212:215], v[50:53]
	v_mfma_f32_16x16x32_bf16 v[54:57], v[184:187], v[216:219], v[54:57]
	v_mfma_f32_16x16x32_bf16 v[58:61], v[184:187], v[220:223], v[58:61]
	v_mfma_f32_16x16x32_bf16 v[62:65], v[184:187], v[224:227], v[62:65]
	s_waitcnt vmcnt(6)
	s_barrier
	v_add_u32_e32 v236, s41, v232
	v_add_u32_e32 v237, s41, v233
	ds_read_b128 v[188:191], v236
	ds_read_b128 v[196:199], v236 offset:2048
	ds_read_b128 v[200:203], v236 offset:4096
	ds_read_b128 v[204:207], v236 offset:6144
	ds_read_b128 v[212:215], v237
	ds_read_b128 v[216:219], v237 offset:2048
	ds_read_b128 v[220:223], v237 offset:4096
	ds_read_b128 v[224:227], v237 offset:6144
	s_add_i32 m0, s51, 0xc000
	s_nop 0
	global_load_lds_dwordx4 v229, s[46:47]
	s_add_i32 m0, s51, 0xc400
	s_nop 0
	global_load_lds_dwordx4 v231, s[46:47]
	s_add_i32 m0, s51, 0xe000
	s_nop 0
	global_load_lds_dwordx4 v228, s[48:49]
	s_add_i32 m0, s51, 0xe400
	s_nop 0
	global_load_lds_dwordx4 v230, s[48:49]
	s_add_i32 m0, s51, 0x10000
	s_nop 0
	global_load_lds_dwordx4 v229, s[48:49]
	s_add_i32 m0, s51, 0x10400
	s_nop 0
	global_load_lds_dwordx4 v231, s[48:49]
	s_waitcnt lgkmcnt(4)
	v_mfma_f32_16x16x32_bf16 v[66:69], v[136:139], v[188:191], v[66:69]
	v_mfma_f32_16x16x32_bf16 v[70:73], v[136:139], v[196:199], v[70:73]
	v_mfma_f32_16x16x32_bf16 v[74:77], v[136:139], v[200:203], v[74:77]
	v_mfma_f32_16x16x32_bf16 v[78:81], v[136:139], v[204:207], v[78:81]
	v_mfma_f32_16x16x32_bf16 v[82:85], v[140:143], v[188:191], v[82:85]
	v_mfma_f32_16x16x32_bf16 v[86:89], v[140:143], v[196:199], v[86:89]
	v_mfma_f32_16x16x32_bf16 v[90:93], v[140:143], v[200:203], v[90:93]
	v_mfma_f32_16x16x32_bf16 v[94:97], v[140:143], v[204:207], v[94:97]
	v_mfma_f32_16x16x32_bf16 v[98:101], v[144:147], v[188:191], v[98:101]
	v_mfma_f32_16x16x32_bf16 v[102:105], v[144:147], v[196:199], v[102:105]
	v_mfma_f32_16x16x32_bf16 v[106:109], v[144:147], v[200:203], v[106:109]
	v_mfma_f32_16x16x32_bf16 v[110:113], v[144:147], v[204:207], v[110:113]
	v_mfma_f32_16x16x32_bf16 v[114:117], v[148:151], v[188:191], v[114:117]
	v_mfma_f32_16x16x32_bf16 v[118:121], v[148:151], v[196:199], v[118:121]
	v_mfma_f32_16x16x32_bf16 v[122:125], v[148:151], v[200:203], v[122:125]
	v_mfma_f32_16x16x32_bf16 v[126:129], v[148:151], v[204:207], v[126:129]
	s_waitcnt lgkmcnt(0)
	v_mfma_f32_16x16x32_bf16 v[66:69], v[172:175], v[212:215], v[66:69]
	v_mfma_f32_16x16x32_bf16 v[70:73], v[172:175], v[216:219], v[70:73]
	v_mfma_f32_16x16x32_bf16 v[74:77], v[172:175], v[220:223], v[74:77]
	v_mfma_f32_16x16x32_bf16 v[78:81], v[172:175], v[224:227], v[78:81]
	v_mfma_f32_16x16x32_bf16 v[82:85], v[176:179], v[212:215], v[82:85]
	v_mfma_f32_16x16x32_bf16 v[86:89], v[176:179], v[216:219], v[86:89]
	v_mfma_f32_16x16x32_bf16 v[90:93], v[176:179], v[220:223], v[90:93]
	v_mfma_f32_16x16x32_bf16 v[94:97], v[176:179], v[224:227], v[94:97]
	v_mfma_f32_16x16x32_bf16 v[98:101], v[180:183], v[212:215], v[98:101]
	v_mfma_f32_16x16x32_bf16 v[102:105], v[180:183], v[216:219], v[102:105]
	v_mfma_f32_16x16x32_bf16 v[106:109], v[180:183], v[220:223], v[106:109]
	v_mfma_f32_16x16x32_bf16 v[110:113], v[180:183], v[224:227], v[110:113]
	v_mfma_f32_16x16x32_bf16 v[114:117], v[184:187], v[212:215], v[114:117]
	v_mfma_f32_16x16x32_bf16 v[118:121], v[184:187], v[216:219], v[118:121]
	v_mfma_f32_16x16x32_bf16 v[122:125], v[184:187], v[220:223], v[122:125]
	v_mfma_f32_16x16x32_bf16 v[126:129], v[184:187], v[224:227], v[126:129]
	v_add_u32_e32 v228, 0x80, v228
	v_add_u32_e32 v229, 0x80, v229
	v_add_u32_e32 v230, 0x80, v230
	v_add_u32_e32 v231, 0x80, v231
	s_waitcnt vmcnt(4)
	s_barrier
	v_add_u32_e32 v234, s24, v232
	v_add_u32_e32 v236, s30, v232
	v_add_u32_e32 v235, s24, v233
	v_add_u32_e32 v237, s30, v233
	ds_read_b128 v[136:139], v234
	ds_read_b128 v[140:143], v234 offset:2048
	ds_read_b128 v[144:147], v234 offset:4096
	ds_read_b128 v[148:151], v234 offset:6144
	ds_read_b128 v[188:191], v236
	ds_read_b128 v[196:199], v236 offset:2048
	ds_read_b128 v[200:203], v236 offset:4096
	ds_read_b128 v[204:207], v236 offset:6144
	ds_read_b128 v[172:175], v235
	ds_read_b128 v[176:179], v235 offset:2048
	ds_read_b128 v[180:183], v235 offset:4096
	ds_read_b128 v[184:187], v235 offset:6144
	ds_read_b128 v[212:215], v237
	ds_read_b128 v[216:219], v237 offset:2048
	ds_read_b128 v[220:223], v237 offset:4096
	ds_read_b128 v[224:227], v237 offset:6144
	s_mov_b32 m0, s51
	s_nop 0
	global_load_lds_dwordx4 v228, s[44:45]
	s_add_i32 m0, s51, 0x400
	s_nop 0
	global_load_lds_dwordx4 v230, s[44:45]
	s_add_i32 m0, s51, 0x2000
	s_nop 0
	global_load_lds_dwordx4 v229, s[44:45]
	s_add_i32 m0, s51, 0x2400
	s_nop 0
	global_load_lds_dwordx4 v231, s[44:45]
	s_add_i32 m0, s51, 0x4000
	s_nop 0
	global_load_lds_dwordx4 v228, s[46:47]
	s_add_i32 m0, s51, 0x4400
	s_nop 0
	global_load_lds_dwordx4 v230, s[46:47]
	s_waitcnt lgkmcnt(8)
	v_mfma_f32_16x16x32_bf16 v[2:5], v[136:139], v[188:191], v[2:5]
	v_mfma_f32_16x16x32_bf16 v[6:9], v[136:139], v[196:199], v[6:9]
	v_mfma_f32_16x16x32_bf16 v[10:13], v[136:139], v[200:203], v[10:13]
	v_mfma_f32_16x16x32_bf16 v[14:17], v[136:139], v[204:207], v[14:17]
	v_mfma_f32_16x16x32_bf16 v[18:21], v[140:143], v[188:191], v[18:21]
	v_mfma_f32_16x16x32_bf16 v[22:25], v[140:143], v[196:199], v[22:25]
	v_mfma_f32_16x16x32_bf16 v[26:29], v[140:143], v[200:203], v[26:29]
	v_mfma_f32_16x16x32_bf16 v[30:33], v[140:143], v[204:207], v[30:33]
	v_mfma_f32_16x16x32_bf16 v[34:37], v[144:147], v[188:191], v[34:37]
	v_mfma_f32_16x16x32_bf16 v[38:41], v[144:147], v[196:199], v[38:41]
	v_mfma_f32_16x16x32_bf16 v[42:45], v[144:147], v[200:203], v[42:45]
	v_mfma_f32_16x16x32_bf16 v[46:49], v[144:147], v[204:207], v[46:49]
	v_mfma_f32_16x16x32_bf16 v[50:53], v[148:151], v[188:191], v[50:53]
	v_mfma_f32_16x16x32_bf16 v[54:57], v[148:151], v[196:199], v[54:57]
	v_mfma_f32_16x16x32_bf16 v[58:61], v[148:151], v[200:203], v[58:61]
	v_mfma_f32_16x16x32_bf16 v[62:65], v[148:151], v[204:207], v[62:65]
	s_waitcnt lgkmcnt(0)
	v_mfma_f32_16x16x32_bf16 v[2:5], v[172:175], v[212:215], v[2:5]
	v_mfma_f32_16x16x32_bf16 v[6:9], v[172:175], v[216:219], v[6:9]
	v_mfma_f32_16x16x32_bf16 v[10:13], v[172:175], v[220:223], v[10:13]
	v_mfma_f32_16x16x32_bf16 v[14:17], v[172:175], v[224:227], v[14:17]
	v_mfma_f32_16x16x32_bf16 v[18:21], v[176:179], v[212:215], v[18:21]
	v_mfma_f32_16x16x32_bf16 v[22:25], v[176:179], v[216:219], v[22:25]
	v_mfma_f32_16x16x32_bf16 v[26:29], v[176:179], v[220:223], v[26:29]
	v_mfma_f32_16x16x32_bf16 v[30:33], v[176:179], v[224:227], v[30:33]
	v_mfma_f32_16x16x32_bf16 v[34:37], v[180:183], v[212:215], v[34:37]
	v_mfma_f32_16x16x32_bf16 v[38:41], v[180:183], v[216:219], v[38:41]
	v_mfma_f32_16x16x32_bf16 v[42:45], v[180:183], v[220:223], v[42:45]
	v_mfma_f32_16x16x32_bf16 v[46:49], v[180:183], v[224:227], v[46:49]
	v_mfma_f32_16x16x32_bf16 v[50:53], v[184:187], v[212:215], v[50:53]
	v_mfma_f32_16x16x32_bf16 v[54:57], v[184:187], v[216:219], v[54:57]
	v_mfma_f32_16x16x32_bf16 v[58:61], v[184:187], v[220:223], v[58:61]
	v_mfma_f32_16x16x32_bf16 v[62:65], v[184:187], v[224:227], v[62:65]
	s_waitcnt vmcnt(6)
	s_barrier
	v_add_u32_e32 v236, s42, v232
	v_add_u32_e32 v237, s42, v233
	ds_read_b128 v[188:191], v236
	ds_read_b128 v[196:199], v236 offset:2048
	ds_read_b128 v[200:203], v236 offset:4096
	ds_read_b128 v[204:207], v236 offset:6144
	ds_read_b128 v[212:215], v237
	ds_read_b128 v[216:219], v237 offset:2048
	ds_read_b128 v[220:223], v237 offset:4096
	ds_read_b128 v[224:227], v237 offset:6144
	s_add_i32 m0, s51, 0x6000
	s_nop 0
	global_load_lds_dwordx4 v229, s[46:47]
	s_add_i32 m0, s51, 0x6400
	s_nop 0
	global_load_lds_dwordx4 v231, s[46:47]
	s_add_i32 m0, s51, 0x8000
	s_nop 0
	global_load_lds_dwordx4 v228, s[48:49]
	s_add_i32 m0, s51, 0x8400
	s_nop 0
	global_load_lds_dwordx4 v230, s[48:49]
	s_add_i32 m0, s51, 0xa000
	s_nop 0
	global_load_lds_dwordx4 v229, s[48:49]
	s_add_i32 m0, s51, 0xa400
	s_nop 0
	global_load_lds_dwordx4 v231, s[48:49]
	s_waitcnt lgkmcnt(4)
	v_mfma_f32_16x16x32_bf16 v[66:69], v[136:139], v[188:191], v[66:69]
	v_mfma_f32_16x16x32_bf16 v[70:73], v[136:139], v[196:199], v[70:73]
	v_mfma_f32_16x16x32_bf16 v[74:77], v[136:139], v[200:203], v[74:77]
	v_mfma_f32_16x16x32_bf16 v[78:81], v[136:139], v[204:207], v[78:81]
	v_mfma_f32_16x16x32_bf16 v[82:85], v[140:143], v[188:191], v[82:85]
	v_mfma_f32_16x16x32_bf16 v[86:89], v[140:143], v[196:199], v[86:89]
	v_mfma_f32_16x16x32_bf16 v[90:93], v[140:143], v[200:203], v[90:93]
	v_mfma_f32_16x16x32_bf16 v[94:97], v[140:143], v[204:207], v[94:97]
	v_mfma_f32_16x16x32_bf16 v[98:101], v[144:147], v[188:191], v[98:101]
	v_mfma_f32_16x16x32_bf16 v[102:105], v[144:147], v[196:199], v[102:105]
	v_mfma_f32_16x16x32_bf16 v[106:109], v[144:147], v[200:203], v[106:109]
	v_mfma_f32_16x16x32_bf16 v[110:113], v[144:147], v[204:207], v[110:113]
	v_mfma_f32_16x16x32_bf16 v[114:117], v[148:151], v[188:191], v[114:117]
	v_mfma_f32_16x16x32_bf16 v[118:121], v[148:151], v[196:199], v[118:121]
	v_mfma_f32_16x16x32_bf16 v[122:125], v[148:151], v[200:203], v[122:125]
	v_mfma_f32_16x16x32_bf16 v[126:129], v[148:151], v[204:207], v[126:129]
	s_waitcnt lgkmcnt(0)
	v_mfma_f32_16x16x32_bf16 v[66:69], v[172:175], v[212:215], v[66:69]
	v_mfma_f32_16x16x32_bf16 v[70:73], v[172:175], v[216:219], v[70:73]
	v_mfma_f32_16x16x32_bf16 v[74:77], v[172:175], v[220:223], v[74:77]
	v_mfma_f32_16x16x32_bf16 v[78:81], v[172:175], v[224:227], v[78:81]
	v_mfma_f32_16x16x32_bf16 v[82:85], v[176:179], v[212:215], v[82:85]
	v_mfma_f32_16x16x32_bf16 v[86:89], v[176:179], v[216:219], v[86:89]
	v_mfma_f32_16x16x32_bf16 v[90:93], v[176:179], v[220:223], v[90:93]
	v_mfma_f32_16x16x32_bf16 v[94:97], v[176:179], v[224:227], v[94:97]
	v_mfma_f32_16x16x32_bf16 v[98:101], v[180:183], v[212:215], v[98:101]
	v_mfma_f32_16x16x32_bf16 v[102:105], v[180:183], v[216:219], v[102:105]
	v_mfma_f32_16x16x32_bf16 v[106:109], v[180:183], v[220:223], v[106:109]
	v_mfma_f32_16x16x32_bf16 v[110:113], v[180:183], v[224:227], v[110:113]
	v_mfma_f32_16x16x32_bf16 v[114:117], v[184:187], v[212:215], v[114:117]
	v_mfma_f32_16x16x32_bf16 v[118:121], v[184:187], v[216:219], v[118:121]
	v_mfma_f32_16x16x32_bf16 v[122:125], v[184:187], v[220:223], v[122:125]
	v_mfma_f32_16x16x32_bf16 v[126:129], v[184:187], v[224:227], v[126:129]
	v_add_u32_e32 v228, 0x80, v228
	v_add_u32_e32 v229, 0x80, v229
	v_add_u32_e32 v230, 0x80, v230
	v_add_u32_e32 v231, 0x80, v231
	s_waitcnt vmcnt(4)
	s_barrier
	s_add_i32 s52, s52, 1
	s_cmp_lt_u32 s52, 29
	s_cbranch_scc1 .Lfin3_loop
	v_add_u32_e32 v234, s22, v232
	v_add_u32_e32 v236, s28, v232
	v_add_u32_e32 v235, s22, v233
	v_add_u32_e32 v237, s28, v233
	ds_read_b128 v[136:139], v234
	ds_read_b128 v[140:143], v234 offset:2048
	ds_read_b128 v[144:147], v234 offset:4096
	ds_read_b128 v[148:151], v234 offset:6144
	ds_read_b128 v[188:191], v236
	ds_read_b128 v[196:199], v236 offset:2048
	ds_read_b128 v[200:203], v236 offset:4096
	ds_read_b128 v[204:207], v236 offset:6144
	ds_read_b128 v[172:175], v235
	ds_read_b128 v[176:179], v235 offset:2048
	ds_read_b128 v[180:183], v235 offset:4096
	ds_read_b128 v[184:187], v235 offset:6144
	ds_read_b128 v[212:215], v237
	ds_read_b128 v[216:219], v237 offset:2048
	ds_read_b128 v[220:223], v237 offset:4096
	ds_read_b128 v[224:227], v237 offset:6144
	s_waitcnt lgkmcnt(8)
	v_mfma_f32_16x16x32_bf16 v[2:5], v[136:139], v[188:191], v[2:5]
	v_mfma_f32_16x16x32_bf16 v[6:9], v[136:139], v[196:199], v[6:9]
	v_mfma_f32_16x16x32_bf16 v[10:13], v[136:139], v[200:203], v[10:13]
	v_mfma_f32_16x16x32_bf16 v[14:17], v[136:139], v[204:207], v[14:17]
	v_mfma_f32_16x16x32_bf16 v[18:21], v[140:143], v[188:191], v[18:21]
	v_mfma_f32_16x16x32_bf16 v[22:25], v[140:143], v[196:199], v[22:25]
	v_mfma_f32_16x16x32_bf16 v[26:29], v[140:143], v[200:203], v[26:29]
	v_mfma_f32_16x16x32_bf16 v[30:33], v[140:143], v[204:207], v[30:33]
	v_mfma_f32_16x16x32_bf16 v[34:37], v[144:147], v[188:191], v[34:37]
	v_mfma_f32_16x16x32_bf16 v[38:41], v[144:147], v[196:199], v[38:41]
	v_mfma_f32_16x16x32_bf16 v[42:45], v[144:147], v[200:203], v[42:45]
	v_mfma_f32_16x16x32_bf16 v[46:49], v[144:147], v[204:207], v[46:49]
	v_mfma_f32_16x16x32_bf16 v[50:53], v[148:151], v[188:191], v[50:53]
	v_mfma_f32_16x16x32_bf16 v[54:57], v[148:151], v[196:199], v[54:57]
	v_mfma_f32_16x16x32_bf16 v[58:61], v[148:151], v[200:203], v[58:61]
	v_mfma_f32_16x16x32_bf16 v[62:65], v[148:151], v[204:207], v[62:65]
	s_waitcnt lgkmcnt(0)
	v_mfma_f32_16x16x32_bf16 v[2:5], v[172:175], v[212:215], v[2:5]
	v_mfma_f32_16x16x32_bf16 v[6:9], v[172:175], v[216:219], v[6:9]
	v_mfma_f32_16x16x32_bf16 v[10:13], v[172:175], v[220:223], v[10:13]
	v_mfma_f32_16x16x32_bf16 v[14:17], v[172:175], v[224:227], v[14:17]
	v_mfma_f32_16x16x32_bf16 v[18:21], v[176:179], v[212:215], v[18:21]
	v_mfma_f32_16x16x32_bf16 v[22:25], v[176:179], v[216:219], v[22:25]
	v_mfma_f32_16x16x32_bf16 v[26:29], v[176:179], v[220:223], v[26:29]
	v_mfma_f32_16x16x32_bf16 v[30:33], v[176:179], v[224:227], v[30:33]
	v_mfma_f32_16x16x32_bf16 v[34:37], v[180:183], v[212:215], v[34:37]
	v_mfma_f32_16x16x32_bf16 v[38:41], v[180:183], v[216:219], v[38:41]
	v_mfma_f32_16x16x32_bf16 v[42:45], v[180:183], v[220:223], v[42:45]
	v_mfma_f32_16x16x32_bf16 v[46:49], v[180:183], v[224:227], v[46:49]
	v_mfma_f32_16x16x32_bf16 v[50:53], v[184:187], v[212:215], v[50:53]
	v_mfma_f32_16x16x32_bf16 v[54:57], v[184:187], v[216:219], v[54:57]
	v_mfma_f32_16x16x32_bf16 v[58:61], v[184:187], v[220:223], v[58:61]
	v_mfma_f32_16x16x32_bf16 v[62:65], v[184:187], v[224:227], v[62:65]
	s_waitcnt vmcnt(0)
	s_barrier
	v_add_u32_e32 v236, s40, v232
	v_add_u32_e32 v237, s40, v233
	ds_read_b128 v[188:191], v236
	ds_read_b128 v[196:199], v236 offset:2048
	ds_read_b128 v[200:203], v236 offset:4096
	ds_read_b128 v[204:207], v236 offset:6144
	ds_read_b128 v[212:215], v237
	ds_read_b128 v[216:219], v237 offset:2048
	ds_read_b128 v[220:223], v237 offset:4096
	ds_read_b128 v[224:227], v237 offset:6144
	s_waitcnt lgkmcnt(4)
	v_mfma_f32_16x16x32_bf16 v[66:69], v[136:139], v[188:191], v[66:69]
	v_mfma_f32_16x16x32_bf16 v[70:73], v[136:139], v[196:199], v[70:73]
	v_mfma_f32_16x16x32_bf16 v[74:77], v[136:139], v[200:203], v[74:77]
	v_mfma_f32_16x16x32_bf16 v[78:81], v[136:139], v[204:207], v[78:81]
	v_mfma_f32_16x16x32_bf16 v[82:85], v[140:143], v[188:191], v[82:85]
	v_mfma_f32_16x16x32_bf16 v[86:89], v[140:143], v[196:199], v[86:89]
	v_mfma_f32_16x16x32_bf16 v[90:93], v[140:143], v[200:203], v[90:93]
	v_mfma_f32_16x16x32_bf16 v[94:97], v[140:143], v[204:207], v[94:97]
	v_mfma_f32_16x16x32_bf16 v[98:101], v[144:147], v[188:191], v[98:101]
	v_mfma_f32_16x16x32_bf16 v[102:105], v[144:147], v[196:199], v[102:105]
	v_mfma_f32_16x16x32_bf16 v[106:109], v[144:147], v[200:203], v[106:109]
	v_mfma_f32_16x16x32_bf16 v[110:113], v[144:147], v[204:207], v[110:113]
	v_mfma_f32_16x16x32_bf16 v[114:117], v[148:151], v[188:191], v[114:117]
	v_mfma_f32_16x16x32_bf16 v[118:121], v[148:151], v[196:199], v[118:121]
	v_mfma_f32_16x16x32_bf16 v[122:125], v[148:151], v[200:203], v[122:125]
	v_mfma_f32_16x16x32_bf16 v[126:129], v[148:151], v[204:207], v[126:129]
	s_waitcnt lgkmcnt(0)
	v_mfma_f32_16x16x32_bf16 v[66:69], v[172:175], v[212:215], v[66:69]
	v_mfma_f32_16x16x32_bf16 v[70:73], v[172:175], v[216:219], v[70:73]
	v_mfma_f32_16x16x32_bf16 v[74:77], v[172:175], v[220:223], v[74:77]
	v_mfma_f32_16x16x32_bf16 v[78:81], v[172:175], v[224:227], v[78:81]
	v_mfma_f32_16x16x32_bf16 v[82:85], v[176:179], v[212:215], v[82:85]
	v_mfma_f32_16x16x32_bf16 v[86:89], v[176:179], v[216:219], v[86:89]
	v_mfma_f32_16x16x32_bf16 v[90:93], v[176:179], v[220:223], v[90:93]
	v_mfma_f32_16x16x32_bf16 v[94:97], v[176:179], v[224:227], v[94:97]
	v_mfma_f32_16x16x32_bf16 v[98:101], v[180:183], v[212:215], v[98:101]
	v_mfma_f32_16x16x32_bf16 v[102:105], v[180:183], v[216:219], v[102:105]
	v_mfma_f32_16x16x32_bf16 v[106:109], v[180:183], v[220:223], v[106:109]
	v_mfma_f32_16x16x32_bf16 v[110:113], v[180:183], v[224:227], v[110:113]
	v_mfma_f32_16x16x32_bf16 v[114:117], v[184:187], v[212:215], v[114:117]
	v_mfma_f32_16x16x32_bf16 v[118:121], v[184:187], v[216:219], v[118:121]
	v_mfma_f32_16x16x32_bf16 v[122:125], v[184:187], v[220:223], v[122:125]
	v_mfma_f32_16x16x32_bf16 v[126:129], v[184:187], v[224:227], v[126:129]
	s_nop 7
	s_barrier
	s_load_dwordx2 s[58:59], s[12:13], 0x100
	v_lshrrev_b32_e32 v241, 5, v131
	v_and_b32_e32 v242, 31, v131
	v_lshlrev_b32_e32 v243, 4, v242
	s_movk_i32 s56, 0x210
	v_mad_u32_u24 v239, v241, s56, v243
	v_add_u32_e32 v239, 16, v239
	v_lshlrev_b32_e32 v240, 13, v241
	v_or_b32_e32 v240, v240, v243
	s_lshl_b32 s56, s53, 13
	s_lshl_b32 s57, s54, 2
	s_add_i32 s56, s56, s57
	s_waitcnt lgkmcnt(0)
	s_add_u32 s58, s58, s56
	s_addc_u32 s59, s59, 0
	ds_write_b32 v238, v2
	ds_write_b32 v238, v3 offset:528
	ds_write_b32 v238, v4 offset:1056
	ds_write_b32 v238, v5 offset:1584
	ds_write_b32 v238, v6 offset:64
	ds_write_b32 v238, v7 offset:592
	ds_write_b32 v238, v8 offset:1120
	ds_write_b32 v238, v9 offset:1648
	ds_write_b32 v238, v10 offset:128
	ds_write_b32 v238, v11 offset:656
	ds_write_b32 v238, v12 offset:1184
	ds_write_b32 v238, v13 offset:1712
	ds_write_b32 v238, v14 offset:192
	ds_write_b32 v238, v15 offset:720
	ds_write_b32 v238, v16 offset:1248
	ds_write_b32 v238, v17 offset:1776
	ds_write_b32 v238, v18 offset:8448
	ds_write_b32 v238, v19 offset:8976
	ds_write_b32 v238, v20 offset:9504
	ds_write_b32 v238, v21 offset:10032
	ds_write_b32 v238, v22 offset:8512
	ds_write_b32 v238, v23 offset:9040
	ds_write_b32 v238, v24 offset:9568
	ds_write_b32 v238, v25 offset:10096
	ds_write_b32 v238, v26 offset:8576
	ds_write_b32 v238, v27 offset:9104
	ds_write_b32 v238, v28 offset:9632
	ds_write_b32 v238, v29 offset:10160
	ds_write_b32 v238, v30 offset:8640
	ds_write_b32 v238, v31 offset:9168
	ds_write_b32 v238, v32 offset:9696
	ds_write_b32 v238, v33 offset:10224
	ds_write_b32 v238, v34 offset:16896
	ds_write_b32 v238, v35 offset:17424
	ds_write_b32 v238, v36 offset:17952
	ds_write_b32 v238, v37 offset:18480
	ds_write_b32 v238, v38 offset:16960
	ds_write_b32 v238, v39 offset:17488
	ds_write_b32 v238, v40 offset:18016
	ds_write_b32 v238, v41 offset:18544
	ds_write_b32 v238, v42 offset:17024
	ds_write_b32 v238, v43 offset:17552
	ds_write_b32 v238, v44 offset:18080
	ds_write_b32 v238, v45 offset:18608
	ds_write_b32 v238, v46 offset:17088
	ds_write_b32 v238, v47 offset:17616
	ds_write_b32 v238, v48 offset:18144
	ds_write_b32 v238, v49 offset:18672
	ds_write_b32 v238, v50 offset:25344
	ds_write_b32 v238, v51 offset:25872
	ds_write_b32 v238, v52 offset:26400
	ds_write_b32 v238, v53 offset:26928
	ds_write_b32 v238, v54 offset:25408
	ds_write_b32 v238, v55 offset:25936
	ds_write_b32 v238, v56 offset:26464
	ds_write_b32 v238, v57 offset:26992
	ds_write_b32 v238, v58 offset:25472
	ds_write_b32 v238, v59 offset:26000
	ds_write_b32 v238, v60 offset:26528
	ds_write_b32 v238, v61 offset:27056
	ds_write_b32 v238, v62 offset:25536
	ds_write_b32 v238, v63 offset:26064
	ds_write_b32 v238, v64 offset:26592
	ds_write_b32 v238, v65 offset:27120
	s_mov_b32 s0, s58
	s_mov_b32 s1, s59
	global_load_dwordx4 v[136:139], v240, s[0:1]
	s_add_u32 s0, s0, 0x10000
	s_addc_u32 s1, s1, 0
	global_load_dwordx4 v[140:143], v240, s[0:1]
	s_add_u32 s0, s0, 0x10000
	s_addc_u32 s1, s1, 0
	global_load_dwordx4 v[144:147], v240, s[0:1]
	s_add_u32 s0, s0, 0x10000
	s_addc_u32 s1, s1, 0
	global_load_dwordx4 v[148:151], v240, s[0:1]
	s_add_u32 s0, s0, 0x10000
	s_addc_u32 s1, s1, 0
	global_load_dwordx4 v[172:175], v240, s[0:1]
	s_add_u32 s0, s0, 0x10000
	s_addc_u32 s1, s1, 0
	global_load_dwordx4 v[176:179], v240, s[0:1]
	s_add_u32 s0, s0, 0x10000
	s_addc_u32 s1, s1, 0
	global_load_dwordx4 v[180:183], v240, s[0:1]
	s_add_u32 s0, s0, 0x10000
	s_addc_u32 s1, s1, 0
	global_load_dwordx4 v[184:187], v240, s[0:1]
	s_add_u32 s0, s0, 0x10000
	s_addc_u32 s1, s1, 0
	global_load_dwordx4 v[188:191], v240, s[0:1]
	s_add_u32 s0, s0, 0x10000
	s_addc_u32 s1, s1, 0
	global_load_dwordx4 v[196:199], v240, s[0:1]
	s_add_u32 s0, s0, 0x10000
	s_addc_u32 s1, s1, 0
	global_load_dwordx4 v[200:203], v240, s[0:1]
	s_add_u32 s0, s0, 0x10000
	s_addc_u32 s1, s1, 0
	global_load_dwordx4 v[204:207], v240, s[0:1]
	s_add_u32 s0, s0, 0x10000
	s_addc_u32 s1, s1, 0
	global_load_dwordx4 v[212:215], v240, s[0:1]
	s_add_u32 s0, s0, 0x10000
	s_addc_u32 s1, s1, 0
	global_load_dwordx4 v[216:219], v240, s[0:1]
	s_add_u32 s0, s0, 0x10000
	s_addc_u32 s1, s1, 0
	global_load_dwordx4 v[220:223], v240, s[0:1]
	s_add_u32 s0, s0, 0x10000
	s_addc_u32 s1, s1, 0
	global_load_dwordx4 v[224:227], v240, s[0:1]
	s_waitcnt lgkmcnt(0)
	s_barrier
	ds_read_b128 v[2:5], v239
	ds_read_b128 v[6:9], v239 offset:4224
	ds_read_b128 v[10:13], v239 offset:8448
	ds_read_b128 v[14:17], v239 offset:12672
	ds_read_b128 v[18:21], v239 offset:16896
	ds_read_b128 v[22:25], v239 offset:21120
	ds_read_b128 v[26:29], v239 offset:25344
	ds_read_b128 v[30:33], v239 offset:29568
	ds_read_b128 v[34:37], v239 offset:33792
	ds_read_b128 v[38:41], v239 offset:38016
	ds_read_b128 v[42:45], v239 offset:42240
	ds_read_b128 v[46:49], v239 offset:46464
	ds_read_b128 v[50:53], v239 offset:50688
	ds_read_b128 v[54:57], v239 offset:54912
	ds_read_b128 v[58:61], v239 offset:59136
	ds_read_b128 v[62:65], v239 offset:63360
	s_mov_b32 s0, s58
	s_mov_b32 s1, s59
	s_waitcnt vmcnt(15) lgkmcnt(15)
	v_pk_add_f32 v[2:3], v[2:3], v[136:137]
	v_pk_add_f32 v[4:5], v[4:5], v[138:139]
	s_waitcnt vmcnt(14) lgkmcnt(14)
	v_pk_add_f32 v[6:7], v[6:7], v[140:141]
	v_pk_add_f32 v[8:9], v[8:9], v[142:143]
	s_waitcnt vmcnt(13) lgkmcnt(13)
	v_pk_add_f32 v[10:11], v[10:11], v[144:145]
	v_pk_add_f32 v[12:13], v[12:13], v[146:147]
	s_waitcnt vmcnt(12) lgkmcnt(12)
	v_pk_add_f32 v[14:15], v[14:15], v[148:149]
	v_pk_add_f32 v[16:17], v[16:17], v[150:151]
	s_waitcnt vmcnt(11) lgkmcnt(11)
	v_pk_add_f32 v[18:19], v[18:19], v[172:173]
	v_pk_add_f32 v[20:21], v[20:21], v[174:175]
	s_waitcnt vmcnt(10) lgkmcnt(10)
	v_pk_add_f32 v[22:23], v[22:23], v[176:177]
	v_pk_add_f32 v[24:25], v[24:25], v[178:179]
	s_waitcnt vmcnt(9) lgkmcnt(9)
	v_pk_add_f32 v[26:27], v[26:27], v[180:181]
	v_pk_add_f32 v[28:29], v[28:29], v[182:183]
	s_waitcnt vmcnt(8) lgkmcnt(8)
	v_pk_add_f32 v[30:31], v[30:31], v[184:185]
	v_pk_add_f32 v[32:33], v[32:33], v[186:187]
	s_waitcnt vmcnt(7) lgkmcnt(7)
	v_pk_add_f32 v[34:35], v[34:35], v[188:189]
	v_pk_add_f32 v[36:37], v[36:37], v[190:191]
	s_waitcnt vmcnt(6) lgkmcnt(6)
	v_pk_add_f32 v[38:39], v[38:39], v[196:197]
	v_pk_add_f32 v[40:41], v[40:41], v[198:199]
	s_waitcnt vmcnt(5) lgkmcnt(5)
	v_pk_add_f32 v[42:43], v[42:43], v[200:201]
	v_pk_add_f32 v[44:45], v[44:45], v[202:203]
	s_waitcnt vmcnt(4) lgkmcnt(4)
	v_pk_add_f32 v[46:47], v[46:47], v[204:205]
	v_pk_add_f32 v[48:49], v[48:49], v[206:207]
	s_waitcnt vmcnt(3) lgkmcnt(3)
	v_pk_add_f32 v[50:51], v[50:51], v[212:213]
	v_pk_add_f32 v[52:53], v[52:53], v[214:215]
	s_waitcnt vmcnt(2) lgkmcnt(2)
	v_pk_add_f32 v[54:55], v[54:55], v[216:217]
	v_pk_add_f32 v[56:57], v[56:57], v[218:219]
	s_waitcnt vmcnt(1) lgkmcnt(1)
	v_pk_add_f32 v[58:59], v[58:59], v[220:221]
	v_pk_add_f32 v[60:61], v[60:61], v[222:223]
	s_waitcnt vmcnt(0) lgkmcnt(0)
	v_pk_add_f32 v[62:63], v[62:63], v[224:225]
	v_pk_add_f32 v[64:65], v[64:65], v[226:227]
	global_store_dwordx4 v240, v[2:5], s[0:1]
	s_add_u32 s0, s0, 0x10000
	s_addc_u32 s1, s1, 0
	global_store_dwordx4 v240, v[6:9], s[0:1]
	s_add_u32 s0, s0, 0x10000
	s_addc_u32 s1, s1, 0
	global_store_dwordx4 v240, v[10:13], s[0:1]
	s_add_u32 s0, s0, 0x10000
	s_addc_u32 s1, s1, 0
	global_store_dwordx4 v240, v[14:17], s[0:1]
	s_add_u32 s0, s0, 0x10000
	s_addc_u32 s1, s1, 0
	global_store_dwordx4 v240, v[18:21], s[0:1]
	s_add_u32 s0, s0, 0x10000
	s_addc_u32 s1, s1, 0
	global_store_dwordx4 v240, v[22:25], s[0:1]
	s_add_u32 s0, s0, 0x10000
	s_addc_u32 s1, s1, 0
	global_store_dwordx4 v240, v[26:29], s[0:1]
	s_add_u32 s0, s0, 0x10000
	s_addc_u32 s1, s1, 0
	global_store_dwordx4 v240, v[30:33], s[0:1]
	s_add_u32 s0, s0, 0x10000
	s_addc_u32 s1, s1, 0
	global_store_dwordx4 v240, v[34:37], s[0:1]
	s_add_u32 s0, s0, 0x10000
	s_addc_u32 s1, s1, 0
	global_store_dwordx4 v240, v[38:41], s[0:1]
	s_add_u32 s0, s0, 0x10000
	s_addc_u32 s1, s1, 0
	global_store_dwordx4 v240, v[42:45], s[0:1]
	s_add_u32 s0, s0, 0x10000
	s_addc_u32 s1, s1, 0
	global_store_dwordx4 v240, v[46:49], s[0:1]
	s_add_u32 s0, s0, 0x10000
	s_addc_u32 s1, s1, 0
	global_store_dwordx4 v240, v[50:53], s[0:1]
	s_add_u32 s0, s0, 0x10000
	s_addc_u32 s1, s1, 0
	global_store_dwordx4 v240, v[54:57], s[0:1]
	s_add_u32 s0, s0, 0x10000
	s_addc_u32 s1, s1, 0
	global_store_dwordx4 v240, v[58:61], s[0:1]
	s_add_u32 s0, s0, 0x10000
	s_addc_u32 s1, s1, 0
	global_store_dwordx4 v240, v[62:65], s[0:1]
	s_add_u32 s58, s58, 0x1000
	s_addc_u32 s59, s59, 0
	s_waitcnt lgkmcnt(0)
	s_barrier
	ds_write_b32 v238, v66
	ds_write_b32 v238, v67 offset:528
	ds_write_b32 v238, v68 offset:1056
	ds_write_b32 v238, v69 offset:1584
	ds_write_b32 v238, v70 offset:64
	ds_write_b32 v238, v71 offset:592
	ds_write_b32 v238, v72 offset:1120
	ds_write_b32 v238, v73 offset:1648
	ds_write_b32 v238, v74 offset:128
	ds_write_b32 v238, v75 offset:656
	ds_write_b32 v238, v76 offset:1184
	ds_write_b32 v238, v77 offset:1712
	ds_write_b32 v238, v78 offset:192
	ds_write_b32 v238, v79 offset:720
	ds_write_b32 v238, v80 offset:1248
	ds_write_b32 v238, v81 offset:1776
	ds_write_b32 v238, v82 offset:8448
	ds_write_b32 v238, v83 offset:8976
	ds_write_b32 v238, v84 offset:9504
	ds_write_b32 v238, v85 offset:10032
	ds_write_b32 v238, v86 offset:8512
	ds_write_b32 v238, v87 offset:9040
	ds_write_b32 v238, v88 offset:9568
	ds_write_b32 v238, v89 offset:10096
	ds_write_b32 v238, v90 offset:8576
	ds_write_b32 v238, v91 offset:9104
	ds_write_b32 v238, v92 offset:9632
	ds_write_b32 v238, v93 offset:10160
	ds_write_b32 v238, v94 offset:8640
	ds_write_b32 v238, v95 offset:9168
	ds_write_b32 v238, v96 offset:9696
	ds_write_b32 v238, v97 offset:10224
	ds_write_b32 v238, v98 offset:16896
	ds_write_b32 v238, v99 offset:17424
	ds_write_b32 v238, v100 offset:17952
	ds_write_b32 v238, v101 offset:18480
	ds_write_b32 v238, v102 offset:16960
	ds_write_b32 v238, v103 offset:17488
	ds_write_b32 v238, v104 offset:18016
	ds_write_b32 v238, v105 offset:18544
	ds_write_b32 v238, v106 offset:17024
	ds_write_b32 v238, v107 offset:17552
	ds_write_b32 v238, v108 offset:18080
	ds_write_b32 v238, v109 offset:18608
	ds_write_b32 v238, v110 offset:17088
	ds_write_b32 v238, v111 offset:17616
	ds_write_b32 v238, v112 offset:18144
	ds_write_b32 v238, v113 offset:18672
	ds_write_b32 v238, v114 offset:25344
	ds_write_b32 v238, v115 offset:25872
	ds_write_b32 v238, v116 offset:26400
	ds_write_b32 v238, v117 offset:26928
	ds_write_b32 v238, v118 offset:25408
	ds_write_b32 v238, v119 offset:25936
	ds_write_b32 v238, v120 offset:26464
	ds_write_b32 v238, v121 offset:26992
	ds_write_b32 v238, v122 offset:25472
	ds_write_b32 v238, v123 offset:26000
	ds_write_b32 v238, v124 offset:26528
	ds_write_b32 v238, v125 offset:27056
	ds_write_b32 v238, v126 offset:25536
	ds_write_b32 v238, v127 offset:26064
	ds_write_b32 v238, v128 offset:26592
	ds_write_b32 v238, v129 offset:27120
	s_mov_b32 s0, s58
	s_mov_b32 s1, s59
	global_load_dwordx4 v[136:139], v240, s[0:1]
	s_add_u32 s0, s0, 0x10000
	s_addc_u32 s1, s1, 0
	global_load_dwordx4 v[140:143], v240, s[0:1]
	s_add_u32 s0, s0, 0x10000
	s_addc_u32 s1, s1, 0
	global_load_dwordx4 v[144:147], v240, s[0:1]
	s_add_u32 s0, s0, 0x10000
	s_addc_u32 s1, s1, 0
	global_load_dwordx4 v[148:151], v240, s[0:1]
	s_add_u32 s0, s0, 0x10000
	s_addc_u32 s1, s1, 0
	global_load_dwordx4 v[172:175], v240, s[0:1]
	s_add_u32 s0, s0, 0x10000
	s_addc_u32 s1, s1, 0
	global_load_dwordx4 v[176:179], v240, s[0:1]
	s_add_u32 s0, s0, 0x10000
	s_addc_u32 s1, s1, 0
	global_load_dwordx4 v[180:183], v240, s[0:1]
	s_add_u32 s0, s0, 0x10000
	s_addc_u32 s1, s1, 0
	global_load_dwordx4 v[184:187], v240, s[0:1]
	s_add_u32 s0, s0, 0x10000
	s_addc_u32 s1, s1, 0
	global_load_dwordx4 v[188:191], v240, s[0:1]
	s_add_u32 s0, s0, 0x10000
	s_addc_u32 s1, s1, 0
	global_load_dwordx4 v[196:199], v240, s[0:1]
	s_add_u32 s0, s0, 0x10000
	s_addc_u32 s1, s1, 0
	global_load_dwordx4 v[200:203], v240, s[0:1]
	s_add_u32 s0, s0, 0x10000
	s_addc_u32 s1, s1, 0
	global_load_dwordx4 v[204:207], v240, s[0:1]
	s_add_u32 s0, s0, 0x10000
	s_addc_u32 s1, s1, 0
	global_load_dwordx4 v[212:215], v240, s[0:1]
	s_add_u32 s0, s0, 0x10000
	s_addc_u32 s1, s1, 0
	global_load_dwordx4 v[216:219], v240, s[0:1]
	s_add_u32 s0, s0, 0x10000
	s_addc_u32 s1, s1, 0
	global_load_dwordx4 v[220:223], v240, s[0:1]
	s_add_u32 s0, s0, 0x10000
	s_addc_u32 s1, s1, 0
	global_load_dwordx4 v[224:227], v240, s[0:1]
	s_waitcnt lgkmcnt(0)
	s_barrier
	ds_read_b128 v[66:69], v239
	ds_read_b128 v[70:73], v239 offset:4224
	ds_read_b128 v[74:77], v239 offset:8448
	ds_read_b128 v[78:81], v239 offset:12672
	ds_read_b128 v[82:85], v239 offset:16896
	ds_read_b128 v[86:89], v239 offset:21120
	ds_read_b128 v[90:93], v239 offset:25344
	ds_read_b128 v[94:97], v239 offset:29568
	ds_read_b128 v[98:101], v239 offset:33792
	ds_read_b128 v[102:105], v239 offset:38016
	ds_read_b128 v[106:109], v239 offset:42240
	ds_read_b128 v[110:113], v239 offset:46464
	ds_read_b128 v[114:117], v239 offset:50688
	ds_read_b128 v[118:121], v239 offset:54912
	ds_read_b128 v[122:125], v239 offset:59136
	ds_read_b128 v[126:129], v239 offset:63360
	s_mov_b32 s0, s58
	s_mov_b32 s1, s59
	s_waitcnt vmcnt(15) lgkmcnt(15)
	v_pk_add_f32 v[66:67], v[66:67], v[136:137]
	v_pk_add_f32 v[68:69], v[68:69], v[138:139]
	s_waitcnt vmcnt(14) lgkmcnt(14)
	v_pk_add_f32 v[70:71], v[70:71], v[140:141]
	v_pk_add_f32 v[72:73], v[72:73], v[142:143]
	s_waitcnt vmcnt(13) lgkmcnt(13)
	v_pk_add_f32 v[74:75], v[74:75], v[144:145]
	v_pk_add_f32 v[76:77], v[76:77], v[146:147]
	s_waitcnt vmcnt(12) lgkmcnt(12)
	v_pk_add_f32 v[78:79], v[78:79], v[148:149]
	v_pk_add_f32 v[80:81], v[80:81], v[150:151]
	s_waitcnt vmcnt(11) lgkmcnt(11)
	v_pk_add_f32 v[82:83], v[82:83], v[172:173]
	v_pk_add_f32 v[84:85], v[84:85], v[174:175]
	s_waitcnt vmcnt(10) lgkmcnt(10)
	v_pk_add_f32 v[86:87], v[86:87], v[176:177]
	v_pk_add_f32 v[88:89], v[88:89], v[178:179]
	s_waitcnt vmcnt(9) lgkmcnt(9)
	v_pk_add_f32 v[90:91], v[90:91], v[180:181]
	v_pk_add_f32 v[92:93], v[92:93], v[182:183]
	s_waitcnt vmcnt(8) lgkmcnt(8)
	v_pk_add_f32 v[94:95], v[94:95], v[184:185]
	v_pk_add_f32 v[96:97], v[96:97], v[186:187]
	s_waitcnt vmcnt(7) lgkmcnt(7)
	v_pk_add_f32 v[98:99], v[98:99], v[188:189]
	v_pk_add_f32 v[100:101], v[100:101], v[190:191]
	s_waitcnt vmcnt(6) lgkmcnt(6)
	v_pk_add_f32 v[102:103], v[102:103], v[196:197]
	v_pk_add_f32 v[104:105], v[104:105], v[198:199]
	s_waitcnt vmcnt(5) lgkmcnt(5)
	v_pk_add_f32 v[106:107], v[106:107], v[200:201]
	v_pk_add_f32 v[108:109], v[108:109], v[202:203]
	s_waitcnt vmcnt(4) lgkmcnt(4)
	v_pk_add_f32 v[110:111], v[110:111], v[204:205]
	v_pk_add_f32 v[112:113], v[112:113], v[206:207]
	s_waitcnt vmcnt(3) lgkmcnt(3)
	v_pk_add_f32 v[114:115], v[114:115], v[212:213]
	v_pk_add_f32 v[116:117], v[116:117], v[214:215]
	s_waitcnt vmcnt(2) lgkmcnt(2)
	v_pk_add_f32 v[118:119], v[118:119], v[216:217]
	v_pk_add_f32 v[120:121], v[120:121], v[218:219]
	s_waitcnt vmcnt(1) lgkmcnt(1)
	v_pk_add_f32 v[122:123], v[122:123], v[220:221]
	v_pk_add_f32 v[124:125], v[124:125], v[222:223]
	s_waitcnt vmcnt(0) lgkmcnt(0)
	v_pk_add_f32 v[126:127], v[126:127], v[224:225]
	v_pk_add_f32 v[128:129], v[128:129], v[226:227]
	global_store_dwordx4 v240, v[66:69], s[0:1]
	s_add_u32 s0, s0, 0x10000
	s_addc_u32 s1, s1, 0
	global_store_dwordx4 v240, v[70:73], s[0:1]
	s_add_u32 s0, s0, 0x10000
	s_addc_u32 s1, s1, 0
	global_store_dwordx4 v240, v[74:77], s[0:1]
	s_add_u32 s0, s0, 0x10000
	s_addc_u32 s1, s1, 0
	global_store_dwordx4 v240, v[78:81], s[0:1]
	s_add_u32 s0, s0, 0x10000
	s_addc_u32 s1, s1, 0
	global_store_dwordx4 v240, v[82:85], s[0:1]
	s_add_u32 s0, s0, 0x10000
	s_addc_u32 s1, s1, 0
	global_store_dwordx4 v240, v[86:89], s[0:1]
	s_add_u32 s0, s0, 0x10000
	s_addc_u32 s1, s1, 0
	global_store_dwordx4 v240, v[90:93], s[0:1]
	s_add_u32 s0, s0, 0x10000
	s_addc_u32 s1, s1, 0
	global_store_dwordx4 v240, v[94:97], s[0:1]
	s_add_u32 s0, s0, 0x10000
	s_addc_u32 s1, s1, 0
	global_store_dwordx4 v240, v[98:101], s[0:1]
	s_add_u32 s0, s0, 0x10000
	s_addc_u32 s1, s1, 0
	global_store_dwordx4 v240, v[102:105], s[0:1]
	s_add_u32 s0, s0, 0x10000
	s_addc_u32 s1, s1, 0
	global_store_dwordx4 v240, v[106:109], s[0:1]
	s_add_u32 s0, s0, 0x10000
	s_addc_u32 s1, s1, 0
	global_store_dwordx4 v240, v[110:113], s[0:1]
	s_add_u32 s0, s0, 0x10000
	s_addc_u32 s1, s1, 0
	global_store_dwordx4 v240, v[114:117], s[0:1]
	s_add_u32 s0, s0, 0x10000
	s_addc_u32 s1, s1, 0
	global_store_dwordx4 v240, v[118:121], s[0:1]
	s_add_u32 s0, s0, 0x10000
	s_addc_u32 s1, s1, 0
	global_store_dwordx4 v240, v[122:125], s[0:1]
	s_add_u32 s0, s0, 0x10000
	s_addc_u32 s1, s1, 0
	global_store_dwordx4 v240, v[126:129], s[0:1]
	s_add_i32 s21, s21, s72
	s_cmpk_lt_i32 s21, 0x200
	s_waitcnt lgkmcnt(0)
	s_barrier
	s_cbranch_scc1 .Lfin3_tile

.Lgu2_loop:
	v_add_u32_e32 v234, s22, v232
	v_add_u32_e32 v236, s28, v232
	v_add_u32_e32 v235, s22, v233
	v_add_u32_e32 v237, s28, v233
	ds_read_b128 v[136:139], v234
	ds_read_b128 v[140:143], v234 offset:2048
	ds_read_b128 v[144:147], v234 offset:4096
	ds_read_b128 v[148:151], v234 offset:6144
	ds_read_b128 v[188:191], v236
	ds_read_b128 v[196:199], v236 offset:2048
	ds_read_b128 v[200:203], v236 offset:4096
	ds_read_b128 v[204:207], v236 offset:6144
	ds_read_b128 v[172:175], v235
	ds_read_b128 v[176:179], v235 offset:2048
	ds_read_b128 v[180:183], v235 offset:4096
	ds_read_b128 v[184:187], v235 offset:6144
	ds_read_b128 v[212:215], v237
	ds_read_b128 v[216:219], v237 offset:2048
	ds_read_b128 v[220:223], v237 offset:4096
	ds_read_b128 v[224:227], v237 offset:6144
	s_add_i32 m0, s51, 0xc000
	s_nop 0
	global_load_lds_dwordx4 v228, s[44:45]
	s_add_i32 m0, s51, 0xc400
	s_nop 0
	global_load_lds_dwordx4 v230, s[44:45]
	s_add_i32 m0, s51, 0xe000
	s_nop 0
	global_load_lds_dwordx4 v229, s[44:45]
	s_add_i32 m0, s51, 0xe400
	s_nop 0
	global_load_lds_dwordx4 v231, s[44:45]
	s_add_i32 m0, s51, 0x10000
	s_nop 0
	global_load_lds_dwordx4 v228, s[46:47]
	s_add_i32 m0, s51, 0x10400
	s_nop 0
	global_load_lds_dwordx4 v230, s[46:47]
	s_waitcnt lgkmcnt(8)
	v_mfma_f32_16x16x32_bf16 v[2:5], v[136:139], v[188:191], v[2:5]
	v_mfma_f32_16x16x32_bf16 v[6:9], v[136:139], v[196:199], v[6:9]
	v_mfma_f32_16x16x32_bf16 v[10:13], v[136:139], v[200:203], v[10:13]
	v_mfma_f32_16x16x32_bf16 v[14:17], v[136:139], v[204:207], v[14:17]
	v_mfma_f32_16x16x32_bf16 v[18:21], v[140:143], v[188:191], v[18:21]
	v_mfma_f32_16x16x32_bf16 v[22:25], v[140:143], v[196:199], v[22:25]
	v_mfma_f32_16x16x32_bf16 v[26:29], v[140:143], v[200:203], v[26:29]
	v_mfma_f32_16x16x32_bf16 v[30:33], v[140:143], v[204:207], v[30:33]
	v_mfma_f32_16x16x32_bf16 v[34:37], v[144:147], v[188:191], v[34:37]
	v_mfma_f32_16x16x32_bf16 v[38:41], v[144:147], v[196:199], v[38:41]
	v_mfma_f32_16x16x32_bf16 v[42:45], v[144:147], v[200:203], v[42:45]
	v_mfma_f32_16x16x32_bf16 v[46:49], v[144:147], v[204:207], v[46:49]
	v_mfma_f32_16x16x32_bf16 v[50:53], v[148:151], v[188:191], v[50:53]
	v_mfma_f32_16x16x32_bf16 v[54:57], v[148:151], v[196:199], v[54:57]
	v_mfma_f32_16x16x32_bf16 v[58:61], v[148:151], v[200:203], v[58:61]
	v_mfma_f32_16x16x32_bf16 v[62:65], v[148:151], v[204:207], v[62:65]
	s_waitcnt lgkmcnt(0)
	v_mfma_f32_16x16x32_bf16 v[2:5], v[172:175], v[212:215], v[2:5]
	v_mfma_f32_16x16x32_bf16 v[6:9], v[172:175], v[216:219], v[6:9]
	v_mfma_f32_16x16x32_bf16 v[10:13], v[172:175], v[220:223], v[10:13]
	v_mfma_f32_16x16x32_bf16 v[14:17], v[172:175], v[224:227], v[14:17]
	v_mfma_f32_16x16x32_bf16 v[18:21], v[176:179], v[212:215], v[18:21]
	v_mfma_f32_16x16x32_bf16 v[22:25], v[176:179], v[216:219], v[22:25]
	v_mfma_f32_16x16x32_bf16 v[26:29], v[176:179], v[220:223], v[26:29]
	v_mfma_f32_16x16x32_bf16 v[30:33], v[176:179], v[224:227], v[30:33]
	v_mfma_f32_16x16x32_bf16 v[34:37], v[180:183], v[212:215], v[34:37]
	v_mfma_f32_16x16x32_bf16 v[38:41], v[180:183], v[216:219], v[38:41]
	v_mfma_f32_16x16x32_bf16 v[42:45], v[180:183], v[220:223], v[42:45]
	v_mfma_f32_16x16x32_bf16 v[46:49], v[180:183], v[224:227], v[46:49]
	v_mfma_f32_16x16x32_bf16 v[50:53], v[184:187], v[212:215], v[50:53]
	v_mfma_f32_16x16x32_bf16 v[54:57], v[184:187], v[216:219], v[54:57]
	v_mfma_f32_16x16x32_bf16 v[58:61], v[184:187], v[220:223], v[58:61]
	v_mfma_f32_16x16x32_bf16 v[62:65], v[184:187], v[224:227], v[62:65]
	s_waitcnt vmcnt(6)
	s_barrier
	v_add_u32_e32 v236, s40, v232
	v_add_u32_e32 v237, s40, v233
	ds_read_b128 v[188:191], v236
	ds_read_b128 v[196:199], v236 offset:2048
	ds_read_b128 v[200:203], v236 offset:4096
	ds_read_b128 v[204:207], v236 offset:6144
	ds_read_b128 v[212:215], v237
	ds_read_b128 v[216:219], v237 offset:2048
	ds_read_b128 v[220:223], v237 offset:4096
	ds_read_b128 v[224:227], v237 offset:6144
	s_mov_b32 m0, s51
	s_nop 0
	global_load_lds_dwordx4 v229, s[46:47]
	s_add_i32 m0, s51, 0x400
	s_nop 0
	global_load_lds_dwordx4 v231, s[46:47]
	s_add_i32 m0, s51, 0x2000
	s_nop 0
	global_load_lds_dwordx4 v228, s[48:49]
	s_add_i32 m0, s51, 0x2400
	s_nop 0
	global_load_lds_dwordx4 v230, s[48:49]
	s_add_i32 m0, s51, 0x4000
	s_nop 0
	global_load_lds_dwordx4 v229, s[48:49]
	s_add_i32 m0, s51, 0x4400
	s_nop 0
	global_load_lds_dwordx4 v231, s[48:49]
	s_waitcnt lgkmcnt(4)
	v_mfma_f32_16x16x32_bf16 v[66:69], v[136:139], v[188:191], v[66:69]
	v_mfma_f32_16x16x32_bf16 v[70:73], v[136:139], v[196:199], v[70:73]
	v_mfma_f32_16x16x32_bf16 v[74:77], v[136:139], v[200:203], v[74:77]
	v_mfma_f32_16x16x32_bf16 v[78:81], v[136:139], v[204:207], v[78:81]
	v_mfma_f32_16x16x32_bf16 v[82:85], v[140:143], v[188:191], v[82:85]
	v_mfma_f32_16x16x32_bf16 v[86:89], v[140:143], v[196:199], v[86:89]
	v_mfma_f32_16x16x32_bf16 v[90:93], v[140:143], v[200:203], v[90:93]
	v_mfma_f32_16x16x32_bf16 v[94:97], v[140:143], v[204:207], v[94:97]
	v_mfma_f32_16x16x32_bf16 v[98:101], v[144:147], v[188:191], v[98:101]
	v_mfma_f32_16x16x32_bf16 v[102:105], v[144:147], v[196:199], v[102:105]
	v_mfma_f32_16x16x32_bf16 v[106:109], v[144:147], v[200:203], v[106:109]
	v_mfma_f32_16x16x32_bf16 v[110:113], v[144:147], v[204:207], v[110:113]
	v_mfma_f32_16x16x32_bf16 v[114:117], v[148:151], v[188:191], v[114:117]
	v_mfma_f32_16x16x32_bf16 v[118:121], v[148:151], v[196:199], v[118:121]
	v_mfma_f32_16x16x32_bf16 v[122:125], v[148:151], v[200:203], v[122:125]
	v_mfma_f32_16x16x32_bf16 v[126:129], v[148:151], v[204:207], v[126:129]
	s_waitcnt lgkmcnt(0)
	v_mfma_f32_16x16x32_bf16 v[66:69], v[172:175], v[212:215], v[66:69]
	v_mfma_f32_16x16x32_bf16 v[70:73], v[172:175], v[216:219], v[70:73]
	v_mfma_f32_16x16x32_bf16 v[74:77], v[172:175], v[220:223], v[74:77]
	v_mfma_f32_16x16x32_bf16 v[78:81], v[172:175], v[224:227], v[78:81]
	v_mfma_f32_16x16x32_bf16 v[82:85], v[176:179], v[212:215], v[82:85]
	v_mfma_f32_16x16x32_bf16 v[86:89], v[176:179], v[216:219], v[86:89]
	v_mfma_f32_16x16x32_bf16 v[90:93], v[176:179], v[220:223], v[90:93]
	v_mfma_f32_16x16x32_bf16 v[94:97], v[176:179], v[224:227], v[94:97]
	v_mfma_f32_16x16x32_bf16 v[98:101], v[180:183], v[212:215], v[98:101]
	v_mfma_f32_16x16x32_bf16 v[102:105], v[180:183], v[216:219], v[102:105]
	v_mfma_f32_16x16x32_bf16 v[106:109], v[180:183], v[220:223], v[106:109]
	v_mfma_f32_16x16x32_bf16 v[110:113], v[180:183], v[224:227], v[110:113]
	v_mfma_f32_16x16x32_bf16 v[114:117], v[184:187], v[212:215], v[114:117]
	v_mfma_f32_16x16x32_bf16 v[118:121], v[184:187], v[216:219], v[118:121]
	v_mfma_f32_16x16x32_bf16 v[122:125], v[184:187], v[220:223], v[122:125]
	v_mfma_f32_16x16x32_bf16 v[126:129], v[184:187], v[224:227], v[126:129]
	v_add_u32_e32 v228, 0x80, v228
	v_add_u32_e32 v229, 0x80, v229
	v_add_u32_e32 v230, 0x80, v230
	v_add_u32_e32 v231, 0x80, v231
	s_waitcnt vmcnt(4)
	s_barrier
	v_add_u32_e32 v234, s23, v232
	v_add_u32_e32 v236, s29, v232
	v_add_u32_e32 v235, s23, v233
	v_add_u32_e32 v237, s29, v233
	ds_read_b128 v[136:139], v234
	ds_read_b128 v[140:143], v234 offset:2048
	ds_read_b128 v[144:147], v234 offset:4096
	ds_read_b128 v[148:151], v234 offset:6144
	ds_read_b128 v[188:191], v236
	ds_read_b128 v[196:199], v236 offset:2048
	ds_read_b128 v[200:203], v236 offset:4096
	ds_read_b128 v[204:207], v236 offset:6144
	ds_read_b128 v[172:175], v235
	ds_read_b128 v[176:179], v235 offset:2048
	ds_read_b128 v[180:183], v235 offset:4096
	ds_read_b128 v[184:187], v235 offset:6144
	ds_read_b128 v[212:215], v237
	ds_read_b128 v[216:219], v237 offset:2048
	ds_read_b128 v[220:223], v237 offset:4096
	ds_read_b128 v[224:227], v237 offset:6144
	s_add_i32 m0, s51, 0x6000
	s_nop 0
	global_load_lds_dwordx4 v228, s[44:45]
	s_add_i32 m0, s51, 0x6400
	s_nop 0
	global_load_lds_dwordx4 v230, s[44:45]
	s_add_i32 m0, s51, 0x8000
	s_nop 0
	global_load_lds_dwordx4 v229, s[44:45]
	s_add_i32 m0, s51, 0x8400
	s_nop 0
	global_load_lds_dwordx4 v231, s[44:45]
	s_add_i32 m0, s51, 0xa000
	s_nop 0
	global_load_lds_dwordx4 v228, s[46:47]
	s_add_i32 m0, s51, 0xa400
	s_nop 0
	global_load_lds_dwordx4 v230, s[46:47]
	s_waitcnt lgkmcnt(8)
	v_mfma_f32_16x16x32_bf16 v[2:5], v[136:139], v[188:191], v[2:5]
	v_mfma_f32_16x16x32_bf16 v[6:9], v[136:139], v[196:199], v[6:9]
	v_mfma_f32_16x16x32_bf16 v[10:13], v[136:139], v[200:203], v[10:13]
	v_mfma_f32_16x16x32_bf16 v[14:17], v[136:139], v[204:207], v[14:17]
	v_mfma_f32_16x16x32_bf16 v[18:21], v[140:143], v[188:191], v[18:21]
	v_mfma_f32_16x16x32_bf16 v[22:25], v[140:143], v[196:199], v[22:25]
	v_mfma_f32_16x16x32_bf16 v[26:29], v[140:143], v[200:203], v[26:29]
	v_mfma_f32_16x16x32_bf16 v[30:33], v[140:143], v[204:207], v[30:33]
	v_mfma_f32_16x16x32_bf16 v[34:37], v[144:147], v[188:191], v[34:37]
	v_mfma_f32_16x16x32_bf16 v[38:41], v[144:147], v[196:199], v[38:41]
	v_mfma_f32_16x16x32_bf16 v[42:45], v[144:147], v[200:203], v[42:45]
	v_mfma_f32_16x16x32_bf16 v[46:49], v[144:147], v[204:207], v[46:49]
	v_mfma_f32_16x16x32_bf16 v[50:53], v[148:151], v[188:191], v[50:53]
	v_mfma_f32_16x16x32_bf16 v[54:57], v[148:151], v[196:199], v[54:57]
	v_mfma_f32_16x16x32_bf16 v[58:61], v[148:151], v[200:203], v[58:61]
	v_mfma_f32_16x16x32_bf16 v[62:65], v[148:151], v[204:207], v[62:65]
	s_waitcnt lgkmcnt(0)
	v_mfma_f32_16x16x32_bf16 v[2:5], v[172:175], v[212:215], v[2:5]
	v_mfma_f32_16x16x32_bf16 v[6:9], v[172:175], v[216:219], v[6:9]
	v_mfma_f32_16x16x32_bf16 v[10:13], v[172:175], v[220:223], v[10:13]
	v_mfma_f32_16x16x32_bf16 v[14:17], v[172:175], v[224:227], v[14:17]
	v_mfma_f32_16x16x32_bf16 v[18:21], v[176:179], v[212:215], v[18:21]
	v_mfma_f32_16x16x32_bf16 v[22:25], v[176:179], v[216:219], v[22:25]
	v_mfma_f32_16x16x32_bf16 v[26:29], v[176:179], v[220:223], v[26:29]
	v_mfma_f32_16x16x32_bf16 v[30:33], v[176:179], v[224:227], v[30:33]
	v_mfma_f32_16x16x32_bf16 v[34:37], v[180:183], v[212:215], v[34:37]
	v_mfma_f32_16x16x32_bf16 v[38:41], v[180:183], v[216:219], v[38:41]
	v_mfma_f32_16x16x32_bf16 v[42:45], v[180:183], v[220:223], v[42:45]
	v_mfma_f32_16x16x32_bf16 v[46:49], v[180:183], v[224:227], v[46:49]
	v_mfma_f32_16x16x32_bf16 v[50:53], v[184:187], v[212:215], v[50:53]
	v_mfma_f32_16x16x32_bf16 v[54:57], v[184:187], v[216:219], v[54:57]
	v_mfma_f32_16x16x32_bf16 v[58:61], v[184:187], v[220:223], v[58:61]
	v_mfma_f32_16x16x32_bf16 v[62:65], v[184:187], v[224:227], v[62:65]
	s_waitcnt vmcnt(6)
	s_barrier
	v_add_u32_e32 v236, s41, v232
	v_add_u32_e32 v237, s41, v233
	ds_read_b128 v[188:191], v236
	ds_read_b128 v[196:199], v236 offset:2048
	ds_read_b128 v[200:203], v236 offset:4096
	ds_read_b128 v[204:207], v236 offset:6144
	ds_read_b128 v[212:215], v237
	ds_read_b128 v[216:219], v237 offset:2048
	ds_read_b128 v[220:223], v237 offset:4096
	ds_read_b128 v[224:227], v237 offset:6144
	s_add_i32 m0, s51, 0xc000
	s_nop 0
	global_load_lds_dwordx4 v229, s[46:47]
	s_add_i32 m0, s51, 0xc400
	s_nop 0
	global_load_lds_dwordx4 v231, s[46:47]
	s_add_i32 m0, s51, 0xe000
	s_nop 0
	global_load_lds_dwordx4 v228, s[48:49]
	s_add_i32 m0, s51, 0xe400
	s_nop 0
	global_load_lds_dwordx4 v230, s[48:49]
	s_add_i32 m0, s51, 0x10000
	s_nop 0
	global_load_lds_dwordx4 v229, s[48:49]
	s_add_i32 m0, s51, 0x10400
	s_nop 0
	global_load_lds_dwordx4 v231, s[48:49]
	s_waitcnt lgkmcnt(4)
	v_mfma_f32_16x16x32_bf16 v[66:69], v[136:139], v[188:191], v[66:69]
	v_mfma_f32_16x16x32_bf16 v[70:73], v[136:139], v[196:199], v[70:73]
	v_mfma_f32_16x16x32_bf16 v[74:77], v[136:139], v[200:203], v[74:77]
	v_mfma_f32_16x16x32_bf16 v[78:81], v[136:139], v[204:207], v[78:81]
	v_mfma_f32_16x16x32_bf16 v[82:85], v[140:143], v[188:191], v[82:85]
	v_mfma_f32_16x16x32_bf16 v[86:89], v[140:143], v[196:199], v[86:89]
	v_mfma_f32_16x16x32_bf16 v[90:93], v[140:143], v[200:203], v[90:93]
	v_mfma_f32_16x16x32_bf16 v[94:97], v[140:143], v[204:207], v[94:97]
	v_mfma_f32_16x16x32_bf16 v[98:101], v[144:147], v[188:191], v[98:101]
	v_mfma_f32_16x16x32_bf16 v[102:105], v[144:147], v[196:199], v[102:105]
	v_mfma_f32_16x16x32_bf16 v[106:109], v[144:147], v[200:203], v[106:109]
	v_mfma_f32_16x16x32_bf16 v[110:113], v[144:147], v[204:207], v[110:113]
	v_mfma_f32_16x16x32_bf16 v[114:117], v[148:151], v[188:191], v[114:117]
	v_mfma_f32_16x16x32_bf16 v[118:121], v[148:151], v[196:199], v[118:121]
	v_mfma_f32_16x16x32_bf16 v[122:125], v[148:151], v[200:203], v[122:125]
	v_mfma_f32_16x16x32_bf16 v[126:129], v[148:151], v[204:207], v[126:129]
	s_waitcnt lgkmcnt(0)
	v_mfma_f32_16x16x32_bf16 v[66:69], v[172:175], v[212:215], v[66:69]
	v_mfma_f32_16x16x32_bf16 v[70:73], v[172:175], v[216:219], v[70:73]
	v_mfma_f32_16x16x32_bf16 v[74:77], v[172:175], v[220:223], v[74:77]
	v_mfma_f32_16x16x32_bf16 v[78:81], v[172:175], v[224:227], v[78:81]
	v_mfma_f32_16x16x32_bf16 v[82:85], v[176:179], v[212:215], v[82:85]
	v_mfma_f32_16x16x32_bf16 v[86:89], v[176:179], v[216:219], v[86:89]
	v_mfma_f32_16x16x32_bf16 v[90:93], v[176:179], v[220:223], v[90:93]
	v_mfma_f32_16x16x32_bf16 v[94:97], v[176:179], v[224:227], v[94:97]
	v_mfma_f32_16x16x32_bf16 v[98:101], v[180:183], v[212:215], v[98:101]
	v_mfma_f32_16x16x32_bf16 v[102:105], v[180:183], v[216:219], v[102:105]
	v_mfma_f32_16x16x32_bf16 v[106:109], v[180:183], v[220:223], v[106:109]
	v_mfma_f32_16x16x32_bf16 v[110:113], v[180:183], v[224:227], v[110:113]
	v_mfma_f32_16x16x32_bf16 v[114:117], v[184:187], v[212:215], v[114:117]
	v_mfma_f32_16x16x32_bf16 v[118:121], v[184:187], v[216:219], v[118:121]
	v_mfma_f32_16x16x32_bf16 v[122:125], v[184:187], v[220:223], v[122:125]
	v_mfma_f32_16x16x32_bf16 v[126:129], v[184:187], v[224:227], v[126:129]
	v_add_u32_e32 v228, 0x80, v228
	v_add_u32_e32 v229, 0x80, v229
	v_add_u32_e32 v230, 0x80, v230
	v_add_u32_e32 v231, 0x80, v231
	s_waitcnt vmcnt(4)
	s_barrier
	v_add_u32_e32 v234, s24, v232
	v_add_u32_e32 v236, s30, v232
	v_add_u32_e32 v235, s24, v233
	v_add_u32_e32 v237, s30, v233
	ds_read_b128 v[136:139], v234
	ds_read_b128 v[140:143], v234 offset:2048
	ds_read_b128 v[144:147], v234 offset:4096
	ds_read_b128 v[148:151], v234 offset:6144
	ds_read_b128 v[188:191], v236
	ds_read_b128 v[196:199], v236 offset:2048
	ds_read_b128 v[200:203], v236 offset:4096
	ds_read_b128 v[204:207], v236 offset:6144
	ds_read_b128 v[172:175], v235
	ds_read_b128 v[176:179], v235 offset:2048
	ds_read_b128 v[180:183], v235 offset:4096
	ds_read_b128 v[184:187], v235 offset:6144
	ds_read_b128 v[212:215], v237
	ds_read_b128 v[216:219], v237 offset:2048
	ds_read_b128 v[220:223], v237 offset:4096
	ds_read_b128 v[224:227], v237 offset:6144
	s_mov_b32 m0, s51
	s_nop 0
	global_load_lds_dwordx4 v228, s[44:45]
	s_add_i32 m0, s51, 0x400
	s_nop 0
	global_load_lds_dwordx4 v230, s[44:45]
	s_add_i32 m0, s51, 0x2000
	s_nop 0
	global_load_lds_dwordx4 v229, s[44:45]
	s_add_i32 m0, s51, 0x2400
	s_nop 0
	global_load_lds_dwordx4 v231, s[44:45]
	s_add_i32 m0, s51, 0x4000
	s_nop 0
	global_load_lds_dwordx4 v228, s[46:47]
	s_add_i32 m0, s51, 0x4400
	s_nop 0
	global_load_lds_dwordx4 v230, s[46:47]
	s_waitcnt lgkmcnt(8)
	v_mfma_f32_16x16x32_bf16 v[2:5], v[136:139], v[188:191], v[2:5]
	v_mfma_f32_16x16x32_bf16 v[6:9], v[136:139], v[196:199], v[6:9]
	v_mfma_f32_16x16x32_bf16 v[10:13], v[136:139], v[200:203], v[10:13]
	v_mfma_f32_16x16x32_bf16 v[14:17], v[136:139], v[204:207], v[14:17]
	v_mfma_f32_16x16x32_bf16 v[18:21], v[140:143], v[188:191], v[18:21]
	v_mfma_f32_16x16x32_bf16 v[22:25], v[140:143], v[196:199], v[22:25]
	v_mfma_f32_16x16x32_bf16 v[26:29], v[140:143], v[200:203], v[26:29]
	v_mfma_f32_16x16x32_bf16 v[30:33], v[140:143], v[204:207], v[30:33]
	v_mfma_f32_16x16x32_bf16 v[34:37], v[144:147], v[188:191], v[34:37]
	v_mfma_f32_16x16x32_bf16 v[38:41], v[144:147], v[196:199], v[38:41]
	v_mfma_f32_16x16x32_bf16 v[42:45], v[144:147], v[200:203], v[42:45]
	v_mfma_f32_16x16x32_bf16 v[46:49], v[144:147], v[204:207], v[46:49]
	v_mfma_f32_16x16x32_bf16 v[50:53], v[148:151], v[188:191], v[50:53]
	v_mfma_f32_16x16x32_bf16 v[54:57], v[148:151], v[196:199], v[54:57]
	v_mfma_f32_16x16x32_bf16 v[58:61], v[148:151], v[200:203], v[58:61]
	v_mfma_f32_16x16x32_bf16 v[62:65], v[148:151], v[204:207], v[62:65]
	s_waitcnt lgkmcnt(0)
	v_mfma_f32_16x16x32_bf16 v[2:5], v[172:175], v[212:215], v[2:5]
	v_mfma_f32_16x16x32_bf16 v[6:9], v[172:175], v[216:219], v[6:9]
	v_mfma_f32_16x16x32_bf16 v[10:13], v[172:175], v[220:223], v[10:13]
	v_mfma_f32_16x16x32_bf16 v[14:17], v[172:175], v[224:227], v[14:17]
	v_mfma_f32_16x16x32_bf16 v[18:21], v[176:179], v[212:215], v[18:21]
	v_mfma_f32_16x16x32_bf16 v[22:25], v[176:179], v[216:219], v[22:25]
	v_mfma_f32_16x16x32_bf16 v[26:29], v[176:179], v[220:223], v[26:29]
	v_mfma_f32_16x16x32_bf16 v[30:33], v[176:179], v[224:227], v[30:33]
	v_mfma_f32_16x16x32_bf16 v[34:37], v[180:183], v[212:215], v[34:37]
	v_mfma_f32_16x16x32_bf16 v[38:41], v[180:183], v[216:219], v[38:41]
	v_mfma_f32_16x16x32_bf16 v[42:45], v[180:183], v[220:223], v[42:45]
	v_mfma_f32_16x16x32_bf16 v[46:49], v[180:183], v[224:227], v[46:49]
	v_mfma_f32_16x16x32_bf16 v[50:53], v[184:187], v[212:215], v[50:53]
	v_mfma_f32_16x16x32_bf16 v[54:57], v[184:187], v[216:219], v[54:57]
	v_mfma_f32_16x16x32_bf16 v[58:61], v[184:187], v[220:223], v[58:61]
	v_mfma_f32_16x16x32_bf16 v[62:65], v[184:187], v[224:227], v[62:65]
	s_waitcnt vmcnt(6)
	s_barrier
	v_add_u32_e32 v236, s42, v232
	v_add_u32_e32 v237, s42, v233
	ds_read_b128 v[188:191], v236
	ds_read_b128 v[196:199], v236 offset:2048
	ds_read_b128 v[200:203], v236 offset:4096
	ds_read_b128 v[204:207], v236 offset:6144
	ds_read_b128 v[212:215], v237
	ds_read_b128 v[216:219], v237 offset:2048
	ds_read_b128 v[220:223], v237 offset:4096
	ds_read_b128 v[224:227], v237 offset:6144
	s_add_i32 m0, s51, 0x6000
	s_nop 0
	global_load_lds_dwordx4 v229, s[46:47]
	s_add_i32 m0, s51, 0x6400
	s_nop 0
	global_load_lds_dwordx4 v231, s[46:47]
	s_add_i32 m0, s51, 0x8000
	s_nop 0
	global_load_lds_dwordx4 v228, s[48:49]
	s_add_i32 m0, s51, 0x8400
	s_nop 0
	global_load_lds_dwordx4 v230, s[48:49]
	s_add_i32 m0, s51, 0xa000
	s_nop 0
	global_load_lds_dwordx4 v229, s[48:49]
	s_add_i32 m0, s51, 0xa400
	s_nop 0
	global_load_lds_dwordx4 v231, s[48:49]
	s_waitcnt lgkmcnt(4)
	v_mfma_f32_16x16x32_bf16 v[66:69], v[136:139], v[188:191], v[66:69]
	v_mfma_f32_16x16x32_bf16 v[70:73], v[136:139], v[196:199], v[70:73]
	v_mfma_f32_16x16x32_bf16 v[74:77], v[136:139], v[200:203], v[74:77]
	v_mfma_f32_16x16x32_bf16 v[78:81], v[136:139], v[204:207], v[78:81]
	v_mfma_f32_16x16x32_bf16 v[82:85], v[140:143], v[188:191], v[82:85]
	v_mfma_f32_16x16x32_bf16 v[86:89], v[140:143], v[196:199], v[86:89]
	v_mfma_f32_16x16x32_bf16 v[90:93], v[140:143], v[200:203], v[90:93]
	v_mfma_f32_16x16x32_bf16 v[94:97], v[140:143], v[204:207], v[94:97]
	v_mfma_f32_16x16x32_bf16 v[98:101], v[144:147], v[188:191], v[98:101]
	v_mfma_f32_16x16x32_bf16 v[102:105], v[144:147], v[196:199], v[102:105]
	v_mfma_f32_16x16x32_bf16 v[106:109], v[144:147], v[200:203], v[106:109]
	v_mfma_f32_16x16x32_bf16 v[110:113], v[144:147], v[204:207], v[110:113]
	v_mfma_f32_16x16x32_bf16 v[114:117], v[148:151], v[188:191], v[114:117]
	v_mfma_f32_16x16x32_bf16 v[118:121], v[148:151], v[196:199], v[118:121]
	v_mfma_f32_16x16x32_bf16 v[122:125], v[148:151], v[200:203], v[122:125]
	v_mfma_f32_16x16x32_bf16 v[126:129], v[148:151], v[204:207], v[126:129]
	s_waitcnt lgkmcnt(0)
	v_mfma_f32_16x16x32_bf16 v[66:69], v[172:175], v[212:215], v[66:69]
	v_mfma_f32_16x16x32_bf16 v[70:73], v[172:175], v[216:219], v[70:73]
	v_mfma_f32_16x16x32_bf16 v[74:77], v[172:175], v[220:223], v[74:77]
	v_mfma_f32_16x16x32_bf16 v[78:81], v[172:175], v[224:227], v[78:81]
	v_mfma_f32_16x16x32_bf16 v[82:85], v[176:179], v[212:215], v[82:85]
	v_mfma_f32_16x16x32_bf16 v[86:89], v[176:179], v[216:219], v[86:89]
	v_mfma_f32_16x16x32_bf16 v[90:93], v[176:179], v[220:223], v[90:93]
	v_mfma_f32_16x16x32_bf16 v[94:97], v[176:179], v[224:227], v[94:97]
	v_mfma_f32_16x16x32_bf16 v[98:101], v[180:183], v[212:215], v[98:101]
	v_mfma_f32_16x16x32_bf16 v[102:105], v[180:183], v[216:219], v[102:105]
	v_mfma_f32_16x16x32_bf16 v[106:109], v[180:183], v[220:223], v[106:109]
	v_mfma_f32_16x16x32_bf16 v[110:113], v[180:183], v[224:227], v[110:113]
	v_mfma_f32_16x16x32_bf16 v[114:117], v[184:187], v[212:215], v[114:117]
	v_mfma_f32_16x16x32_bf16 v[118:121], v[184:187], v[216:219], v[118:121]
	v_mfma_f32_16x16x32_bf16 v[122:125], v[184:187], v[220:223], v[122:125]
	v_mfma_f32_16x16x32_bf16 v[126:129], v[184:187], v[224:227], v[126:129]
	v_add_u32_e32 v228, 0x80, v228
	v_add_u32_e32 v229, 0x80, v229
	v_add_u32_e32 v230, 0x80, v230
	v_add_u32_e32 v231, 0x80, v231
	s_waitcnt vmcnt(4)
	s_barrier
	s_add_i32 s52, s52, 1
	s_cmp_lt_u32 s52, 10
	s_cbranch_scc1 .Lgu2_loop
	v_add_u32_e32 v234, s22, v232
	v_add_u32_e32 v236, s28, v232
	v_add_u32_e32 v235, s22, v233
	v_add_u32_e32 v237, s28, v233
	ds_read_b128 v[136:139], v234
	ds_read_b128 v[140:143], v234 offset:2048
	ds_read_b128 v[144:147], v234 offset:4096
	ds_read_b128 v[148:151], v234 offset:6144
	ds_read_b128 v[188:191], v236
	ds_read_b128 v[196:199], v236 offset:2048
	ds_read_b128 v[200:203], v236 offset:4096
	ds_read_b128 v[204:207], v236 offset:6144
	ds_read_b128 v[172:175], v235
	ds_read_b128 v[176:179], v235 offset:2048
	ds_read_b128 v[180:183], v235 offset:4096
	ds_read_b128 v[184:187], v235 offset:6144
	ds_read_b128 v[212:215], v237
	ds_read_b128 v[216:219], v237 offset:2048
	ds_read_b128 v[220:223], v237 offset:4096
	ds_read_b128 v[224:227], v237 offset:6144
	s_add_i32 m0, s51, 0xc000
	s_nop 0
	global_load_lds_dwordx4 v228, s[44:45]
	s_add_i32 m0, s51, 0xc400
	s_nop 0
	global_load_lds_dwordx4 v230, s[44:45]
	s_add_i32 m0, s51, 0xe000
	s_nop 0
	global_load_lds_dwordx4 v229, s[44:45]
	s_add_i32 m0, s51, 0xe400
	s_nop 0
	global_load_lds_dwordx4 v231, s[44:45]
	s_add_i32 m0, s51, 0x10000
	s_nop 0
	global_load_lds_dwordx4 v228, s[46:47]
	s_add_i32 m0, s51, 0x10400
	s_nop 0
	global_load_lds_dwordx4 v230, s[46:47]
	s_waitcnt lgkmcnt(8)
	v_mfma_f32_16x16x32_bf16 v[2:5], v[136:139], v[188:191], v[2:5]
	v_mfma_f32_16x16x32_bf16 v[6:9], v[136:139], v[196:199], v[6:9]
	v_mfma_f32_16x16x32_bf16 v[10:13], v[136:139], v[200:203], v[10:13]
	v_mfma_f32_16x16x32_bf16 v[14:17], v[136:139], v[204:207], v[14:17]
	v_mfma_f32_16x16x32_bf16 v[18:21], v[140:143], v[188:191], v[18:21]
	v_mfma_f32_16x16x32_bf16 v[22:25], v[140:143], v[196:199], v[22:25]
	v_mfma_f32_16x16x32_bf16 v[26:29], v[140:143], v[200:203], v[26:29]
	v_mfma_f32_16x16x32_bf16 v[30:33], v[140:143], v[204:207], v[30:33]
	v_mfma_f32_16x16x32_bf16 v[34:37], v[144:147], v[188:191], v[34:37]
	v_mfma_f32_16x16x32_bf16 v[38:41], v[144:147], v[196:199], v[38:41]
	v_mfma_f32_16x16x32_bf16 v[42:45], v[144:147], v[200:203], v[42:45]
	v_mfma_f32_16x16x32_bf16 v[46:49], v[144:147], v[204:207], v[46:49]
	v_mfma_f32_16x16x32_bf16 v[50:53], v[148:151], v[188:191], v[50:53]
	v_mfma_f32_16x16x32_bf16 v[54:57], v[148:151], v[196:199], v[54:57]
	v_mfma_f32_16x16x32_bf16 v[58:61], v[148:151], v[200:203], v[58:61]
	v_mfma_f32_16x16x32_bf16 v[62:65], v[148:151], v[204:207], v[62:65]
	s_waitcnt lgkmcnt(0)
	v_mfma_f32_16x16x32_bf16 v[2:5], v[172:175], v[212:215], v[2:5]
	v_mfma_f32_16x16x32_bf16 v[6:9], v[172:175], v[216:219], v[6:9]
	v_mfma_f32_16x16x32_bf16 v[10:13], v[172:175], v[220:223], v[10:13]
	v_mfma_f32_16x16x32_bf16 v[14:17], v[172:175], v[224:227], v[14:17]
	v_mfma_f32_16x16x32_bf16 v[18:21], v[176:179], v[212:215], v[18:21]
	v_mfma_f32_16x16x32_bf16 v[22:25], v[176:179], v[216:219], v[22:25]
	v_mfma_f32_16x16x32_bf16 v[26:29], v[176:179], v[220:223], v[26:29]
	v_mfma_f32_16x16x32_bf16 v[30:33], v[176:179], v[224:227], v[30:33]
	v_mfma_f32_16x16x32_bf16 v[34:37], v[180:183], v[212:215], v[34:37]
	v_mfma_f32_16x16x32_bf16 v[38:41], v[180:183], v[216:219], v[38:41]
	v_mfma_f32_16x16x32_bf16 v[42:45], v[180:183], v[220:223], v[42:45]
	v_mfma_f32_16x16x32_bf16 v[46:49], v[180:183], v[224:227], v[46:49]
	v_mfma_f32_16x16x32_bf16 v[50:53], v[184:187], v[212:215], v[50:53]
	v_mfma_f32_16x16x32_bf16 v[54:57], v[184:187], v[216:219], v[54:57]
	v_mfma_f32_16x16x32_bf16 v[58:61], v[184:187], v[220:223], v[58:61]
	v_mfma_f32_16x16x32_bf16 v[62:65], v[184:187], v[224:227], v[62:65]
	s_waitcnt vmcnt(6)
	s_barrier
	v_add_u32_e32 v236, s40, v232
	v_add_u32_e32 v237, s40, v233
	ds_read_b128 v[188:191], v236
	ds_read_b128 v[196:199], v236 offset:2048
	ds_read_b128 v[200:203], v236 offset:4096
	ds_read_b128 v[204:207], v236 offset:6144
	ds_read_b128 v[212:215], v237
	ds_read_b128 v[216:219], v237 offset:2048
	ds_read_b128 v[220:223], v237 offset:4096
	ds_read_b128 v[224:227], v237 offset:6144
	s_mov_b32 m0, s51
	s_nop 0
	global_load_lds_dwordx4 v229, s[46:47]
	s_add_i32 m0, s51, 0x400
	s_nop 0
	global_load_lds_dwordx4 v231, s[46:47]
	s_add_i32 m0, s51, 0x2000
	s_nop 0
	global_load_lds_dwordx4 v228, s[48:49]
	s_add_i32 m0, s51, 0x2400
	s_nop 0
	global_load_lds_dwordx4 v230, s[48:49]
	s_add_i32 m0, s51, 0x4000
	s_nop 0
	global_load_lds_dwordx4 v229, s[48:49]
	s_add_i32 m0, s51, 0x4400
	s_nop 0
	global_load_lds_dwordx4 v231, s[48:49]
	s_waitcnt lgkmcnt(4)
	v_mfma_f32_16x16x32_bf16 v[66:69], v[136:139], v[188:191], v[66:69]
	v_mfma_f32_16x16x32_bf16 v[70:73], v[136:139], v[196:199], v[70:73]
	v_mfma_f32_16x16x32_bf16 v[74:77], v[136:139], v[200:203], v[74:77]
	v_mfma_f32_16x16x32_bf16 v[78:81], v[136:139], v[204:207], v[78:81]
	v_mfma_f32_16x16x32_bf16 v[82:85], v[140:143], v[188:191], v[82:85]
	v_mfma_f32_16x16x32_bf16 v[86:89], v[140:143], v[196:199], v[86:89]
	v_mfma_f32_16x16x32_bf16 v[90:93], v[140:143], v[200:203], v[90:93]
	v_mfma_f32_16x16x32_bf16 v[94:97], v[140:143], v[204:207], v[94:97]
	v_mfma_f32_16x16x32_bf16 v[98:101], v[144:147], v[188:191], v[98:101]
	v_mfma_f32_16x16x32_bf16 v[102:105], v[144:147], v[196:199], v[102:105]
	v_mfma_f32_16x16x32_bf16 v[106:109], v[144:147], v[200:203], v[106:109]
	v_mfma_f32_16x16x32_bf16 v[110:113], v[144:147], v[204:207], v[110:113]
	v_mfma_f32_16x16x32_bf16 v[114:117], v[148:151], v[188:191], v[114:117]
	v_mfma_f32_16x16x32_bf16 v[118:121], v[148:151], v[196:199], v[118:121]
	v_mfma_f32_16x16x32_bf16 v[122:125], v[148:151], v[200:203], v[122:125]
	v_mfma_f32_16x16x32_bf16 v[126:129], v[148:151], v[204:207], v[126:129]
	s_waitcnt lgkmcnt(0)
	v_mfma_f32_16x16x32_bf16 v[66:69], v[172:175], v[212:215], v[66:69]
	v_mfma_f32_16x16x32_bf16 v[70:73], v[172:175], v[216:219], v[70:73]
	v_mfma_f32_16x16x32_bf16 v[74:77], v[172:175], v[220:223], v[74:77]
	v_mfma_f32_16x16x32_bf16 v[78:81], v[172:175], v[224:227], v[78:81]
	v_mfma_f32_16x16x32_bf16 v[82:85], v[176:179], v[212:215], v[82:85]
	v_mfma_f32_16x16x32_bf16 v[86:89], v[176:179], v[216:219], v[86:89]
	v_mfma_f32_16x16x32_bf16 v[90:93], v[176:179], v[220:223], v[90:93]
	v_mfma_f32_16x16x32_bf16 v[94:97], v[176:179], v[224:227], v[94:97]
	v_mfma_f32_16x16x32_bf16 v[98:101], v[180:183], v[212:215], v[98:101]
	v_mfma_f32_16x16x32_bf16 v[102:105], v[180:183], v[216:219], v[102:105]
	v_mfma_f32_16x16x32_bf16 v[106:109], v[180:183], v[220:223], v[106:109]
	v_mfma_f32_16x16x32_bf16 v[110:113], v[180:183], v[224:227], v[110:113]
	v_mfma_f32_16x16x32_bf16 v[114:117], v[184:187], v[212:215], v[114:117]
	v_mfma_f32_16x16x32_bf16 v[118:121], v[184:187], v[216:219], v[118:121]
	v_mfma_f32_16x16x32_bf16 v[122:125], v[184:187], v[220:223], v[122:125]
	v_mfma_f32_16x16x32_bf16 v[126:129], v[184:187], v[224:227], v[126:129]
	v_add_u32_e32 v228, 0x80, v228
	v_add_u32_e32 v229, 0x80, v229
	v_add_u32_e32 v230, 0x80, v230
	v_add_u32_e32 v231, 0x80, v231
	s_waitcnt vmcnt(4)
	s_barrier
	v_add_u32_e32 v234, s23, v232
	v_add_u32_e32 v236, s29, v232
	v_add_u32_e32 v235, s23, v233
	v_add_u32_e32 v237, s29, v233
	ds_read_b128 v[136:139], v234
	ds_read_b128 v[140:143], v234 offset:2048
	ds_read_b128 v[144:147], v234 offset:4096
	ds_read_b128 v[148:151], v234 offset:6144
	ds_read_b128 v[188:191], v236
	ds_read_b128 v[196:199], v236 offset:2048
	ds_read_b128 v[200:203], v236 offset:4096
	ds_read_b128 v[204:207], v236 offset:6144
	ds_read_b128 v[172:175], v235
	ds_read_b128 v[176:179], v235 offset:2048
	ds_read_b128 v[180:183], v235 offset:4096
	ds_read_b128 v[184:187], v235 offset:6144
	ds_read_b128 v[212:215], v237
	ds_read_b128 v[216:219], v237 offset:2048
	ds_read_b128 v[220:223], v237 offset:4096
	ds_read_b128 v[224:227], v237 offset:6144
	s_waitcnt lgkmcnt(8)
	v_mfma_f32_16x16x32_bf16 v[2:5], v[136:139], v[188:191], v[2:5]
	v_mfma_f32_16x16x32_bf16 v[6:9], v[136:139], v[196:199], v[6:9]
	v_mfma_f32_16x16x32_bf16 v[10:13], v[136:139], v[200:203], v[10:13]
	v_mfma_f32_16x16x32_bf16 v[14:17], v[136:139], v[204:207], v[14:17]
	v_mfma_f32_16x16x32_bf16 v[18:21], v[140:143], v[188:191], v[18:21]
	v_mfma_f32_16x16x32_bf16 v[22:25], v[140:143], v[196:199], v[22:25]
	v_mfma_f32_16x16x32_bf16 v[26:29], v[140:143], v[200:203], v[26:29]
	v_mfma_f32_16x16x32_bf16 v[30:33], v[140:143], v[204:207], v[30:33]
	v_mfma_f32_16x16x32_bf16 v[34:37], v[144:147], v[188:191], v[34:37]
	v_mfma_f32_16x16x32_bf16 v[38:41], v[144:147], v[196:199], v[38:41]
	v_mfma_f32_16x16x32_bf16 v[42:45], v[144:147], v[200:203], v[42:45]
	v_mfma_f32_16x16x32_bf16 v[46:49], v[144:147], v[204:207], v[46:49]
	v_mfma_f32_16x16x32_bf16 v[50:53], v[148:151], v[188:191], v[50:53]
	v_mfma_f32_16x16x32_bf16 v[54:57], v[148:151], v[196:199], v[54:57]
	v_mfma_f32_16x16x32_bf16 v[58:61], v[148:151], v[200:203], v[58:61]
	v_mfma_f32_16x16x32_bf16 v[62:65], v[148:151], v[204:207], v[62:65]
	s_waitcnt lgkmcnt(0)
	v_mfma_f32_16x16x32_bf16 v[2:5], v[172:175], v[212:215], v[2:5]
	v_mfma_f32_16x16x32_bf16 v[6:9], v[172:175], v[216:219], v[6:9]
	v_mfma_f32_16x16x32_bf16 v[10:13], v[172:175], v[220:223], v[10:13]
	v_mfma_f32_16x16x32_bf16 v[14:17], v[172:175], v[224:227], v[14:17]
	v_mfma_f32_16x16x32_bf16 v[18:21], v[176:179], v[212:215], v[18:21]
	v_mfma_f32_16x16x32_bf16 v[22:25], v[176:179], v[216:219], v[22:25]
	v_mfma_f32_16x16x32_bf16 v[26:29], v[176:179], v[220:223], v[26:29]
	v_mfma_f32_16x16x32_bf16 v[30:33], v[176:179], v[224:227], v[30:33]
	v_mfma_f32_16x16x32_bf16 v[34:37], v[180:183], v[212:215], v[34:37]
	v_mfma_f32_16x16x32_bf16 v[38:41], v[180:183], v[216:219], v[38:41]
	v_mfma_f32_16x16x32_bf16 v[42:45], v[180:183], v[220:223], v[42:45]
	v_mfma_f32_16x16x32_bf16 v[46:49], v[180:183], v[224:227], v[46:49]
	v_mfma_f32_16x16x32_bf16 v[50:53], v[184:187], v[212:215], v[50:53]
	v_mfma_f32_16x16x32_bf16 v[54:57], v[184:187], v[216:219], v[54:57]
	v_mfma_f32_16x16x32_bf16 v[58:61], v[184:187], v[220:223], v[58:61]
	v_mfma_f32_16x16x32_bf16 v[62:65], v[184:187], v[224:227], v[62:65]
	s_waitcnt vmcnt(0)
	s_barrier
	v_add_u32_e32 v236, s41, v232
	v_add_u32_e32 v237, s41, v233
	ds_read_b128 v[188:191], v236
	ds_read_b128 v[196:199], v236 offset:2048
	ds_read_b128 v[200:203], v236 offset:4096
	ds_read_b128 v[204:207], v236 offset:6144
	ds_read_b128 v[212:215], v237
	ds_read_b128 v[216:219], v237 offset:2048
	ds_read_b128 v[220:223], v237 offset:4096
	ds_read_b128 v[224:227], v237 offset:6144
	s_waitcnt lgkmcnt(4)
	v_mfma_f32_16x16x32_bf16 v[66:69], v[136:139], v[188:191], v[66:69]
	v_mfma_f32_16x16x32_bf16 v[70:73], v[136:139], v[196:199], v[70:73]
	v_mfma_f32_16x16x32_bf16 v[74:77], v[136:139], v[200:203], v[74:77]
	v_mfma_f32_16x16x32_bf16 v[78:81], v[136:139], v[204:207], v[78:81]
	v_mfma_f32_16x16x32_bf16 v[82:85], v[140:143], v[188:191], v[82:85]
	v_mfma_f32_16x16x32_bf16 v[86:89], v[140:143], v[196:199], v[86:89]
	v_mfma_f32_16x16x32_bf16 v[90:93], v[140:143], v[200:203], v[90:93]
	v_mfma_f32_16x16x32_bf16 v[94:97], v[140:143], v[204:207], v[94:97]
	v_mfma_f32_16x16x32_bf16 v[98:101], v[144:147], v[188:191], v[98:101]
	v_mfma_f32_16x16x32_bf16 v[102:105], v[144:147], v[196:199], v[102:105]
	v_mfma_f32_16x16x32_bf16 v[106:109], v[144:147], v[200:203], v[106:109]
	v_mfma_f32_16x16x32_bf16 v[110:113], v[144:147], v[204:207], v[110:113]
	v_mfma_f32_16x16x32_bf16 v[114:117], v[148:151], v[188:191], v[114:117]
	v_mfma_f32_16x16x32_bf16 v[118:121], v[148:151], v[196:199], v[118:121]
	v_mfma_f32_16x16x32_bf16 v[122:125], v[148:151], v[200:203], v[122:125]
	v_mfma_f32_16x16x32_bf16 v[126:129], v[148:151], v[204:207], v[126:129]
	s_waitcnt lgkmcnt(0)
	v_mfma_f32_16x16x32_bf16 v[66:69], v[172:175], v[212:215], v[66:69]
	v_mfma_f32_16x16x32_bf16 v[70:73], v[172:175], v[216:219], v[70:73]
	v_mfma_f32_16x16x32_bf16 v[74:77], v[172:175], v[220:223], v[74:77]
	v_mfma_f32_16x16x32_bf16 v[78:81], v[172:175], v[224:227], v[78:81]
	v_mfma_f32_16x16x32_bf16 v[82:85], v[176:179], v[212:215], v[82:85]
	v_mfma_f32_16x16x32_bf16 v[86:89], v[176:179], v[216:219], v[86:89]
	v_mfma_f32_16x16x32_bf16 v[90:93], v[176:179], v[220:223], v[90:93]
	v_mfma_f32_16x16x32_bf16 v[94:97], v[176:179], v[224:227], v[94:97]
	v_mfma_f32_16x16x32_bf16 v[98:101], v[180:183], v[212:215], v[98:101]
	v_mfma_f32_16x16x32_bf16 v[102:105], v[180:183], v[216:219], v[102:105]
	v_mfma_f32_16x16x32_bf16 v[106:109], v[180:183], v[220:223], v[106:109]
	v_mfma_f32_16x16x32_bf16 v[110:113], v[180:183], v[224:227], v[110:113]
	v_mfma_f32_16x16x32_bf16 v[114:117], v[184:187], v[212:215], v[114:117]
	v_mfma_f32_16x16x32_bf16 v[118:121], v[184:187], v[216:219], v[118:121]
	v_mfma_f32_16x16x32_bf16 v[122:125], v[184:187], v[220:223], v[122:125]
	v_mfma_f32_16x16x32_bf16 v[126:129], v[184:187], v[224:227], v[126:129]
	s_nop 7
	s_barrier
	s_load_dwordx2 s[58:59], s[12:13], 0x180
	v_mov_b32_e32 v241, 0x3a000000
	v_mov_b32_e32 v242, 0x358637bd
	v_fma_f32 v152, v152, v241, v242
	v_fma_f32 v153, v153, v241, v242
	v_fma_f32 v154, v154, v241, v242
	v_fma_f32 v155, v155, v241, v242
	v_fma_f32 v244, v244, v241, v242
	v_fma_f32 v245, v245, v241, v242
	v_fma_f32 v246, v246, v241, v242
	v_fma_f32 v247, v247, v241, v242
	v_fma_f32 v248, v248, v241, v242
	v_fma_f32 v249, v249, v241, v242
	v_fma_f32 v250, v250, v241, v242
	v_fma_f32 v251, v251, v241, v242
	v_fma_f32 v252, v252, v241, v242
	v_fma_f32 v253, v253, v241, v242
	v_fma_f32 v254, v254, v241, v242
	v_fma_f32 v255, v255, v241, v242
	v_rsq_f32_e32 v152, v152
	v_rsq_f32_e32 v153, v153
	v_rsq_f32_e32 v154, v154
	v_rsq_f32_e32 v155, v155
	v_rsq_f32_e32 v244, v244
	v_rsq_f32_e32 v245, v245
	v_rsq_f32_e32 v246, v246
	v_rsq_f32_e32 v247, v247
	v_rsq_f32_e32 v248, v248
	v_rsq_f32_e32 v249, v249
	v_rsq_f32_e32 v250, v250
	v_rsq_f32_e32 v251, v251
	v_rsq_f32_e32 v252, v252
	v_rsq_f32_e32 v253, v253
	v_rsq_f32_e32 v254, v254
	v_rsq_f32_e32 v255, v255
	v_and_b32_e32 v241, 63, v131
	v_lshrrev_b32_e32 v242, 4, v241
	v_and_b32_e32 v241, 15, v241
	s_lshr_b32 s56, s50, 1
	s_and_b32 s57, s50, 1
	s_mul_i32 s56, s56, 64*144
	s_lshl_b32 s57, s57, 6
	s_add_i32 s56, s56, s57
	s_add_i32 s56, s56, 16
	v_mul_u32_u24_e32 v242, 4*144, v242
	v_lshl_add_u32 v242, v241, 1, v242
	v_add_u32_e32 v188, s56, v242
	v_lshrrev_b32_e32 v241, 3, v131
	v_and_b32_e32 v242, 7, v131
	v_lshlrev_b32_e32 v242, 4, v242
	v_mul_u32_u24_e32 v189, 144, v241
	v_add3_u32 v189, v189, v242, 16
	s_movk_i32 s56, 0x2c80
	v_mad_u32_u24 v243, v241, s56, v242
	s_mul_i32 s56, s53, 0x2c80
	s_add_i32 s56, s56, s54
	s_waitcnt lgkmcnt(0)
	s_add_u32 s58, s58, s56
	s_addc_u32 s59, s59, 0
	v_mul_f32_e32 v2, v2, v152
	v_mul_f32_e32 v6, v6, v152
	v_mul_f32_e32 v10, v10, v152
	v_mul_f32_e32 v14, v14, v152
	v_mul_f32_e32 v136, 0xbfb8aa3b, v2
	v_mul_f32_e32 v137, 0xbfb8aa3b, v6
	v_exp_f32_e32 v136, v136
	v_exp_f32_e32 v137, v137
	v_mul_f32_e32 v10, v10, v2
	v_mul_f32_e32 v14, v14, v6
	v_add_f32_e32 v136, 1.0, v136
	v_add_f32_e32 v137, 1.0, v137
	v_rcp_f32_e32 v136, v136
	v_rcp_f32_e32 v137, v137
	s_nop 0
	v_mul_f32_e32 v10, v10, v136
	v_mul_f32_e32 v14, v14, v137
	v_cvt_pk_bf16_f32 v10, v10, v14
	ds_write_b16 v188, v10
	ds_write_b16_d16_hi v188, v10 offset:32
	v_mul_f32_e32 v3, v3, v153
	v_mul_f32_e32 v7, v7, v153
	v_mul_f32_e32 v11, v11, v153
	v_mul_f32_e32 v15, v15, v153
	v_mul_f32_e32 v136, 0xbfb8aa3b, v3
	v_mul_f32_e32 v137, 0xbfb8aa3b, v7
	v_exp_f32_e32 v136, v136
	v_exp_f32_e32 v137, v137
	v_mul_f32_e32 v11, v11, v3
	v_mul_f32_e32 v15, v15, v7
	v_add_f32_e32 v136, 1.0, v136
	v_add_f32_e32 v137, 1.0, v137
	v_rcp_f32_e32 v136, v136
	v_rcp_f32_e32 v137, v137
	s_nop 0
	v_mul_f32_e32 v11, v11, v136
	v_mul_f32_e32 v15, v15, v137
	v_cvt_pk_bf16_f32 v11, v11, v15
	ds_write_b16 v188, v11 offset:144
	ds_write_b16_d16_hi v188, v11 offset:176
	v_mul_f32_e32 v4, v4, v154
	v_mul_f32_e32 v8, v8, v154
	v_mul_f32_e32 v12, v12, v154
	v_mul_f32_e32 v16, v16, v154
	v_mul_f32_e32 v136, 0xbfb8aa3b, v4
	v_mul_f32_e32 v137, 0xbfb8aa3b, v8
	v_exp_f32_e32 v136, v136
	v_exp_f32_e32 v137, v137
	v_mul_f32_e32 v12, v12, v4
	v_mul_f32_e32 v16, v16, v8
	v_add_f32_e32 v136, 1.0, v136
	v_add_f32_e32 v137, 1.0, v137
	v_rcp_f32_e32 v136, v136
	v_rcp_f32_e32 v137, v137
	s_nop 0
	v_mul_f32_e32 v12, v12, v136
	v_mul_f32_e32 v16, v16, v137
	v_cvt_pk_bf16_f32 v12, v12, v16
	ds_write_b16 v188, v12 offset:288
	ds_write_b16_d16_hi v188, v12 offset:320
	v_mul_f32_e32 v5, v5, v155
	v_mul_f32_e32 v9, v9, v155
	v_mul_f32_e32 v13, v13, v155
	v_mul_f32_e32 v17, v17, v155
	v_mul_f32_e32 v136, 0xbfb8aa3b, v5
	v_mul_f32_e32 v137, 0xbfb8aa3b, v9
	v_exp_f32_e32 v136, v136
	v_exp_f32_e32 v137, v137
	v_mul_f32_e32 v13, v13, v5
	v_mul_f32_e32 v17, v17, v9
	v_add_f32_e32 v136, 1.0, v136
	v_add_f32_e32 v137, 1.0, v137
	v_rcp_f32_e32 v136, v136
	v_rcp_f32_e32 v137, v137
	s_nop 0
	v_mul_f32_e32 v13, v13, v136
	v_mul_f32_e32 v17, v17, v137
	v_cvt_pk_bf16_f32 v13, v13, v17
	ds_write_b16 v188, v13 offset:432
	ds_write_b16_d16_hi v188, v13 offset:464
	v_mul_f32_e32 v18, v18, v244
	v_mul_f32_e32 v22, v22, v244
	v_mul_f32_e32 v26, v26, v244
	v_mul_f32_e32 v30, v30, v244
	v_mul_f32_e32 v136, 0xbfb8aa3b, v18
	v_mul_f32_e32 v137, 0xbfb8aa3b, v22
	v_exp_f32_e32 v136, v136
	v_exp_f32_e32 v137, v137
	v_mul_f32_e32 v26, v26, v18
	v_mul_f32_e32 v30, v30, v22
	v_add_f32_e32 v136, 1.0, v136
	v_add_f32_e32 v137, 1.0, v137
	v_rcp_f32_e32 v136, v136
	v_rcp_f32_e32 v137, v137
	s_nop 0
	v_mul_f32_e32 v26, v26, v136
	v_mul_f32_e32 v30, v30, v137
	v_cvt_pk_bf16_f32 v26, v26, v30
	ds_write_b16 v188, v26 offset:2304
	ds_write_b16_d16_hi v188, v26 offset:2336
	v_mul_f32_e32 v19, v19, v245
	v_mul_f32_e32 v23, v23, v245
	v_mul_f32_e32 v27, v27, v245
	v_mul_f32_e32 v31, v31, v245
	v_mul_f32_e32 v136, 0xbfb8aa3b, v19
	v_mul_f32_e32 v137, 0xbfb8aa3b, v23
	v_exp_f32_e32 v136, v136
	v_exp_f32_e32 v137, v137
	v_mul_f32_e32 v27, v27, v19
	v_mul_f32_e32 v31, v31, v23
	v_add_f32_e32 v136, 1.0, v136
	v_add_f32_e32 v137, 1.0, v137
	v_rcp_f32_e32 v136, v136
	v_rcp_f32_e32 v137, v137
	s_nop 0
	v_mul_f32_e32 v27, v27, v136
	v_mul_f32_e32 v31, v31, v137
	v_cvt_pk_bf16_f32 v27, v27, v31
	ds_write_b16 v188, v27 offset:2448
	ds_write_b16_d16_hi v188, v27 offset:2480
	v_mul_f32_e32 v20, v20, v246
	v_mul_f32_e32 v24, v24, v246
	v_mul_f32_e32 v28, v28, v246
	v_mul_f32_e32 v32, v32, v246
	v_mul_f32_e32 v136, 0xbfb8aa3b, v20
	v_mul_f32_e32 v137, 0xbfb8aa3b, v24
	v_exp_f32_e32 v136, v136
	v_exp_f32_e32 v137, v137
	v_mul_f32_e32 v28, v28, v20
	v_mul_f32_e32 v32, v32, v24
	v_add_f32_e32 v136, 1.0, v136
	v_add_f32_e32 v137, 1.0, v137
	v_rcp_f32_e32 v136, v136
	v_rcp_f32_e32 v137, v137
	s_nop 0
	v_mul_f32_e32 v28, v28, v136
	v_mul_f32_e32 v32, v32, v137
	v_cvt_pk_bf16_f32 v28, v28, v32
	ds_write_b16 v188, v28 offset:2592
	ds_write_b16_d16_hi v188, v28 offset:2624
	v_mul_f32_e32 v21, v21, v247
	v_mul_f32_e32 v25, v25, v247
	v_mul_f32_e32 v29, v29, v247
	v_mul_f32_e32 v33, v33, v247
	v_mul_f32_e32 v136, 0xbfb8aa3b, v21
	v_mul_f32_e32 v137, 0xbfb8aa3b, v25
	v_exp_f32_e32 v136, v136
	v_exp_f32_e32 v137, v137
	v_mul_f32_e32 v29, v29, v21
	v_mul_f32_e32 v33, v33, v25
	v_add_f32_e32 v136, 1.0, v136
	v_add_f32_e32 v137, 1.0, v137
	v_rcp_f32_e32 v136, v136
	v_rcp_f32_e32 v137, v137
	s_nop 0
	v_mul_f32_e32 v29, v29, v136
	v_mul_f32_e32 v33, v33, v137
	v_cvt_pk_bf16_f32 v29, v29, v33
	ds_write_b16 v188, v29 offset:2736
	ds_write_b16_d16_hi v188, v29 offset:2768
	v_mul_f32_e32 v34, v34, v248
	v_mul_f32_e32 v38, v38, v248
	v_mul_f32_e32 v42, v42, v248
	v_mul_f32_e32 v46, v46, v248
	v_mul_f32_e32 v136, 0xbfb8aa3b, v34
	v_mul_f32_e32 v137, 0xbfb8aa3b, v38
	v_exp_f32_e32 v136, v136
	v_exp_f32_e32 v137, v137
	v_mul_f32_e32 v42, v42, v34
	v_mul_f32_e32 v46, v46, v38
	v_add_f32_e32 v136, 1.0, v136
	v_add_f32_e32 v137, 1.0, v137
	v_rcp_f32_e32 v136, v136
	v_rcp_f32_e32 v137, v137
	s_nop 0
	v_mul_f32_e32 v42, v42, v136
	v_mul_f32_e32 v46, v46, v137
	v_cvt_pk_bf16_f32 v42, v42, v46
	ds_write_b16 v188, v42 offset:4608
	ds_write_b16_d16_hi v188, v42 offset:4640
	v_mul_f32_e32 v35, v35, v249
	v_mul_f32_e32 v39, v39, v249
	v_mul_f32_e32 v43, v43, v249
	v_mul_f32_e32 v47, v47, v249
	v_mul_f32_e32 v136, 0xbfb8aa3b, v35
	v_mul_f32_e32 v137, 0xbfb8aa3b, v39
	v_exp_f32_e32 v136, v136
	v_exp_f32_e32 v137, v137
	v_mul_f32_e32 v43, v43, v35
	v_mul_f32_e32 v47, v47, v39
	v_add_f32_e32 v136, 1.0, v136
	v_add_f32_e32 v137, 1.0, v137
	v_rcp_f32_e32 v136, v136
	v_rcp_f32_e32 v137, v137
	s_nop 0
	v_mul_f32_e32 v43, v43, v136
	v_mul_f32_e32 v47, v47, v137
	v_cvt_pk_bf16_f32 v43, v43, v47
	ds_write_b16 v188, v43 offset:4752
	ds_write_b16_d16_hi v188, v43 offset:4784
	v_mul_f32_e32 v36, v36, v250
	v_mul_f32_e32 v40, v40, v250
	v_mul_f32_e32 v44, v44, v250
	v_mul_f32_e32 v48, v48, v250
	v_mul_f32_e32 v136, 0xbfb8aa3b, v36
	v_mul_f32_e32 v137, 0xbfb8aa3b, v40
	v_exp_f32_e32 v136, v136
	v_exp_f32_e32 v137, v137
	v_mul_f32_e32 v44, v44, v36
	v_mul_f32_e32 v48, v48, v40
	v_add_f32_e32 v136, 1.0, v136
	v_add_f32_e32 v137, 1.0, v137
	v_rcp_f32_e32 v136, v136
	v_rcp_f32_e32 v137, v137
	s_nop 0
	v_mul_f32_e32 v44, v44, v136
	v_mul_f32_e32 v48, v48, v137
	v_cvt_pk_bf16_f32 v44, v44, v48
	ds_write_b16 v188, v44 offset:4896
	ds_write_b16_d16_hi v188, v44 offset:4928
	v_mul_f32_e32 v37, v37, v251
	v_mul_f32_e32 v41, v41, v251
	v_mul_f32_e32 v45, v45, v251
	v_mul_f32_e32 v49, v49, v251
	v_mul_f32_e32 v136, 0xbfb8aa3b, v37
	v_mul_f32_e32 v137, 0xbfb8aa3b, v41
	v_exp_f32_e32 v136, v136
	v_exp_f32_e32 v137, v137
	v_mul_f32_e32 v45, v45, v37
	v_mul_f32_e32 v49, v49, v41
	v_add_f32_e32 v136, 1.0, v136
	v_add_f32_e32 v137, 1.0, v137
	v_rcp_f32_e32 v136, v136
	v_rcp_f32_e32 v137, v137
	s_nop 0
	v_mul_f32_e32 v45, v45, v136
	v_mul_f32_e32 v49, v49, v137
	v_cvt_pk_bf16_f32 v45, v45, v49
	ds_write_b16 v188, v45 offset:5040
	ds_write_b16_d16_hi v188, v45 offset:5072
	v_mul_f32_e32 v50, v50, v252
	v_mul_f32_e32 v54, v54, v252
	v_mul_f32_e32 v58, v58, v252
	v_mul_f32_e32 v62, v62, v252
	v_mul_f32_e32 v136, 0xbfb8aa3b, v50
	v_mul_f32_e32 v137, 0xbfb8aa3b, v54
	v_exp_f32_e32 v136, v136
	v_exp_f32_e32 v137, v137
	v_mul_f32_e32 v58, v58, v50
	v_mul_f32_e32 v62, v62, v54
	v_add_f32_e32 v136, 1.0, v136
	v_add_f32_e32 v137, 1.0, v137
	v_rcp_f32_e32 v136, v136
	v_rcp_f32_e32 v137, v137
	s_nop 0
	v_mul_f32_e32 v58, v58, v136
	v_mul_f32_e32 v62, v62, v137
	v_cvt_pk_bf16_f32 v58, v58, v62
	ds_write_b16 v188, v58 offset:6912
	ds_write_b16_d16_hi v188, v58 offset:6944
	v_mul_f32_e32 v51, v51, v253
	v_mul_f32_e32 v55, v55, v253
	v_mul_f32_e32 v59, v59, v253
	v_mul_f32_e32 v63, v63, v253
	v_mul_f32_e32 v136, 0xbfb8aa3b, v51
	v_mul_f32_e32 v137, 0xbfb8aa3b, v55
	v_exp_f32_e32 v136, v136
	v_exp_f32_e32 v137, v137
	v_mul_f32_e32 v59, v59, v51
	v_mul_f32_e32 v63, v63, v55
	v_add_f32_e32 v136, 1.0, v136
	v_add_f32_e32 v137, 1.0, v137
	v_rcp_f32_e32 v136, v136
	v_rcp_f32_e32 v137, v137
	s_nop 0
	v_mul_f32_e32 v59, v59, v136
	v_mul_f32_e32 v63, v63, v137
	v_cvt_pk_bf16_f32 v59, v59, v63
	ds_write_b16 v188, v59 offset:7056
	ds_write_b16_d16_hi v188, v59 offset:7088
	v_mul_f32_e32 v52, v52, v254
	v_mul_f32_e32 v56, v56, v254
	v_mul_f32_e32 v60, v60, v254
	v_mul_f32_e32 v64, v64, v254
	v_mul_f32_e32 v136, 0xbfb8aa3b, v52
	v_mul_f32_e32 v137, 0xbfb8aa3b, v56
	v_exp_f32_e32 v136, v136
	v_exp_f32_e32 v137, v137
	v_mul_f32_e32 v60, v60, v52
	v_mul_f32_e32 v64, v64, v56
	v_add_f32_e32 v136, 1.0, v136
	v_add_f32_e32 v137, 1.0, v137
	v_rcp_f32_e32 v136, v136
	v_rcp_f32_e32 v137, v137
	s_nop 0
	v_mul_f32_e32 v60, v60, v136
	v_mul_f32_e32 v64, v64, v137
	v_cvt_pk_bf16_f32 v60, v60, v64
	ds_write_b16 v188, v60 offset:7200
	ds_write_b16_d16_hi v188, v60 offset:7232
	v_mul_f32_e32 v53, v53, v255
	v_mul_f32_e32 v57, v57, v255
	v_mul_f32_e32 v61, v61, v255
	v_mul_f32_e32 v65, v65, v255
	v_mul_f32_e32 v136, 0xbfb8aa3b, v53
	v_mul_f32_e32 v137, 0xbfb8aa3b, v57
	v_exp_f32_e32 v136, v136
	v_exp_f32_e32 v137, v137
	v_mul_f32_e32 v61, v61, v53
	v_mul_f32_e32 v65, v65, v57
	v_add_f32_e32 v136, 1.0, v136
	v_add_f32_e32 v137, 1.0, v137
	v_rcp_f32_e32 v136, v136
	v_rcp_f32_e32 v137, v137
	s_nop 0
	v_mul_f32_e32 v61, v61, v136
	v_mul_f32_e32 v65, v65, v137
	v_cvt_pk_bf16_f32 v61, v61, v65
	ds_write_b16 v188, v61 offset:7344
	ds_write_b16_d16_hi v188, v61 offset:7376
	s_waitcnt lgkmcnt(0)
	s_barrier
	ds_read_b128 v[144:147], v189
	ds_read_b128 v[148:151], v189 offset:4608
	ds_read_b128 v[172:175], v189 offset:9216
	ds_read_b128 v[176:179], v189 offset:13824
	s_mov_b32 s56, s58
	s_mov_b32 s57, s59
	s_waitcnt lgkmcnt(3)
	global_store_dwordx4 v243, v[144:147], s[56:57]
	s_add_u32 s56, s56, 0x59000
	s_addc_u32 s57, s57, 0
	s_waitcnt lgkmcnt(2)
	global_store_dwordx4 v243, v[148:151], s[56:57]
	s_add_u32 s56, s56, 0x59000
	s_addc_u32 s57, s57, 0
	s_waitcnt lgkmcnt(1)
	global_store_dwordx4 v243, v[172:175], s[56:57]
	s_add_u32 s56, s56, 0x59000
	s_addc_u32 s57, s57, 0
	s_waitcnt lgkmcnt(0)
	global_store_dwordx4 v243, v[176:179], s[56:57]
	s_add_u32 s58, s58, 0x400
	s_addc_u32 s59, s59, 0
	s_barrier
	v_mul_f32_e32 v66, v66, v152
	v_mul_f32_e32 v70, v70, v152
	v_mul_f32_e32 v74, v74, v152
	v_mul_f32_e32 v78, v78, v152
	v_mul_f32_e32 v136, 0xbfb8aa3b, v66
	v_mul_f32_e32 v137, 0xbfb8aa3b, v70
	v_exp_f32_e32 v136, v136
	v_exp_f32_e32 v137, v137
	v_mul_f32_e32 v74, v74, v66
	v_mul_f32_e32 v78, v78, v70
	v_add_f32_e32 v136, 1.0, v136
	v_add_f32_e32 v137, 1.0, v137
	v_rcp_f32_e32 v136, v136
	v_rcp_f32_e32 v137, v137
	s_nop 0
	v_mul_f32_e32 v74, v74, v136
	v_mul_f32_e32 v78, v78, v137
	v_cvt_pk_bf16_f32 v74, v74, v78
	ds_write_b16 v188, v74
	ds_write_b16_d16_hi v188, v74 offset:32
	v_mul_f32_e32 v67, v67, v153
	v_mul_f32_e32 v71, v71, v153
	v_mul_f32_e32 v75, v75, v153
	v_mul_f32_e32 v79, v79, v153
	v_mul_f32_e32 v136, 0xbfb8aa3b, v67
	v_mul_f32_e32 v137, 0xbfb8aa3b, v71
	v_exp_f32_e32 v136, v136
	v_exp_f32_e32 v137, v137
	v_mul_f32_e32 v75, v75, v67
	v_mul_f32_e32 v79, v79, v71
	v_add_f32_e32 v136, 1.0, v136
	v_add_f32_e32 v137, 1.0, v137
	v_rcp_f32_e32 v136, v136
	v_rcp_f32_e32 v137, v137
	s_nop 0
	v_mul_f32_e32 v75, v75, v136
	v_mul_f32_e32 v79, v79, v137
	v_cvt_pk_bf16_f32 v75, v75, v79
	ds_write_b16 v188, v75 offset:144
	ds_write_b16_d16_hi v188, v75 offset:176
	v_mul_f32_e32 v68, v68, v154
	v_mul_f32_e32 v72, v72, v154
	v_mul_f32_e32 v76, v76, v154
	v_mul_f32_e32 v80, v80, v154
	v_mul_f32_e32 v136, 0xbfb8aa3b, v68
	v_mul_f32_e32 v137, 0xbfb8aa3b, v72
	v_exp_f32_e32 v136, v136
	v_exp_f32_e32 v137, v137
	v_mul_f32_e32 v76, v76, v68
	v_mul_f32_e32 v80, v80, v72
	v_add_f32_e32 v136, 1.0, v136
	v_add_f32_e32 v137, 1.0, v137
	v_rcp_f32_e32 v136, v136
	v_rcp_f32_e32 v137, v137
	s_nop 0
	v_mul_f32_e32 v76, v76, v136
	v_mul_f32_e32 v80, v80, v137
	v_cvt_pk_bf16_f32 v76, v76, v80
	ds_write_b16 v188, v76 offset:288
	ds_write_b16_d16_hi v188, v76 offset:320
	v_mul_f32_e32 v69, v69, v155
	v_mul_f32_e32 v73, v73, v155
	v_mul_f32_e32 v77, v77, v155
	v_mul_f32_e32 v81, v81, v155
	v_mul_f32_e32 v136, 0xbfb8aa3b, v69
	v_mul_f32_e32 v137, 0xbfb8aa3b, v73
	v_exp_f32_e32 v136, v136
	v_exp_f32_e32 v137, v137
	v_mul_f32_e32 v77, v77, v69
	v_mul_f32_e32 v81, v81, v73
	v_add_f32_e32 v136, 1.0, v136
	v_add_f32_e32 v137, 1.0, v137
	v_rcp_f32_e32 v136, v136
	v_rcp_f32_e32 v137, v137
	s_nop 0
	v_mul_f32_e32 v77, v77, v136
	v_mul_f32_e32 v81, v81, v137
	v_cvt_pk_bf16_f32 v77, v77, v81
	ds_write_b16 v188, v77 offset:432
	ds_write_b16_d16_hi v188, v77 offset:464
	v_mul_f32_e32 v82, v82, v244
	v_mul_f32_e32 v86, v86, v244
	v_mul_f32_e32 v90, v90, v244
	v_mul_f32_e32 v94, v94, v244
	v_mul_f32_e32 v136, 0xbfb8aa3b, v82
	v_mul_f32_e32 v137, 0xbfb8aa3b, v86
	v_exp_f32_e32 v136, v136
	v_exp_f32_e32 v137, v137
	v_mul_f32_e32 v90, v90, v82
	v_mul_f32_e32 v94, v94, v86
	v_add_f32_e32 v136, 1.0, v136
	v_add_f32_e32 v137, 1.0, v137
	v_rcp_f32_e32 v136, v136
	v_rcp_f32_e32 v137, v137
	s_nop 0
	v_mul_f32_e32 v90, v90, v136
	v_mul_f32_e32 v94, v94, v137
	v_cvt_pk_bf16_f32 v90, v90, v94
	ds_write_b16 v188, v90 offset:2304
	ds_write_b16_d16_hi v188, v90 offset:2336
	v_mul_f32_e32 v83, v83, v245
	v_mul_f32_e32 v87, v87, v245
	v_mul_f32_e32 v91, v91, v245
	v_mul_f32_e32 v95, v95, v245
	v_mul_f32_e32 v136, 0xbfb8aa3b, v83
	v_mul_f32_e32 v137, 0xbfb8aa3b, v87
	v_exp_f32_e32 v136, v136
	v_exp_f32_e32 v137, v137
	v_mul_f32_e32 v91, v91, v83
	v_mul_f32_e32 v95, v95, v87
	v_add_f32_e32 v136, 1.0, v136
	v_add_f32_e32 v137, 1.0, v137
	v_rcp_f32_e32 v136, v136
	v_rcp_f32_e32 v137, v137
	s_nop 0
	v_mul_f32_e32 v91, v91, v136
	v_mul_f32_e32 v95, v95, v137
	v_cvt_pk_bf16_f32 v91, v91, v95
	ds_write_b16 v188, v91 offset:2448
	ds_write_b16_d16_hi v188, v91 offset:2480
	v_mul_f32_e32 v84, v84, v246
	v_mul_f32_e32 v88, v88, v246
	v_mul_f32_e32 v92, v92, v246
	v_mul_f32_e32 v96, v96, v246
	v_mul_f32_e32 v136, 0xbfb8aa3b, v84
	v_mul_f32_e32 v137, 0xbfb8aa3b, v88
	v_exp_f32_e32 v136, v136
	v_exp_f32_e32 v137, v137
	v_mul_f32_e32 v92, v92, v84
	v_mul_f32_e32 v96, v96, v88
	v_add_f32_e32 v136, 1.0, v136
	v_add_f32_e32 v137, 1.0, v137
	v_rcp_f32_e32 v136, v136
	v_rcp_f32_e32 v137, v137
	s_nop 0
	v_mul_f32_e32 v92, v92, v136
	v_mul_f32_e32 v96, v96, v137
	v_cvt_pk_bf16_f32 v92, v92, v96
	ds_write_b16 v188, v92 offset:2592
	ds_write_b16_d16_hi v188, v92 offset:2624
	v_mul_f32_e32 v85, v85, v247
	v_mul_f32_e32 v89, v89, v247
	v_mul_f32_e32 v93, v93, v247
	v_mul_f32_e32 v97, v97, v247
	v_mul_f32_e32 v136, 0xbfb8aa3b, v85
	v_mul_f32_e32 v137, 0xbfb8aa3b, v89
	v_exp_f32_e32 v136, v136
	v_exp_f32_e32 v137, v137
	v_mul_f32_e32 v93, v93, v85
	v_mul_f32_e32 v97, v97, v89
	v_add_f32_e32 v136, 1.0, v136
	v_add_f32_e32 v137, 1.0, v137
	v_rcp_f32_e32 v136, v136
	v_rcp_f32_e32 v137, v137
	s_nop 0
	v_mul_f32_e32 v93, v93, v136
	v_mul_f32_e32 v97, v97, v137
	v_cvt_pk_bf16_f32 v93, v93, v97
	ds_write_b16 v188, v93 offset:2736
	ds_write_b16_d16_hi v188, v93 offset:2768
	v_mul_f32_e32 v98, v98, v248
	v_mul_f32_e32 v102, v102, v248
	v_mul_f32_e32 v106, v106, v248
	v_mul_f32_e32 v110, v110, v248
	v_mul_f32_e32 v136, 0xbfb8aa3b, v98
	v_mul_f32_e32 v137, 0xbfb8aa3b, v102
	v_exp_f32_e32 v136, v136
	v_exp_f32_e32 v137, v137
	v_mul_f32_e32 v106, v106, v98
	v_mul_f32_e32 v110, v110, v102
	v_add_f32_e32 v136, 1.0, v136
	v_add_f32_e32 v137, 1.0, v137
	v_rcp_f32_e32 v136, v136
	v_rcp_f32_e32 v137, v137
	s_nop 0
	v_mul_f32_e32 v106, v106, v136
	v_mul_f32_e32 v110, v110, v137
	v_cvt_pk_bf16_f32 v106, v106, v110
	ds_write_b16 v188, v106 offset:4608
	ds_write_b16_d16_hi v188, v106 offset:4640
	v_mul_f32_e32 v99, v99, v249
	v_mul_f32_e32 v103, v103, v249
	v_mul_f32_e32 v107, v107, v249
	v_mul_f32_e32 v111, v111, v249
	v_mul_f32_e32 v136, 0xbfb8aa3b, v99
	v_mul_f32_e32 v137, 0xbfb8aa3b, v103
	v_exp_f32_e32 v136, v136
	v_exp_f32_e32 v137, v137
	v_mul_f32_e32 v107, v107, v99
	v_mul_f32_e32 v111, v111, v103
	v_add_f32_e32 v136, 1.0, v136
	v_add_f32_e32 v137, 1.0, v137
	v_rcp_f32_e32 v136, v136
	v_rcp_f32_e32 v137, v137
	s_nop 0
	v_mul_f32_e32 v107, v107, v136
	v_mul_f32_e32 v111, v111, v137
	v_cvt_pk_bf16_f32 v107, v107, v111
	ds_write_b16 v188, v107 offset:4752
	ds_write_b16_d16_hi v188, v107 offset:4784
	v_mul_f32_e32 v100, v100, v250
	v_mul_f32_e32 v104, v104, v250
	v_mul_f32_e32 v108, v108, v250
	v_mul_f32_e32 v112, v112, v250
	v_mul_f32_e32 v136, 0xbfb8aa3b, v100
	v_mul_f32_e32 v137, 0xbfb8aa3b, v104
	v_exp_f32_e32 v136, v136
	v_exp_f32_e32 v137, v137
	v_mul_f32_e32 v108, v108, v100
	v_mul_f32_e32 v112, v112, v104
	v_add_f32_e32 v136, 1.0, v136
	v_add_f32_e32 v137, 1.0, v137
	v_rcp_f32_e32 v136, v136
	v_rcp_f32_e32 v137, v137
	s_nop 0
	v_mul_f32_e32 v108, v108, v136
	v_mul_f32_e32 v112, v112, v137
	v_cvt_pk_bf16_f32 v108, v108, v112
	ds_write_b16 v188, v108 offset:4896
	ds_write_b16_d16_hi v188, v108 offset:4928
	v_mul_f32_e32 v101, v101, v251
	v_mul_f32_e32 v105, v105, v251
	v_mul_f32_e32 v109, v109, v251
	v_mul_f32_e32 v113, v113, v251
	v_mul_f32_e32 v136, 0xbfb8aa3b, v101
	v_mul_f32_e32 v137, 0xbfb8aa3b, v105
	v_exp_f32_e32 v136, v136
	v_exp_f32_e32 v137, v137
	v_mul_f32_e32 v109, v109, v101
	v_mul_f32_e32 v113, v113, v105
	v_add_f32_e32 v136, 1.0, v136
	v_add_f32_e32 v137, 1.0, v137
	v_rcp_f32_e32 v136, v136
	v_rcp_f32_e32 v137, v137
	s_nop 0
	v_mul_f32_e32 v109, v109, v136
	v_mul_f32_e32 v113, v113, v137
	v_cvt_pk_bf16_f32 v109, v109, v113
	ds_write_b16 v188, v109 offset:5040
	ds_write_b16_d16_hi v188, v109 offset:5072
	v_mul_f32_e32 v114, v114, v252
	v_mul_f32_e32 v118, v118, v252
	v_mul_f32_e32 v122, v122, v252
	v_mul_f32_e32 v126, v126, v252
	v_mul_f32_e32 v136, 0xbfb8aa3b, v114
	v_mul_f32_e32 v137, 0xbfb8aa3b, v118
	v_exp_f32_e32 v136, v136
	v_exp_f32_e32 v137, v137
	v_mul_f32_e32 v122, v122, v114
	v_mul_f32_e32 v126, v126, v118
	v_add_f32_e32 v136, 1.0, v136
	v_add_f32_e32 v137, 1.0, v137
	v_rcp_f32_e32 v136, v136
	v_rcp_f32_e32 v137, v137
	s_nop 0
	v_mul_f32_e32 v122, v122, v136
	v_mul_f32_e32 v126, v126, v137
	v_cvt_pk_bf16_f32 v122, v122, v126
	ds_write_b16 v188, v122 offset:6912
	ds_write_b16_d16_hi v188, v122 offset:6944
	v_mul_f32_e32 v115, v115, v253
	v_mul_f32_e32 v119, v119, v253
	v_mul_f32_e32 v123, v123, v253
	v_mul_f32_e32 v127, v127, v253
	v_mul_f32_e32 v136, 0xbfb8aa3b, v115
	v_mul_f32_e32 v137, 0xbfb8aa3b, v119
	v_exp_f32_e32 v136, v136
	v_exp_f32_e32 v137, v137
	v_mul_f32_e32 v123, v123, v115
	v_mul_f32_e32 v127, v127, v119
	v_add_f32_e32 v136, 1.0, v136
	v_add_f32_e32 v137, 1.0, v137
	v_rcp_f32_e32 v136, v136
	v_rcp_f32_e32 v137, v137
	s_nop 0
	v_mul_f32_e32 v123, v123, v136
	v_mul_f32_e32 v127, v127, v137
	v_cvt_pk_bf16_f32 v123, v123, v127
	ds_write_b16 v188, v123 offset:7056
	ds_write_b16_d16_hi v188, v123 offset:7088
	v_mul_f32_e32 v116, v116, v254
	v_mul_f32_e32 v120, v120, v254
	v_mul_f32_e32 v124, v124, v254
	v_mul_f32_e32 v128, v128, v254
	v_mul_f32_e32 v136, 0xbfb8aa3b, v116
	v_mul_f32_e32 v137, 0xbfb8aa3b, v120
	v_exp_f32_e32 v136, v136
	v_exp_f32_e32 v137, v137
	v_mul_f32_e32 v124, v124, v116
	v_mul_f32_e32 v128, v128, v120
	v_add_f32_e32 v136, 1.0, v136
	v_add_f32_e32 v137, 1.0, v137
	v_rcp_f32_e32 v136, v136
	v_rcp_f32_e32 v137, v137
	s_nop 0
	v_mul_f32_e32 v124, v124, v136
	v_mul_f32_e32 v128, v128, v137
	v_cvt_pk_bf16_f32 v124, v124, v128
	ds_write_b16 v188, v124 offset:7200
	ds_write_b16_d16_hi v188, v124 offset:7232
	v_mul_f32_e32 v117, v117, v255
	v_mul_f32_e32 v121, v121, v255
	v_mul_f32_e32 v125, v125, v255
	v_mul_f32_e32 v129, v129, v255
	v_mul_f32_e32 v136, 0xbfb8aa3b, v117
	v_mul_f32_e32 v137, 0xbfb8aa3b, v121
	v_exp_f32_e32 v136, v136
	v_exp_f32_e32 v137, v137
	v_mul_f32_e32 v125, v125, v117
	v_mul_f32_e32 v129, v129, v121
	v_add_f32_e32 v136, 1.0, v136
	v_add_f32_e32 v137, 1.0, v137
	v_rcp_f32_e32 v136, v136
	v_rcp_f32_e32 v137, v137
	s_nop 0
	v_mul_f32_e32 v125, v125, v136
	v_mul_f32_e32 v129, v129, v137
	v_cvt_pk_bf16_f32 v125, v125, v129
	ds_write_b16 v188, v125 offset:7344
	ds_write_b16_d16_hi v188, v125 offset:7376
	s_waitcnt lgkmcnt(0)
	s_barrier
	ds_read_b128 v[144:147], v189
	ds_read_b128 v[148:151], v189 offset:4608
	ds_read_b128 v[172:175], v189 offset:9216
	ds_read_b128 v[176:179], v189 offset:13824
	s_mov_b32 s56, s58
	s_mov_b32 s57, s59
	s_waitcnt lgkmcnt(3)
	global_store_dwordx4 v243, v[144:147], s[56:57]
	s_add_u32 s56, s56, 0x59000
	s_addc_u32 s57, s57, 0
	s_waitcnt lgkmcnt(2)
	global_store_dwordx4 v243, v[148:151], s[56:57]
	s_add_u32 s56, s56, 0x59000
	s_addc_u32 s57, s57, 0
	s_waitcnt lgkmcnt(1)
	global_store_dwordx4 v243, v[172:175], s[56:57]
	s_add_u32 s56, s56, 0x59000
	s_addc_u32 s57, s57, 0
	s_waitcnt lgkmcnt(0)
	global_store_dwordx4 v243, v[176:179], s[56:57]
	s_add_i32 s55, s55, 1
	s_cmp_lt_u32 s55, 5
	s_barrier
	s_cbranch_scc1 .Lgu2_tile
	s_add_i32 s21, s21, s72
	s_cmpk_lt_i32 s21, 0x200
	s_cbranch_scc1 .Lgu2_vloop

.LBB0_185:
	s_andn2_b64 vcc, exec, s[40:41]
	s_cbranch_vccnz .LBB0_225
	s_andn2_b64 vcc, exec, s[62:63]
	s_cbranch_vccnz .LBB0_225
	v_readlane_b32 s8, v209, 18
	v_readlane_b32 s20, v210, 55
	s_mov_b32 s21, s60
	s_branch .Lres1_entry
.Lres1_entry:
	s_mov_b32 s21, s60
	s_cmpk_gt_i32 s21, 0x1ff
	s_cbranch_scc1 .Lres1_done
.Lres1_tile:
	s_load_dwordx2 s[44:45], s[12:13], 0x178
	s_load_dwordx2 s[46:47], s[12:13], 0x118
	s_bfe_u32 s53, s21, 0x30006
	s_lshl_b32 s53, s53, 3
	s_and_b32 s56, s21, 7
	s_or_b32 s53, s53, s56
	s_lshl_b32 s53, s53, 7
	s_bfe_u32 s54, s21, 0x30003
	s_lshl_b32 s54, s54, 7
	v_lshrrev_b32_e32 v241, 6, v131
	v_and_b32_e32 v242, 63, v131
	s_nop 0
	v_readfirstlane_b32 s50, v241
	v_lshrrev_b32_e32 v241, 3, v242
	v_lshrrev_b32_e32 v243, 4, v242
	v_and_b32_e32 v244, 7, v242
	s_movk_i32 s56, 0x1080
	v_xor_b32_e32 v245, v244, v243
	v_lshlrev_b32_e32 v245, 4, v245
	v_mad_u32_u24 v228, v241, s56, v245
	v_or_b32_e32 v243, 4, v243
	v_xor_b32_e32 v245, v244, v243
	v_lshlrev_b32_e32 v245, 4, v245
	v_add_u32_e32 v241, 8, v241
	v_mad_u32_u24 v230, v241, s56, v245
	v_add_u32_e32 v229, 0x42000, v228
	v_add_u32_e32 v231, 0x42000, v230
	v_and_b32_e32 v241, 15, v242
	v_lshrrev_b32_e32 v243, 4, v242
	v_bfe_u32 v244, v242, 1, 3
	v_xor_b32_e32 v244, v243, v244
	v_lshlrev_b32_e32 v244, 4, v244
	v_lshl_or_b32 v232, v241, 7, v244
	v_xor_b32_e32 v233, 64, v232
	s_lshr_b32 s56, s50, 1
	s_and_b32 s57, s50, 1
	s_mul_i32 s0, s56, 64*528
	s_lshl_b32 s52, s57, 8
	s_add_i32 s0, s0, s52
	s_add_i32 s0, s0, 16
	v_mul_u32_u24_e32 v243, 4*528, v243
	v_lshl_add_u32 v243, v241, 2, v243
	v_add_u32_e32 v238, s0, v243
	s_add_i32 s22, s56, 0
	s_lshl_b32 s22, s22, 13
	s_add_i32 s22, s22, 16
	s_add_i32 s28, s57, 2
	s_lshl_b32 s28, s28, 13
	s_add_i32 s28, s28, 16
	s_add_i32 s40, s57, 4
	s_lshl_b32 s40, s40, 13
	s_add_i32 s40, s40, 16
	s_add_i32 s23, s56, 6
	s_lshl_b32 s23, s23, 13
	s_add_i32 s23, s23, 16
	s_add_i32 s29, s57, 8
	s_cmp_ge_u32 s29, 9
	s_cselect_b32 s0, 9, 0
	s_sub_i32 s29, s29, s0
	s_lshl_b32 s29, s29, 13
	s_add_i32 s29, s29, 16
	s_add_i32 s41, s57, 1
	s_lshl_b32 s41, s41, 13
	s_add_i32 s41, s41, 16
	s_add_i32 s24, s56, 3
	s_lshl_b32 s24, s24, 13
	s_add_i32 s24, s24, 16
	s_add_i32 s30, s57, 5
	s_lshl_b32 s30, s30, 13
	s_add_i32 s30, s30, 16
	s_add_i32 s42, s57, 7
	s_lshl_b32 s42, s42, 13
	s_add_i32 s42, s42, 16
	s_lshl_b32 s56, s50, 4
	s_add_i32 s57, s53, s56
	s_add_i32 s56, s54, s56
	s_mul_i32 s57, s57, 0x1080
	s_mul_i32 s56, s56, 0x1080
	s_waitcnt lgkmcnt(0)
	s_add_u32 s44, s44, s57
	s_addc_u32 s45, s45, 0
	s_add_u32 s46, s46, s56
	s_addc_u32 s47, s47, 0
	s_add_u32 s48, s46, 0x420000
	s_addc_u32 s49, s47, 0
	s_lshl_b32 s51, s50, 11
	s_add_i32 s51, s51, 16
	v_mov_b32_e32 v2, 0
	v_mov_b32_e32 v3, 0
	v_mov_b32_e32 v4, 0
	v_mov_b32_e32 v5, 0
	v_mov_b32_e32 v6, 0
	v_mov_b32_e32 v7, 0
	v_mov_b32_e32 v8, 0
	v_mov_b32_e32 v9, 0
	v_mov_b32_e32 v10, 0
	v_mov_b32_e32 v11, 0
	v_mov_b32_e32 v12, 0
	v_mov_b32_e32 v13, 0
	v_mov_b32_e32 v14, 0
	v_mov_b32_e32 v15, 0
	v_mov_b32_e32 v16, 0
	v_mov_b32_e32 v17, 0
	v_mov_b32_e32 v18, 0
	v_mov_b32_e32 v19, 0
	v_mov_b32_e32 v20, 0
	v_mov_b32_e32 v21, 0
	v_mov_b32_e32 v22, 0
	v_mov_b32_e32 v23, 0
	v_mov_b32_e32 v24, 0
	v_mov_b32_e32 v25, 0
	v_mov_b32_e32 v26, 0
	v_mov_b32_e32 v27, 0
	v_mov_b32_e32 v28, 0
	v_mov_b32_e32 v29, 0
	v_mov_b32_e32 v30, 0
	v_mov_b32_e32 v31, 0
	v_mov_b32_e32 v32, 0
	v_mov_b32_e32 v33, 0
	v_mov_b32_e32 v34, 0
	v_mov_b32_e32 v35, 0
	v_mov_b32_e32 v36, 0
	v_mov_b32_e32 v37, 0
	v_mov_b32_e32 v38, 0
	v_mov_b32_e32 v39, 0
	v_mov_b32_e32 v40, 0
	v_mov_b32_e32 v41, 0
	v_mov_b32_e32 v42, 0
	v_mov_b32_e32 v43, 0
	v_mov_b32_e32 v44, 0
	v_mov_b32_e32 v45, 0
	v_mov_b32_e32 v46, 0
	v_mov_b32_e32 v47, 0
	v_mov_b32_e32 v48, 0
	v_mov_b32_e32 v49, 0
	v_mov_b32_e32 v50, 0
	v_mov_b32_e32 v51, 0
	v_mov_b32_e32 v52, 0
	v_mov_b32_e32 v53, 0
	v_mov_b32_e32 v54, 0
	v_mov_b32_e32 v55, 0
	v_mov_b32_e32 v56, 0
	v_mov_b32_e32 v57, 0
	v_mov_b32_e32 v58, 0
	v_mov_b32_e32 v59, 0
	v_mov_b32_e32 v60, 0
	v_mov_b32_e32 v61, 0
	v_mov_b32_e32 v62, 0
	v_mov_b32_e32 v63, 0
	v_mov_b32_e32 v64, 0
	v_mov_b32_e32 v65, 0
	v_mov_b32_e32 v66, 0
	v_mov_b32_e32 v67, 0
	v_mov_b32_e32 v68, 0
	v_mov_b32_e32 v69, 0
	v_mov_b32_e32 v70, 0
	v_mov_b32_e32 v71, 0
	v_mov_b32_e32 v72, 0
	v_mov_b32_e32 v73, 0
	v_mov_b32_e32 v74, 0
	v_mov_b32_e32 v75, 0
	v_mov_b32_e32 v76, 0
	v_mov_b32_e32 v77, 0
	v_mov_b32_e32 v78, 0
	v_mov_b32_e32 v79, 0
	v_mov_b32_e32 v80, 0
	v_mov_b32_e32 v81, 0
	v_mov_b32_e32 v82, 0
	v_mov_b32_e32 v83, 0
	v_mov_b32_e32 v84, 0
	v_mov_b32_e32 v85, 0
	v_mov_b32_e32 v86, 0
	v_mov_b32_e32 v87, 0
	v_mov_b32_e32 v88, 0
	v_mov_b32_e32 v89, 0
	v_mov_b32_e32 v90, 0
	v_mov_b32_e32 v91, 0
	v_mov_b32_e32 v92, 0
	v_mov_b32_e32 v93, 0
	v_mov_b32_e32 v94, 0
	v_mov_b32_e32 v95, 0
	v_mov_b32_e32 v96, 0
	v_mov_b32_e32 v97, 0
	v_mov_b32_e32 v98, 0
	v_mov_b32_e32 v99, 0
	v_mov_b32_e32 v100, 0
	v_mov_b32_e32 v101, 0
	v_mov_b32_e32 v102, 0
	v_mov_b32_e32 v103, 0
	v_mov_b32_e32 v104, 0
	v_mov_b32_e32 v105, 0
	v_mov_b32_e32 v106, 0
	v_mov_b32_e32 v107, 0
	v_mov_b32_e32 v108, 0
	v_mov_b32_e32 v109, 0
	v_mov_b32_e32 v110, 0
	v_mov_b32_e32 v111, 0
	v_mov_b32_e32 v112, 0
	v_mov_b32_e32 v113, 0
	v_mov_b32_e32 v114, 0
	v_mov_b32_e32 v115, 0
	v_mov_b32_e32 v116, 0
	v_mov_b32_e32 v117, 0
	v_mov_b32_e32 v118, 0
	v_mov_b32_e32 v119, 0
	v_mov_b32_e32 v120, 0
	v_mov_b32_e32 v121, 0
	v_mov_b32_e32 v122, 0
	v_mov_b32_e32 v123, 0
	v_mov_b32_e32 v124, 0
	v_mov_b32_e32 v125, 0
	v_mov_b32_e32 v126, 0
	v_mov_b32_e32 v127, 0
	v_mov_b32_e32 v128, 0
	v_mov_b32_e32 v129, 0
	s_barrier
	s_mov_b32 m0, s51
	s_nop 0
	global_load_lds_dwordx4 v228, s[44:45]
	s_add_i32 m0, s51, 0x400
	s_nop 0
	global_load_lds_dwordx4 v230, s[44:45]
	s_add_i32 m0, s51, 0x2000
	s_nop 0
	global_load_lds_dwordx4 v229, s[44:45]
	s_add_i32 m0, s51, 0x2400
	s_nop 0
	global_load_lds_dwordx4 v231, s[44:45]
	s_add_i32 m0, s51, 0x4000
	s_nop 0
	global_load_lds_dwordx4 v228, s[46:47]
	s_add_i32 m0, s51, 0x4400
	s_nop 0
	global_load_lds_dwordx4 v230, s[46:47]
	s_add_i32 m0, s51, 0x6000
	s_nop 0
	global_load_lds_dwordx4 v229, s[46:47]
	s_add_i32 m0, s51, 0x6400
	s_nop 0
	global_load_lds_dwordx4 v231, s[46:47]
	s_add_i32 m0, s51, 0x8000
	s_nop 0
	global_load_lds_dwordx4 v228, s[48:49]
	s_add_i32 m0, s51, 0x8400
	s_nop 0
	global_load_lds_dwordx4 v230, s[48:49]
	s_add_i32 m0, s51, 0xa000
	s_nop 0
	global_load_lds_dwordx4 v229, s[48:49]
	s_add_i32 m0, s51, 0xa400
	s_nop 0
	global_load_lds_dwordx4 v231, s[48:49]
	v_add_u32_e32 v228, 0x80, v228
	v_add_u32_e32 v229, 0x80, v229
	v_add_u32_e32 v230, 0x80, v230
	v_add_u32_e32 v231, 0x80, v231
	s_waitcnt vmcnt(4)
	s_barrier
	s_mov_b32 s52, 0
.Lres1_loop:
	v_add_u32_e32 v234, s22, v232
	v_add_u32_e32 v236, s28, v232
	v_add_u32_e32 v235, s22, v233
	v_add_u32_e32 v237, s28, v233
	ds_read_b128 v[136:139], v234
	ds_read_b128 v[140:143], v234 offset:2048
	ds_read_b128 v[144:147], v234 offset:4096
	ds_read_b128 v[148:151], v234 offset:6144
	ds_read_b128 v[188:191], v236
	ds_read_b128 v[196:199], v236 offset:2048
	ds_read_b128 v[200:203], v236 offset:4096
	ds_read_b128 v[204:207], v236 offset:6144
	ds_read_b128 v[172:175], v235
	ds_read_b128 v[176:179], v235 offset:2048
	ds_read_b128 v[180:183], v235 offset:4096
	ds_read_b128 v[184:187], v235 offset:6144
	ds_read_b128 v[212:215], v237
	ds_read_b128 v[216:219], v237 offset:2048
	ds_read_b128 v[220:223], v237 offset:4096
	ds_read_b128 v[224:227], v237 offset:6144
	s_add_i32 m0, s51, 0xc000
	s_nop 0
	global_load_lds_dwordx4 v228, s[44:45]
	s_add_i32 m0, s51, 0xc400
	s_nop 0
	global_load_lds_dwordx4 v230, s[44:45]
	s_add_i32 m0, s51, 0xe000
	s_nop 0
	global_load_lds_dwordx4 v229, s[44:45]
	s_add_i32 m0, s51, 0xe400
	s_nop 0
	global_load_lds_dwordx4 v231, s[44:45]
	s_add_i32 m0, s51, 0x10000
	s_nop 0
	global_load_lds_dwordx4 v228, s[46:47]
	s_add_i32 m0, s51, 0x10400
	s_nop 0
	global_load_lds_dwordx4 v230, s[46:47]
	s_waitcnt lgkmcnt(8)
	v_mfma_f32_16x16x32_bf16 v[2:5], v[136:139], v[188:191], v[2:5]
	v_mfma_f32_16x16x32_bf16 v[6:9], v[136:139], v[196:199], v[6:9]
	v_mfma_f32_16x16x32_bf16 v[10:13], v[136:139], v[200:203], v[10:13]
	v_mfma_f32_16x16x32_bf16 v[14:17], v[136:139], v[204:207], v[14:17]
	v_mfma_f32_16x16x32_bf16 v[18:21], v[140:143], v[188:191], v[18:21]
	v_mfma_f32_16x16x32_bf16 v[22:25], v[140:143], v[196:199], v[22:25]
	v_mfma_f32_16x16x32_bf16 v[26:29], v[140:143], v[200:203], v[26:29]
	v_mfma_f32_16x16x32_bf16 v[30:33], v[140:143], v[204:207], v[30:33]
	v_mfma_f32_16x16x32_bf16 v[34:37], v[144:147], v[188:191], v[34:37]
	v_mfma_f32_16x16x32_bf16 v[38:41], v[144:147], v[196:199], v[38:41]
	v_mfma_f32_16x16x32_bf16 v[42:45], v[144:147], v[200:203], v[42:45]
	v_mfma_f32_16x16x32_bf16 v[46:49], v[144:147], v[204:207], v[46:49]
	v_mfma_f32_16x16x32_bf16 v[50:53], v[148:151], v[188:191], v[50:53]
	v_mfma_f32_16x16x32_bf16 v[54:57], v[148:151], v[196:199], v[54:57]
	v_mfma_f32_16x16x32_bf16 v[58:61], v[148:151], v[200:203], v[58:61]
	v_mfma_f32_16x16x32_bf16 v[62:65], v[148:151], v[204:207], v[62:65]
	s_waitcnt lgkmcnt(0)
	v_mfma_f32_16x16x32_bf16 v[2:5], v[172:175], v[212:215], v[2:5]
	v_mfma_f32_16x16x32_bf16 v[6:9], v[172:175], v[216:219], v[6:9]
	v_mfma_f32_16x16x32_bf16 v[10:13], v[172:175], v[220:223], v[10:13]
	v_mfma_f32_16x16x32_bf16 v[14:17], v[172:175], v[224:227], v[14:17]
	v_mfma_f32_16x16x32_bf16 v[18:21], v[176:179], v[212:215], v[18:21]
	v_mfma_f32_16x16x32_bf16 v[22:25], v[176:179], v[216:219], v[22:25]
	v_mfma_f32_16x16x32_bf16 v[26:29], v[176:179], v[220:223], v[26:29]
	v_mfma_f32_16x16x32_bf16 v[30:33], v[176:179], v[224:227], v[30:33]
	v_mfma_f32_16x16x32_bf16 v[34:37], v[180:183], v[212:215], v[34:37]
	v_mfma_f32_16x16x32_bf16 v[38:41], v[180:183], v[216:219], v[38:41]
	v_mfma_f32_16x16x32_bf16 v[42:45], v[180:183], v[220:223], v[42:45]
	v_mfma_f32_16x16x32_bf16 v[46:49], v[180:183], v[224:227], v[46:49]
	v_mfma_f32_16x16x32_bf16 v[50:53], v[184:187], v[212:215], v[50:53]
	v_mfma_f32_16x16x32_bf16 v[54:57], v[184:187], v[216:219], v[54:57]
	v_mfma_f32_16x16x32_bf16 v[58:61], v[184:187], v[220:223], v[58:61]
	v_mfma_f32_16x16x32_bf16 v[62:65], v[184:187], v[224:227], v[62:65]
	s_waitcnt vmcnt(6)
	s_barrier
	v_add_u32_e32 v236, s40, v232
	v_add_u32_e32 v237, s40, v233
	ds_read_b128 v[188:191], v236
	ds_read_b128 v[196:199], v236 offset:2048
	ds_read_b128 v[200:203], v236 offset:4096
	ds_read_b128 v[204:207], v236 offset:6144
	ds_read_b128 v[212:215], v237
	ds_read_b128 v[216:219], v237 offset:2048
	ds_read_b128 v[220:223], v237 offset:4096
	ds_read_b128 v[224:227], v237 offset:6144
	s_mov_b32 m0, s51
	s_nop 0
	global_load_lds_dwordx4 v229, s[46:47]
	s_add_i32 m0, s51, 0x400
	s_nop 0
	global_load_lds_dwordx4 v231, s[46:47]
	s_add_i32 m0, s51, 0x2000
	s_nop 0
	global_load_lds_dwordx4 v228, s[48:49]
	s_add_i32 m0, s51, 0x2400
	s_nop 0
	global_load_lds_dwordx4 v230, s[48:49]
	s_add_i32 m0, s51, 0x4000
	s_nop 0
	global_load_lds_dwordx4 v229, s[48:49]
	s_add_i32 m0, s51, 0x4400
	s_nop 0
	global_load_lds_dwordx4 v231, s[48:49]
	s_waitcnt lgkmcnt(4)
	v_mfma_f32_16x16x32_bf16 v[66:69], v[136:139], v[188:191], v[66:69]
	v_mfma_f32_16x16x32_bf16 v[70:73], v[136:139], v[196:199], v[70:73]
	v_mfma_f32_16x16x32_bf16 v[74:77], v[136:139], v[200:203], v[74:77]
	v_mfma_f32_16x16x32_bf16 v[78:81], v[136:139], v[204:207], v[78:81]
	v_mfma_f32_16x16x32_bf16 v[82:85], v[140:143], v[188:191], v[82:85]
	v_mfma_f32_16x16x32_bf16 v[86:89], v[140:143], v[196:199], v[86:89]
	v_mfma_f32_16x16x32_bf16 v[90:93], v[140:143], v[200:203], v[90:93]
	v_mfma_f32_16x16x32_bf16 v[94:97], v[140:143], v[204:207], v[94:97]
	v_mfma_f32_16x16x32_bf16 v[98:101], v[144:147], v[188:191], v[98:101]
	v_mfma_f32_16x16x32_bf16 v[102:105], v[144:147], v[196:199], v[102:105]
	v_mfma_f32_16x16x32_bf16 v[106:109], v[144:147], v[200:203], v[106:109]
	v_mfma_f32_16x16x32_bf16 v[110:113], v[144:147], v[204:207], v[110:113]
	v_mfma_f32_16x16x32_bf16 v[114:117], v[148:151], v[188:191], v[114:117]
	v_mfma_f32_16x16x32_bf16 v[118:121], v[148:151], v[196:199], v[118:121]
	v_mfma_f32_16x16x32_bf16 v[122:125], v[148:151], v[200:203], v[122:125]
	v_mfma_f32_16x16x32_bf16 v[126:129], v[148:151], v[204:207], v[126:129]
	s_waitcnt lgkmcnt(0)
	v_mfma_f32_16x16x32_bf16 v[66:69], v[172:175], v[212:215], v[66:69]
	v_mfma_f32_16x16x32_bf16 v[70:73], v[172:175], v[216:219], v[70:73]
	v_mfma_f32_16x16x32_bf16 v[74:77], v[172:175], v[220:223], v[74:77]
	v_mfma_f32_16x16x32_bf16 v[78:81], v[172:175], v[224:227], v[78:81]
	v_mfma_f32_16x16x32_bf16 v[82:85], v[176:179], v[212:215], v[82:85]
	v_mfma_f32_16x16x32_bf16 v[86:89], v[176:179], v[216:219], v[86:89]
	v_mfma_f32_16x16x32_bf16 v[90:93], v[176:179], v[220:223], v[90:93]
	v_mfma_f32_16x16x32_bf16 v[94:97], v[176:179], v[224:227], v[94:97]
	v_mfma_f32_16x16x32_bf16 v[98:101], v[180:183], v[212:215], v[98:101]
	v_mfma_f32_16x16x32_bf16 v[102:105], v[180:183], v[216:219], v[102:105]
	v_mfma_f32_16x16x32_bf16 v[106:109], v[180:183], v[220:223], v[106:109]
	v_mfma_f32_16x16x32_bf16 v[110:113], v[180:183], v[224:227], v[110:113]
	v_mfma_f32_16x16x32_bf16 v[114:117], v[184:187], v[212:215], v[114:117]
	v_mfma_f32_16x16x32_bf16 v[118:121], v[184:187], v[216:219], v[118:121]
	v_mfma_f32_16x16x32_bf16 v[122:125], v[184:187], v[220:223], v[122:125]
	v_mfma_f32_16x16x32_bf16 v[126:129], v[184:187], v[224:227], v[126:129]
	v_add_u32_e32 v228, 0x80, v228
	v_add_u32_e32 v229, 0x80, v229
	v_add_u32_e32 v230, 0x80, v230
	v_add_u32_e32 v231, 0x80, v231
	s_waitcnt vmcnt(4)
	s_barrier
	v_add_u32_e32 v234, s23, v232
	v_add_u32_e32 v236, s29, v232
	v_add_u32_e32 v235, s23, v233
	v_add_u32_e32 v237, s29, v233
	ds_read_b128 v[136:139], v234
	ds_read_b128 v[140:143], v234 offset:2048
	ds_read_b128 v[144:147], v234 offset:4096
	ds_read_b128 v[148:151], v234 offset:6144
	ds_read_b128 v[188:191], v236
	ds_read_b128 v[196:199], v236 offset:2048
	ds_read_b128 v[200:203], v236 offset:4096
	ds_read_b128 v[204:207], v236 offset:6144
	ds_read_b128 v[172:175], v235
	ds_read_b128 v[176:179], v235 offset:2048
	ds_read_b128 v[180:183], v235 offset:4096
	ds_read_b128 v[184:187], v235 offset:6144
	ds_read_b128 v[212:215], v237
	ds_read_b128 v[216:219], v237 offset:2048
	ds_read_b128 v[220:223], v237 offset:4096
	ds_read_b128 v[224:227], v237 offset:6144
	s_add_i32 m0, s51, 0x6000
	s_nop 0
	global_load_lds_dwordx4 v228, s[44:45]
	s_add_i32 m0, s51, 0x6400
	s_nop 0
	global_load_lds_dwordx4 v230, s[44:45]
	s_add_i32 m0, s51, 0x8000
	s_nop 0
	global_load_lds_dwordx4 v229, s[44:45]
	s_add_i32 m0, s51, 0x8400
	s_nop 0
	global_load_lds_dwordx4 v231, s[44:45]
	s_add_i32 m0, s51, 0xa000
	s_nop 0
	global_load_lds_dwordx4 v228, s[46:47]
	s_add_i32 m0, s51, 0xa400
	s_nop 0
	global_load_lds_dwordx4 v230, s[46:47]
	s_waitcnt lgkmcnt(8)
	v_mfma_f32_16x16x32_bf16 v[2:5], v[136:139], v[188:191], v[2:5]
	v_mfma_f32_16x16x32_bf16 v[6:9], v[136:139], v[196:199], v[6:9]
	v_mfma_f32_16x16x32_bf16 v[10:13], v[136:139], v[200:203], v[10:13]
	v_mfma_f32_16x16x32_bf16 v[14:17], v[136:139], v[204:207], v[14:17]
	v_mfma_f32_16x16x32_bf16 v[18:21], v[140:143], v[188:191], v[18:21]
	v_mfma_f32_16x16x32_bf16 v[22:25], v[140:143], v[196:199], v[22:25]
	v_mfma_f32_16x16x32_bf16 v[26:29], v[140:143], v[200:203], v[26:29]
	v_mfma_f32_16x16x32_bf16 v[30:33], v[140:143], v[204:207], v[30:33]
	v_mfma_f32_16x16x32_bf16 v[34:37], v[144:147], v[188:191], v[34:37]
	v_mfma_f32_16x16x32_bf16 v[38:41], v[144:147], v[196:199], v[38:41]
	v_mfma_f32_16x16x32_bf16 v[42:45], v[144:147], v[200:203], v[42:45]
	v_mfma_f32_16x16x32_bf16 v[46:49], v[144:147], v[204:207], v[46:49]
	v_mfma_f32_16x16x32_bf16 v[50:53], v[148:151], v[188:191], v[50:53]
	v_mfma_f32_16x16x32_bf16 v[54:57], v[148:151], v[196:199], v[54:57]
	v_mfma_f32_16x16x32_bf16 v[58:61], v[148:151], v[200:203], v[58:61]
	v_mfma_f32_16x16x32_bf16 v[62:65], v[148:151], v[204:207], v[62:65]
	s_waitcnt lgkmcnt(0)
	v_mfma_f32_16x16x32_bf16 v[2:5], v[172:175], v[212:215], v[2:5]
	v_mfma_f32_16x16x32_bf16 v[6:9], v[172:175], v[216:219], v[6:9]
	v_mfma_f32_16x16x32_bf16 v[10:13], v[172:175], v[220:223], v[10:13]
	v_mfma_f32_16x16x32_bf16 v[14:17], v[172:175], v[224:227], v[14:17]
	v_mfma_f32_16x16x32_bf16 v[18:21], v[176:179], v[212:215], v[18:21]
	v_mfma_f32_16x16x32_bf16 v[22:25], v[176:179], v[216:219], v[22:25]
	v_mfma_f32_16x16x32_bf16 v[26:29], v[176:179], v[220:223], v[26:29]
	v_mfma_f32_16x16x32_bf16 v[30:33], v[176:179], v[224:227], v[30:33]
	v_mfma_f32_16x16x32_bf16 v[34:37], v[180:183], v[212:215], v[34:37]
	v_mfma_f32_16x16x32_bf16 v[38:41], v[180:183], v[216:219], v[38:41]
	v_mfma_f32_16x16x32_bf16 v[42:45], v[180:183], v[220:223], v[42:45]
	v_mfma_f32_16x16x32_bf16 v[46:49], v[180:183], v[224:227], v[46:49]
	v_mfma_f32_16x16x32_bf16 v[50:53], v[184:187], v[212:215], v[50:53]
	v_mfma_f32_16x16x32_bf16 v[54:57], v[184:187], v[216:219], v[54:57]
	v_mfma_f32_16x16x32_bf16 v[58:61], v[184:187], v[220:223], v[58:61]
	v_mfma_f32_16x16x32_bf16 v[62:65], v[184:187], v[224:227], v[62:65]
	s_waitcnt vmcnt(6)
	s_barrier
	v_add_u32_e32 v236, s41, v232
	v_add_u32_e32 v237, s41, v233
	ds_read_b128 v[188:191], v236
	ds_read_b128 v[196:199], v236 offset:2048
	ds_read_b128 v[200:203], v236 offset:4096
	ds_read_b128 v[204:207], v236 offset:6144
	ds_read_b128 v[212:215], v237
	ds_read_b128 v[216:219], v237 offset:2048
	ds_read_b128 v[220:223], v237 offset:4096
	ds_read_b128 v[224:227], v237 offset:6144
	s_add_i32 m0, s51, 0xc000
	s_nop 0
	global_load_lds_dwordx4 v229, s[46:47]
	s_add_i32 m0, s51, 0xc400
	s_nop 0
	global_load_lds_dwordx4 v231, s[46:47]
	s_add_i32 m0, s51, 0xe000
	s_nop 0
	global_load_lds_dwordx4 v228, s[48:49]
	s_add_i32 m0, s51, 0xe400
	s_nop 0
	global_load_lds_dwordx4 v230, s[48:49]
	s_add_i32 m0, s51, 0x10000
	s_nop 0
	global_load_lds_dwordx4 v229, s[48:49]
	s_add_i32 m0, s51, 0x10400
	s_nop 0
	global_load_lds_dwordx4 v231, s[48:49]
	s_waitcnt lgkmcnt(4)
	v_mfma_f32_16x16x32_bf16 v[66:69], v[136:139], v[188:191], v[66:69]
	v_mfma_f32_16x16x32_bf16 v[70:73], v[136:139], v[196:199], v[70:73]
	v_mfma_f32_16x16x32_bf16 v[74:77], v[136:139], v[200:203], v[74:77]
	v_mfma_f32_16x16x32_bf16 v[78:81], v[136:139], v[204:207], v[78:81]
	v_mfma_f32_16x16x32_bf16 v[82:85], v[140:143], v[188:191], v[82:85]
	v_mfma_f32_16x16x32_bf16 v[86:89], v[140:143], v[196:199], v[86:89]
	v_mfma_f32_16x16x32_bf16 v[90:93], v[140:143], v[200:203], v[90:93]
	v_mfma_f32_16x16x32_bf16 v[94:97], v[140:143], v[204:207], v[94:97]
	v_mfma_f32_16x16x32_bf16 v[98:101], v[144:147], v[188:191], v[98:101]
	v_mfma_f32_16x16x32_bf16 v[102:105], v[144:147], v[196:199], v[102:105]
	v_mfma_f32_16x16x32_bf16 v[106:109], v[144:147], v[200:203], v[106:109]
	v_mfma_f32_16x16x32_bf16 v[110:113], v[144:147], v[204:207], v[110:113]
	v_mfma_f32_16x16x32_bf16 v[114:117], v[148:151], v[188:191], v[114:117]
	v_mfma_f32_16x16x32_bf16 v[118:121], v[148:151], v[196:199], v[118:121]
	v_mfma_f32_16x16x32_bf16 v[122:125], v[148:151], v[200:203], v[122:125]
	v_mfma_f32_16x16x32_bf16 v[126:129], v[148:151], v[204:207], v[126:129]
	s_waitcnt lgkmcnt(0)
	v_mfma_f32_16x16x32_bf16 v[66:69], v[172:175], v[212:215], v[66:69]
	v_mfma_f32_16x16x32_bf16 v[70:73], v[172:175], v[216:219], v[70:73]
	v_mfma_f32_16x16x32_bf16 v[74:77], v[172:175], v[220:223], v[74:77]
	v_mfma_f32_16x16x32_bf16 v[78:81], v[172:175], v[224:227], v[78:81]
	v_mfma_f32_16x16x32_bf16 v[82:85], v[176:179], v[212:215], v[82:85]
	v_mfma_f32_16x16x32_bf16 v[86:89], v[176:179], v[216:219], v[86:89]
	v_mfma_f32_16x16x32_bf16 v[90:93], v[176:179], v[220:223], v[90:93]
	v_mfma_f32_16x16x32_bf16 v[94:97], v[176:179], v[224:227], v[94:97]
	v_mfma_f32_16x16x32_bf16 v[98:101], v[180:183], v[212:215], v[98:101]
	v_mfma_f32_16x16x32_bf16 v[102:105], v[180:183], v[216:219], v[102:105]
	v_mfma_f32_16x16x32_bf16 v[106:109], v[180:183], v[220:223], v[106:109]
	v_mfma_f32_16x16x32_bf16 v[110:113], v[180:183], v[224:227], v[110:113]
	v_mfma_f32_16x16x32_bf16 v[114:117], v[184:187], v[212:215], v[114:117]
	v_mfma_f32_16x16x32_bf16 v[118:121], v[184:187], v[216:219], v[118:121]
	v_mfma_f32_16x16x32_bf16 v[122:125], v[184:187], v[220:223], v[122:125]
	v_mfma_f32_16x16x32_bf16 v[126:129], v[184:187], v[224:227], v[126:129]
	v_add_u32_e32 v228, 0x80, v228
	v_add_u32_e32 v229, 0x80, v229
	v_add_u32_e32 v230, 0x80, v230
	v_add_u32_e32 v231, 0x80, v231
	s_waitcnt vmcnt(4)
	s_barrier
	v_add_u32_e32 v234, s24, v232
	v_add_u32_e32 v236, s30, v232
	v_add_u32_e32 v235, s24, v233
	v_add_u32_e32 v237, s30, v233
	ds_read_b128 v[136:139], v234
	ds_read_b128 v[140:143], v234 offset:2048
	ds_read_b128 v[144:147], v234 offset:4096
	ds_read_b128 v[148:151], v234 offset:6144
	ds_read_b128 v[188:191], v236
	ds_read_b128 v[196:199], v236 offset:2048
	ds_read_b128 v[200:203], v236 offset:4096
	ds_read_b128 v[204:207], v236 offset:6144
	ds_read_b128 v[172:175], v235
	ds_read_b128 v[176:179], v235 offset:2048
	ds_read_b128 v[180:183], v235 offset:4096
	ds_read_b128 v[184:187], v235 offset:6144
	ds_read_b128 v[212:215], v237
	ds_read_b128 v[216:219], v237 offset:2048
	ds_read_b128 v[220:223], v237 offset:4096
	ds_read_b128 v[224:227], v237 offset:6144
	s_mov_b32 m0, s51
	s_nop 0
	global_load_lds_dwordx4 v228, s[44:45]
	s_add_i32 m0, s51, 0x400
	s_nop 0
	global_load_lds_dwordx4 v230, s[44:45]
	s_add_i32 m0, s51, 0x2000
	s_nop 0
	global_load_lds_dwordx4 v229, s[44:45]
	s_add_i32 m0, s51, 0x2400
	s_nop 0
	global_load_lds_dwordx4 v231, s[44:45]
	s_add_i32 m0, s51, 0x4000
	s_nop 0
	global_load_lds_dwordx4 v228, s[46:47]
	s_add_i32 m0, s51, 0x4400
	s_nop 0
	global_load_lds_dwordx4 v230, s[46:47]
	s_waitcnt lgkmcnt(8)
	v_mfma_f32_16x16x32_bf16 v[2:5], v[136:139], v[188:191], v[2:5]
	v_mfma_f32_16x16x32_bf16 v[6:9], v[136:139], v[196:199], v[6:9]
	v_mfma_f32_16x16x32_bf16 v[10:13], v[136:139], v[200:203], v[10:13]
	v_mfma_f32_16x16x32_bf16 v[14:17], v[136:139], v[204:207], v[14:17]
	v_mfma_f32_16x16x32_bf16 v[18:21], v[140:143], v[188:191], v[18:21]
	v_mfma_f32_16x16x32_bf16 v[22:25], v[140:143], v[196:199], v[22:25]
	v_mfma_f32_16x16x32_bf16 v[26:29], v[140:143], v[200:203], v[26:29]
	v_mfma_f32_16x16x32_bf16 v[30:33], v[140:143], v[204:207], v[30:33]
	v_mfma_f32_16x16x32_bf16 v[34:37], v[144:147], v[188:191], v[34:37]
	v_mfma_f32_16x16x32_bf16 v[38:41], v[144:147], v[196:199], v[38:41]
	v_mfma_f32_16x16x32_bf16 v[42:45], v[144:147], v[200:203], v[42:45]
	v_mfma_f32_16x16x32_bf16 v[46:49], v[144:147], v[204:207], v[46:49]
	v_mfma_f32_16x16x32_bf16 v[50:53], v[148:151], v[188:191], v[50:53]
	v_mfma_f32_16x16x32_bf16 v[54:57], v[148:151], v[196:199], v[54:57]
	v_mfma_f32_16x16x32_bf16 v[58:61], v[148:151], v[200:203], v[58:61]
	v_mfma_f32_16x16x32_bf16 v[62:65], v[148:151], v[204:207], v[62:65]
	s_waitcnt lgkmcnt(0)
	v_mfma_f32_16x16x32_bf16 v[2:5], v[172:175], v[212:215], v[2:5]
	v_mfma_f32_16x16x32_bf16 v[6:9], v[172:175], v[216:219], v[6:9]
	v_mfma_f32_16x16x32_bf16 v[10:13], v[172:175], v[220:223], v[10:13]
	v_mfma_f32_16x16x32_bf16 v[14:17], v[172:175], v[224:227], v[14:17]
	v_mfma_f32_16x16x32_bf16 v[18:21], v[176:179], v[212:215], v[18:21]
	v_mfma_f32_16x16x32_bf16 v[22:25], v[176:179], v[216:219], v[22:25]
	v_mfma_f32_16x16x32_bf16 v[26:29], v[176:179], v[220:223], v[26:29]
	v_mfma_f32_16x16x32_bf16 v[30:33], v[176:179], v[224:227], v[30:33]
	v_mfma_f32_16x16x32_bf16 v[34:37], v[180:183], v[212:215], v[34:37]
	v_mfma_f32_16x16x32_bf16 v[38:41], v[180:183], v[216:219], v[38:41]
	v_mfma_f32_16x16x32_bf16 v[42:45], v[180:183], v[220:223], v[42:45]
	v_mfma_f32_16x16x32_bf16 v[46:49], v[180:183], v[224:227], v[46:49]
	v_mfma_f32_16x16x32_bf16 v[50:53], v[184:187], v[212:215], v[50:53]
	v_mfma_f32_16x16x32_bf16 v[54:57], v[184:187], v[216:219], v[54:57]
	v_mfma_f32_16x16x32_bf16 v[58:61], v[184:187], v[220:223], v[58:61]
	v_mfma_f32_16x16x32_bf16 v[62:65], v[184:187], v[224:227], v[62:65]
	s_waitcnt vmcnt(6)
	s_barrier
	v_add_u32_e32 v236, s42, v232
	v_add_u32_e32 v237, s42, v233
	ds_read_b128 v[188:191], v236
	ds_read_b128 v[196:199], v236 offset:2048
	ds_read_b128 v[200:203], v236 offset:4096
	ds_read_b128 v[204:207], v236 offset:6144
	ds_read_b128 v[212:215], v237
	ds_read_b128 v[216:219], v237 offset:2048
	ds_read_b128 v[220:223], v237 offset:4096
	ds_read_b128 v[224:227], v237 offset:6144
	s_add_i32 m0, s51, 0x6000
	s_nop 0
	global_load_lds_dwordx4 v229, s[46:47]
	s_add_i32 m0, s51, 0x6400
	s_nop 0
	global_load_lds_dwordx4 v231, s[46:47]
	s_add_i32 m0, s51, 0x8000
	s_nop 0
	global_load_lds_dwordx4 v228, s[48:49]
	s_add_i32 m0, s51, 0x8400
	s_nop 0
	global_load_lds_dwordx4 v230, s[48:49]
	s_add_i32 m0, s51, 0xa000
	s_nop 0
	global_load_lds_dwordx4 v229, s[48:49]
	s_add_i32 m0, s51, 0xa400
	s_nop 0
	global_load_lds_dwordx4 v231, s[48:49]
	s_waitcnt lgkmcnt(4)
	v_mfma_f32_16x16x32_bf16 v[66:69], v[136:139], v[188:191], v[66:69]
	v_mfma_f32_16x16x32_bf16 v[70:73], v[136:139], v[196:199], v[70:73]
	v_mfma_f32_16x16x32_bf16 v[74:77], v[136:139], v[200:203], v[74:77]
	v_mfma_f32_16x16x32_bf16 v[78:81], v[136:139], v[204:207], v[78:81]
	v_mfma_f32_16x16x32_bf16 v[82:85], v[140:143], v[188:191], v[82:85]
	v_mfma_f32_16x16x32_bf16 v[86:89], v[140:143], v[196:199], v[86:89]
	v_mfma_f32_16x16x32_bf16 v[90:93], v[140:143], v[200:203], v[90:93]
	v_mfma_f32_16x16x32_bf16 v[94:97], v[140:143], v[204:207], v[94:97]
	v_mfma_f32_16x16x32_bf16 v[98:101], v[144:147], v[188:191], v[98:101]
	v_mfma_f32_16x16x32_bf16 v[102:105], v[144:147], v[196:199], v[102:105]
	v_mfma_f32_16x16x32_bf16 v[106:109], v[144:147], v[200:203], v[106:109]
	v_mfma_f32_16x16x32_bf16 v[110:113], v[144:147], v[204:207], v[110:113]
	v_mfma_f32_16x16x32_bf16 v[114:117], v[148:151], v[188:191], v[114:117]
	v_mfma_f32_16x16x32_bf16 v[118:121], v[148:151], v[196:199], v[118:121]
	v_mfma_f32_16x16x32_bf16 v[122:125], v[148:151], v[200:203], v[122:125]
	v_mfma_f32_16x16x32_bf16 v[126:129], v[148:151], v[204:207], v[126:129]
	s_waitcnt lgkmcnt(0)
	v_mfma_f32_16x16x32_bf16 v[66:69], v[172:175], v[212:215], v[66:69]
	v_mfma_f32_16x16x32_bf16 v[70:73], v[172:175], v[216:219], v[70:73]
	v_mfma_f32_16x16x32_bf16 v[74:77], v[172:175], v[220:223], v[74:77]
	v_mfma_f32_16x16x32_bf16 v[78:81], v[172:175], v[224:227], v[78:81]
	v_mfma_f32_16x16x32_bf16 v[82:85], v[176:179], v[212:215], v[82:85]
	v_mfma_f32_16x16x32_bf16 v[86:89], v[176:179], v[216:219], v[86:89]
	v_mfma_f32_16x16x32_bf16 v[90:93], v[176:179], v[220:223], v[90:93]
	v_mfma_f32_16x16x32_bf16 v[94:97], v[176:179], v[224:227], v[94:97]
	v_mfma_f32_16x16x32_bf16 v[98:101], v[180:183], v[212:215], v[98:101]
	v_mfma_f32_16x16x32_bf16 v[102:105], v[180:183], v[216:219], v[102:105]
	v_mfma_f32_16x16x32_bf16 v[106:109], v[180:183], v[220:223], v[106:109]
	v_mfma_f32_16x16x32_bf16 v[110:113], v[180:183], v[224:227], v[110:113]
	v_mfma_f32_16x16x32_bf16 v[114:117], v[184:187], v[212:215], v[114:117]
	v_mfma_f32_16x16x32_bf16 v[118:121], v[184:187], v[216:219], v[118:121]
	v_mfma_f32_16x16x32_bf16 v[122:125], v[184:187], v[220:223], v[122:125]
	v_mfma_f32_16x16x32_bf16 v[126:129], v[184:187], v[224:227], v[126:129]
	v_add_u32_e32 v228, 0x80, v228
	v_add_u32_e32 v229, 0x80, v229
	v_add_u32_e32 v230, 0x80, v230
	v_add_u32_e32 v231, 0x80, v231
	s_waitcnt vmcnt(4)
	s_barrier
	s_add_i32 s52, s52, 1
	s_cmp_lt_u32 s52, 10
	s_cbranch_scc1 .Lres1_loop
	v_add_u32_e32 v234, s22, v232
	v_add_u32_e32 v236, s28, v232
	v_add_u32_e32 v235, s22, v233
	v_add_u32_e32 v237, s28, v233
	ds_read_b128 v[136:139], v234
	ds_read_b128 v[140:143], v234 offset:2048
	ds_read_b128 v[144:147], v234 offset:4096
	ds_read_b128 v[148:151], v234 offset:6144
	ds_read_b128 v[188:191], v236
	ds_read_b128 v[196:199], v236 offset:2048
	ds_read_b128 v[200:203], v236 offset:4096
	ds_read_b128 v[204:207], v236 offset:6144
	ds_read_b128 v[172:175], v235
	ds_read_b128 v[176:179], v235 offset:2048
	ds_read_b128 v[180:183], v235 offset:4096
	ds_read_b128 v[184:187], v235 offset:6144
	ds_read_b128 v[212:215], v237
	ds_read_b128 v[216:219], v237 offset:2048
	ds_read_b128 v[220:223], v237 offset:4096
	ds_read_b128 v[224:227], v237 offset:6144
	s_add_i32 m0, s51, 0xc000
	s_nop 0
	global_load_lds_dwordx4 v228, s[44:45]
	s_add_i32 m0, s51, 0xc400
	s_nop 0
	global_load_lds_dwordx4 v230, s[44:45]
	s_add_i32 m0, s51, 0xe000
	s_nop 0
	global_load_lds_dwordx4 v229, s[44:45]
	s_add_i32 m0, s51, 0xe400
	s_nop 0
	global_load_lds_dwordx4 v231, s[44:45]
	s_add_i32 m0, s51, 0x10000
	s_nop 0
	global_load_lds_dwordx4 v228, s[46:47]
	s_add_i32 m0, s51, 0x10400
	s_nop 0
	global_load_lds_dwordx4 v230, s[46:47]
	s_waitcnt lgkmcnt(8)
	v_mfma_f32_16x16x32_bf16 v[2:5], v[136:139], v[188:191], v[2:5]
	v_mfma_f32_16x16x32_bf16 v[6:9], v[136:139], v[196:199], v[6:9]
	v_mfma_f32_16x16x32_bf16 v[10:13], v[136:139], v[200:203], v[10:13]
	v_mfma_f32_16x16x32_bf16 v[14:17], v[136:139], v[204:207], v[14:17]
	v_mfma_f32_16x16x32_bf16 v[18:21], v[140:143], v[188:191], v[18:21]
	v_mfma_f32_16x16x32_bf16 v[22:25], v[140:143], v[196:199], v[22:25]
	v_mfma_f32_16x16x32_bf16 v[26:29], v[140:143], v[200:203], v[26:29]
	v_mfma_f32_16x16x32_bf16 v[30:33], v[140:143], v[204:207], v[30:33]
	v_mfma_f32_16x16x32_bf16 v[34:37], v[144:147], v[188:191], v[34:37]
	v_mfma_f32_16x16x32_bf16 v[38:41], v[144:147], v[196:199], v[38:41]
	v_mfma_f32_16x16x32_bf16 v[42:45], v[144:147], v[200:203], v[42:45]
	v_mfma_f32_16x16x32_bf16 v[46:49], v[144:147], v[204:207], v[46:49]
	v_mfma_f32_16x16x32_bf16 v[50:53], v[148:151], v[188:191], v[50:53]
	v_mfma_f32_16x16x32_bf16 v[54:57], v[148:151], v[196:199], v[54:57]
	v_mfma_f32_16x16x32_bf16 v[58:61], v[148:151], v[200:203], v[58:61]
	v_mfma_f32_16x16x32_bf16 v[62:65], v[148:151], v[204:207], v[62:65]
	s_waitcnt lgkmcnt(0)
	v_mfma_f32_16x16x32_bf16 v[2:5], v[172:175], v[212:215], v[2:5]
	v_mfma_f32_16x16x32_bf16 v[6:9], v[172:175], v[216:219], v[6:9]
	v_mfma_f32_16x16x32_bf16 v[10:13], v[172:175], v[220:223], v[10:13]
	v_mfma_f32_16x16x32_bf16 v[14:17], v[172:175], v[224:227], v[14:17]
	v_mfma_f32_16x16x32_bf16 v[18:21], v[176:179], v[212:215], v[18:21]
	v_mfma_f32_16x16x32_bf16 v[22:25], v[176:179], v[216:219], v[22:25]
	v_mfma_f32_16x16x32_bf16 v[26:29], v[176:179], v[220:223], v[26:29]
	v_mfma_f32_16x16x32_bf16 v[30:33], v[176:179], v[224:227], v[30:33]
	v_mfma_f32_16x16x32_bf16 v[34:37], v[180:183], v[212:215], v[34:37]
	v_mfma_f32_16x16x32_bf16 v[38:41], v[180:183], v[216:219], v[38:41]
	v_mfma_f32_16x16x32_bf16 v[42:45], v[180:183], v[220:223], v[42:45]
	v_mfma_f32_16x16x32_bf16 v[46:49], v[180:183], v[224:227], v[46:49]
	v_mfma_f32_16x16x32_bf16 v[50:53], v[184:187], v[212:215], v[50:53]
	v_mfma_f32_16x16x32_bf16 v[54:57], v[184:187], v[216:219], v[54:57]
	v_mfma_f32_16x16x32_bf16 v[58:61], v[184:187], v[220:223], v[58:61]
	v_mfma_f32_16x16x32_bf16 v[62:65], v[184:187], v[224:227], v[62:65]
	s_waitcnt vmcnt(6)
	s_barrier
	v_add_u32_e32 v236, s40, v232
	v_add_u32_e32 v237, s40, v233
	ds_read_b128 v[188:191], v236
	ds_read_b128 v[196:199], v236 offset:2048
	ds_read_b128 v[200:203], v236 offset:4096
	ds_read_b128 v[204:207], v236 offset:6144
	ds_read_b128 v[212:215], v237
	ds_read_b128 v[216:219], v237 offset:2048
	ds_read_b128 v[220:223], v237 offset:4096
	ds_read_b128 v[224:227], v237 offset:6144
	s_mov_b32 m0, s51
	s_nop 0
	global_load_lds_dwordx4 v229, s[46:47]
	s_add_i32 m0, s51, 0x400
	s_nop 0
	global_load_lds_dwordx4 v231, s[46:47]
	s_add_i32 m0, s51, 0x2000
	s_nop 0
	global_load_lds_dwordx4 v228, s[48:49]
	s_add_i32 m0, s51, 0x2400
	s_nop 0
	global_load_lds_dwordx4 v230, s[48:49]
	s_add_i32 m0, s51, 0x4000
	s_nop 0
	global_load_lds_dwordx4 v229, s[48:49]
	s_add_i32 m0, s51, 0x4400
	s_nop 0
	global_load_lds_dwordx4 v231, s[48:49]
	s_waitcnt lgkmcnt(4)
	v_mfma_f32_16x16x32_bf16 v[66:69], v[136:139], v[188:191], v[66:69]
	v_mfma_f32_16x16x32_bf16 v[70:73], v[136:139], v[196:199], v[70:73]
	v_mfma_f32_16x16x32_bf16 v[74:77], v[136:139], v[200:203], v[74:77]
	v_mfma_f32_16x16x32_bf16 v[78:81], v[136:139], v[204:207], v[78:81]
	v_mfma_f32_16x16x32_bf16 v[82:85], v[140:143], v[188:191], v[82:85]
	v_mfma_f32_16x16x32_bf16 v[86:89], v[140:143], v[196:199], v[86:89]
	v_mfma_f32_16x16x32_bf16 v[90:93], v[140:143], v[200:203], v[90:93]
	v_mfma_f32_16x16x32_bf16 v[94:97], v[140:143], v[204:207], v[94:97]
	v_mfma_f32_16x16x32_bf16 v[98:101], v[144:147], v[188:191], v[98:101]
	v_mfma_f32_16x16x32_bf16 v[102:105], v[144:147], v[196:199], v[102:105]
	v_mfma_f32_16x16x32_bf16 v[106:109], v[144:147], v[200:203], v[106:109]
	v_mfma_f32_16x16x32_bf16 v[110:113], v[144:147], v[204:207], v[110:113]
	v_mfma_f32_16x16x32_bf16 v[114:117], v[148:151], v[188:191], v[114:117]
	v_mfma_f32_16x16x32_bf16 v[118:121], v[148:151], v[196:199], v[118:121]
	v_mfma_f32_16x16x32_bf16 v[122:125], v[148:151], v[200:203], v[122:125]
	v_mfma_f32_16x16x32_bf16 v[126:129], v[148:151], v[204:207], v[126:129]
	s_waitcnt lgkmcnt(0)
	v_mfma_f32_16x16x32_bf16 v[66:69], v[172:175], v[212:215], v[66:69]
	v_mfma_f32_16x16x32_bf16 v[70:73], v[172:175], v[216:219], v[70:73]
	v_mfma_f32_16x16x32_bf16 v[74:77], v[172:175], v[220:223], v[74:77]
	v_mfma_f32_16x16x32_bf16 v[78:81], v[172:175], v[224:227], v[78:81]
	v_mfma_f32_16x16x32_bf16 v[82:85], v[176:179], v[212:215], v[82:85]
	v_mfma_f32_16x16x32_bf16 v[86:89], v[176:179], v[216:219], v[86:89]
	v_mfma_f32_16x16x32_bf16 v[90:93], v[176:179], v[220:223], v[90:93]
	v_mfma_f32_16x16x32_bf16 v[94:97], v[176:179], v[224:227], v[94:97]
	v_mfma_f32_16x16x32_bf16 v[98:101], v[180:183], v[212:215], v[98:101]
	v_mfma_f32_16x16x32_bf16 v[102:105], v[180:183], v[216:219], v[102:105]
	v_mfma_f32_16x16x32_bf16 v[106:109], v[180:183], v[220:223], v[106:109]
	v_mfma_f32_16x16x32_bf16 v[110:113], v[180:183], v[224:227], v[110:113]
	v_mfma_f32_16x16x32_bf16 v[114:117], v[184:187], v[212:215], v[114:117]
	v_mfma_f32_16x16x32_bf16 v[118:121], v[184:187], v[216:219], v[118:121]
	v_mfma_f32_16x16x32_bf16 v[122:125], v[184:187], v[220:223], v[122:125]
	v_mfma_f32_16x16x32_bf16 v[126:129], v[184:187], v[224:227], v[126:129]
	v_add_u32_e32 v228, 0x80, v228
	v_add_u32_e32 v229, 0x80, v229
	v_add_u32_e32 v230, 0x80, v230
	v_add_u32_e32 v231, 0x80, v231
	s_waitcnt vmcnt(4)
	s_barrier
	v_add_u32_e32 v234, s23, v232
	v_add_u32_e32 v236, s29, v232
	v_add_u32_e32 v235, s23, v233
	v_add_u32_e32 v237, s29, v233
	ds_read_b128 v[136:139], v234
	ds_read_b128 v[140:143], v234 offset:2048
	ds_read_b128 v[144:147], v234 offset:4096
	ds_read_b128 v[148:151], v234 offset:6144
	ds_read_b128 v[188:191], v236
	ds_read_b128 v[196:199], v236 offset:2048
	ds_read_b128 v[200:203], v236 offset:4096
	ds_read_b128 v[204:207], v236 offset:6144
	ds_read_b128 v[172:175], v235
	ds_read_b128 v[176:179], v235 offset:2048
	ds_read_b128 v[180:183], v235 offset:4096
	ds_read_b128 v[184:187], v235 offset:6144
	ds_read_b128 v[212:215], v237
	ds_read_b128 v[216:219], v237 offset:2048
	ds_read_b128 v[220:223], v237 offset:4096
	ds_read_b128 v[224:227], v237 offset:6144
	s_waitcnt lgkmcnt(8)
	v_mfma_f32_16x16x32_bf16 v[2:5], v[136:139], v[188:191], v[2:5]
	v_mfma_f32_16x16x32_bf16 v[6:9], v[136:139], v[196:199], v[6:9]
	v_mfma_f32_16x16x32_bf16 v[10:13], v[136:139], v[200:203], v[10:13]
	v_mfma_f32_16x16x32_bf16 v[14:17], v[136:139], v[204:207], v[14:17]
	v_mfma_f32_16x16x32_bf16 v[18:21], v[140:143], v[188:191], v[18:21]
	v_mfma_f32_16x16x32_bf16 v[22:25], v[140:143], v[196:199], v[22:25]
	v_mfma_f32_16x16x32_bf16 v[26:29], v[140:143], v[200:203], v[26:29]
	v_mfma_f32_16x16x32_bf16 v[30:33], v[140:143], v[204:207], v[30:33]
	v_mfma_f32_16x16x32_bf16 v[34:37], v[144:147], v[188:191], v[34:37]
	v_mfma_f32_16x16x32_bf16 v[38:41], v[144:147], v[196:199], v[38:41]
	v_mfma_f32_16x16x32_bf16 v[42:45], v[144:147], v[200:203], v[42:45]
	v_mfma_f32_16x16x32_bf16 v[46:49], v[144:147], v[204:207], v[46:49]
	v_mfma_f32_16x16x32_bf16 v[50:53], v[148:151], v[188:191], v[50:53]
	v_mfma_f32_16x16x32_bf16 v[54:57], v[148:151], v[196:199], v[54:57]
	v_mfma_f32_16x16x32_bf16 v[58:61], v[148:151], v[200:203], v[58:61]
	v_mfma_f32_16x16x32_bf16 v[62:65], v[148:151], v[204:207], v[62:65]
	s_waitcnt lgkmcnt(0)
	v_mfma_f32_16x16x32_bf16 v[2:5], v[172:175], v[212:215], v[2:5]
	v_mfma_f32_16x16x32_bf16 v[6:9], v[172:175], v[216:219], v[6:9]
	v_mfma_f32_16x16x32_bf16 v[10:13], v[172:175], v[220:223], v[10:13]
	v_mfma_f32_16x16x32_bf16 v[14:17], v[172:175], v[224:227], v[14:17]
	v_mfma_f32_16x16x32_bf16 v[18:21], v[176:179], v[212:215], v[18:21]
	v_mfma_f32_16x16x32_bf16 v[22:25], v[176:179], v[216:219], v[22:25]
	v_mfma_f32_16x16x32_bf16 v[26:29], v[176:179], v[220:223], v[26:29]
	v_mfma_f32_16x16x32_bf16 v[30:33], v[176:179], v[224:227], v[30:33]
	v_mfma_f32_16x16x32_bf16 v[34:37], v[180:183], v[212:215], v[34:37]
	v_mfma_f32_16x16x32_bf16 v[38:41], v[180:183], v[216:219], v[38:41]
	v_mfma_f32_16x16x32_bf16 v[42:45], v[180:183], v[220:223], v[42:45]
	v_mfma_f32_16x16x32_bf16 v[46:49], v[180:183], v[224:227], v[46:49]
	v_mfma_f32_16x16x32_bf16 v[50:53], v[184:187], v[212:215], v[50:53]
	v_mfma_f32_16x16x32_bf16 v[54:57], v[184:187], v[216:219], v[54:57]
	v_mfma_f32_16x16x32_bf16 v[58:61], v[184:187], v[220:223], v[58:61]
	v_mfma_f32_16x16x32_bf16 v[62:65], v[184:187], v[224:227], v[62:65]
	s_waitcnt vmcnt(0)
	s_barrier
	v_add_u32_e32 v236, s41, v232
	v_add_u32_e32 v237, s41, v233
	ds_read_b128 v[188:191], v236
	ds_read_b128 v[196:199], v236 offset:2048
	ds_read_b128 v[200:203], v236 offset:4096
	ds_read_b128 v[204:207], v236 offset:6144
	ds_read_b128 v[212:215], v237
	ds_read_b128 v[216:219], v237 offset:2048
	ds_read_b128 v[220:223], v237 offset:4096
	ds_read_b128 v[224:227], v237 offset:6144
	s_waitcnt lgkmcnt(4)
	v_mfma_f32_16x16x32_bf16 v[66:69], v[136:139], v[188:191], v[66:69]
	v_mfma_f32_16x16x32_bf16 v[70:73], v[136:139], v[196:199], v[70:73]
	v_mfma_f32_16x16x32_bf16 v[74:77], v[136:139], v[200:203], v[74:77]
	v_mfma_f32_16x16x32_bf16 v[78:81], v[136:139], v[204:207], v[78:81]
	v_mfma_f32_16x16x32_bf16 v[82:85], v[140:143], v[188:191], v[82:85]
	v_mfma_f32_16x16x32_bf16 v[86:89], v[140:143], v[196:199], v[86:89]
	v_mfma_f32_16x16x32_bf16 v[90:93], v[140:143], v[200:203], v[90:93]
	v_mfma_f32_16x16x32_bf16 v[94:97], v[140:143], v[204:207], v[94:97]
	v_mfma_f32_16x16x32_bf16 v[98:101], v[144:147], v[188:191], v[98:101]
	v_mfma_f32_16x16x32_bf16 v[102:105], v[144:147], v[196:199], v[102:105]
	v_mfma_f32_16x16x32_bf16 v[106:109], v[144:147], v[200:203], v[106:109]
	v_mfma_f32_16x16x32_bf16 v[110:113], v[144:147], v[204:207], v[110:113]
	v_mfma_f32_16x16x32_bf16 v[114:117], v[148:151], v[188:191], v[114:117]
	v_mfma_f32_16x16x32_bf16 v[118:121], v[148:151], v[196:199], v[118:121]
	v_mfma_f32_16x16x32_bf16 v[122:125], v[148:151], v[200:203], v[122:125]
	v_mfma_f32_16x16x32_bf16 v[126:129], v[148:151], v[204:207], v[126:129]
	s_waitcnt lgkmcnt(0)
	v_mfma_f32_16x16x32_bf16 v[66:69], v[172:175], v[212:215], v[66:69]
	v_mfma_f32_16x16x32_bf16 v[70:73], v[172:175], v[216:219], v[70:73]
	v_mfma_f32_16x16x32_bf16 v[74:77], v[172:175], v[220:223], v[74:77]
	v_mfma_f32_16x16x32_bf16 v[78:81], v[172:175], v[224:227], v[78:81]
	v_mfma_f32_16x16x32_bf16 v[82:85], v[176:179], v[212:215], v[82:85]
	v_mfma_f32_16x16x32_bf16 v[86:89], v[176:179], v[216:219], v[86:89]
	v_mfma_f32_16x16x32_bf16 v[90:93], v[176:179], v[220:223], v[90:93]
	v_mfma_f32_16x16x32_bf16 v[94:97], v[176:179], v[224:227], v[94:97]
	v_mfma_f32_16x16x32_bf16 v[98:101], v[180:183], v[212:215], v[98:101]
	v_mfma_f32_16x16x32_bf16 v[102:105], v[180:183], v[216:219], v[102:105]
	v_mfma_f32_16x16x32_bf16 v[106:109], v[180:183], v[220:223], v[106:109]
	v_mfma_f32_16x16x32_bf16 v[110:113], v[180:183], v[224:227], v[110:113]
	v_mfma_f32_16x16x32_bf16 v[114:117], v[184:187], v[212:215], v[114:117]
	v_mfma_f32_16x16x32_bf16 v[118:121], v[184:187], v[216:219], v[118:121]
	v_mfma_f32_16x16x32_bf16 v[122:125], v[184:187], v[220:223], v[122:125]
	v_mfma_f32_16x16x32_bf16 v[126:129], v[184:187], v[224:227], v[126:129]
	s_nop 7
	s_barrier
	s_load_dwordx2 s[44:45], s[12:13], 0x0
	s_load_dwordx2 s[58:59], s[12:13], 0x100
	s_load_dwordx2 s[46:47], s[12:13], 0x160
	s_load_dwordx2 s[48:49], s[12:13], 0x1c8
	v_lshrrev_b32_e32 v241, 5, v131
	v_and_b32_e32 v242, 31, v131
	v_lshlrev_b32_e32 v243, 4, v242
	s_movk_i32 s56, 0x210
	v_mad_u32_u24 v239, v241, s56, v243
	v_add_u32_e32 v239, 16, v239
	v_lshlrev_b32_e32 v240, 13, v241
	v_or_b32_e32 v240, v240, v243
	v_lshlrev_b32_e32 v244, 3, v242
	v_mad_u32_u24 v244, v241, s81, v244
	v_lshlrev_b32_e32 v245, 2, v241
	s_lshl_b32 s56, s53, 13
	s_lshl_b32 s57, s54, 2
	s_add_i32 s56, s56, s57
	s_mul_i32 s57, s53, s81
	s_lshl_b32 s0, s54, 1
	s_add_i32 s57, s57, s0
	s_lshl_b32 s0, s53, 2
	s_waitcnt lgkmcnt(0)
	s_add_u32 s44, s44, s56
	s_addc_u32 s45, s45, 0
	s_add_u32 s58, s58, s56
	s_addc_u32 s59, s59, 0
	s_add_u32 s46, s46, s57
	s_addc_u32 s47, s47, 0
	s_add_u32 s48, s48, s0
	s_addc_u32 s49, s49, 0
	s_mov_b32 s56, s44
	s_mov_b32 s57, s45
	global_load_dwordx4 v[136:139], v240, s[56:57]
	s_add_u32 s56, s56, 0x10000
	s_addc_u32 s57, s57, 0
	global_load_dwordx4 v[140:143], v240, s[56:57]
	s_add_u32 s56, s56, 0x10000
	s_addc_u32 s57, s57, 0
	global_load_dwordx4 v[144:147], v240, s[56:57]
	s_add_u32 s56, s56, 0x10000
	s_addc_u32 s57, s57, 0
	global_load_dwordx4 v[148:151], v240, s[56:57]
	s_add_u32 s56, s56, 0x10000
	s_addc_u32 s57, s57, 0
	global_load_dwordx4 v[172:175], v240, s[56:57]
	s_add_u32 s56, s56, 0x10000
	s_addc_u32 s57, s57, 0
	global_load_dwordx4 v[176:179], v240, s[56:57]
	s_add_u32 s56, s56, 0x10000
	s_addc_u32 s57, s57, 0
	global_load_dwordx4 v[180:183], v240, s[56:57]
	s_add_u32 s56, s56, 0x10000
	s_addc_u32 s57, s57, 0
	global_load_dwordx4 v[184:187], v240, s[56:57]
	s_add_u32 s56, s56, 0x10000
	s_addc_u32 s57, s57, 0
	global_load_dwordx4 v[188:191], v240, s[56:57]
	s_add_u32 s56, s56, 0x10000
	s_addc_u32 s57, s57, 0
	global_load_dwordx4 v[196:199], v240, s[56:57]
	s_add_u32 s56, s56, 0x10000
	s_addc_u32 s57, s57, 0
	global_load_dwordx4 v[200:203], v240, s[56:57]
	s_add_u32 s56, s56, 0x10000
	s_addc_u32 s57, s57, 0
	global_load_dwordx4 v[204:207], v240, s[56:57]
	s_add_u32 s56, s56, 0x10000
	s_addc_u32 s57, s57, 0
	global_load_dwordx4 v[212:215], v240, s[56:57]
	s_add_u32 s56, s56, 0x10000
	s_addc_u32 s57, s57, 0
	global_load_dwordx4 v[216:219], v240, s[56:57]
	s_add_u32 s56, s56, 0x10000
	s_addc_u32 s57, s57, 0
	global_load_dwordx4 v[220:223], v240, s[56:57]
	s_add_u32 s56, s56, 0x10000
	s_addc_u32 s57, s57, 0
	global_load_dwordx4 v[224:227], v240, s[56:57]
	ds_write_b32 v238, v2
	ds_write_b32 v238, v3 offset:528
	ds_write_b32 v238, v4 offset:1056
	ds_write_b32 v238, v5 offset:1584
	ds_write_b32 v238, v6 offset:64
	ds_write_b32 v238, v7 offset:592
	ds_write_b32 v238, v8 offset:1120
	ds_write_b32 v238, v9 offset:1648
	ds_write_b32 v238, v10 offset:128
	ds_write_b32 v238, v11 offset:656
	ds_write_b32 v238, v12 offset:1184
	ds_write_b32 v238, v13 offset:1712
	ds_write_b32 v238, v14 offset:192
	ds_write_b32 v238, v15 offset:720
	ds_write_b32 v238, v16 offset:1248
	ds_write_b32 v238, v17 offset:1776
	ds_write_b32 v238, v18 offset:8448
	ds_write_b32 v238, v19 offset:8976
	ds_write_b32 v238, v20 offset:9504
	ds_write_b32 v238, v21 offset:10032
	ds_write_b32 v238, v22 offset:8512
	ds_write_b32 v238, v23 offset:9040
	ds_write_b32 v238, v24 offset:9568
	ds_write_b32 v238, v25 offset:10096
	ds_write_b32 v238, v26 offset:8576
	ds_write_b32 v238, v27 offset:9104
	ds_write_b32 v238, v28 offset:9632
	ds_write_b32 v238, v29 offset:10160
	ds_write_b32 v238, v30 offset:8640
	ds_write_b32 v238, v31 offset:9168
	ds_write_b32 v238, v32 offset:9696
	ds_write_b32 v238, v33 offset:10224
	ds_write_b32 v238, v34 offset:16896
	ds_write_b32 v238, v35 offset:17424
	ds_write_b32 v238, v36 offset:17952
	ds_write_b32 v238, v37 offset:18480
	ds_write_b32 v238, v38 offset:16960
	ds_write_b32 v238, v39 offset:17488
	ds_write_b32 v238, v40 offset:18016
	ds_write_b32 v238, v41 offset:18544
	ds_write_b32 v238, v42 offset:17024
	ds_write_b32 v238, v43 offset:17552
	ds_write_b32 v238, v44 offset:18080
	ds_write_b32 v238, v45 offset:18608
	ds_write_b32 v238, v46 offset:17088
	ds_write_b32 v238, v47 offset:17616
	ds_write_b32 v238, v48 offset:18144
	ds_write_b32 v238, v49 offset:18672
	ds_write_b32 v238, v50 offset:25344
	ds_write_b32 v238, v51 offset:25872
	ds_write_b32 v238, v52 offset:26400
	ds_write_b32 v238, v53 offset:26928
	ds_write_b32 v238, v54 offset:25408
	ds_write_b32 v238, v55 offset:25936
	ds_write_b32 v238, v56 offset:26464
	ds_write_b32 v238, v57 offset:26992
	ds_write_b32 v238, v58 offset:25472
	ds_write_b32 v238, v59 offset:26000
	ds_write_b32 v238, v60 offset:26528
	ds_write_b32 v238, v61 offset:27056
	ds_write_b32 v238, v62 offset:25536
	ds_write_b32 v238, v63 offset:26064
	ds_write_b32 v238, v64 offset:26592
	ds_write_b32 v238, v65 offset:27120
	s_waitcnt lgkmcnt(0)
	s_barrier
	ds_read_b128 v[2:5], v239
	ds_read_b128 v[6:9], v239 offset:4224
	ds_read_b128 v[10:13], v239 offset:8448
	ds_read_b128 v[14:17], v239 offset:12672
	ds_read_b128 v[18:21], v239 offset:16896
	ds_read_b128 v[22:25], v239 offset:21120
	ds_read_b128 v[26:29], v239 offset:25344
	ds_read_b128 v[30:33], v239 offset:29568
	ds_read_b128 v[34:37], v239 offset:33792
	ds_read_b128 v[38:41], v239 offset:38016
	ds_read_b128 v[42:45], v239 offset:42240
	ds_read_b128 v[46:49], v239 offset:46464
	ds_read_b128 v[50:53], v239 offset:50688
	ds_read_b128 v[54:57], v239 offset:54912
	ds_read_b128 v[58:61], v239 offset:59136
	ds_read_b128 v[62:65], v239 offset:63360
	s_waitcnt vmcnt(15) lgkmcnt(15)
	v_pk_add_f32 v[2:3], v[2:3], v[136:137]
	v_pk_add_f32 v[4:5], v[4:5], v[138:139]
	v_cvt_pk_bf16_f32 v136, v2, v3
	v_cvt_pk_bf16_f32 v137, v4, v5
	v_mul_f32_e32 v138, v2, v2
	v_fmac_f32_e32 v138, v3, v3
	v_fmac_f32_e32 v138, v4, v4
	v_fmac_f32_e32 v138, v5, v5
	s_waitcnt vmcnt(14) lgkmcnt(14)
	v_pk_add_f32 v[6:7], v[6:7], v[140:141]
	v_pk_add_f32 v[8:9], v[8:9], v[142:143]
	v_cvt_pk_bf16_f32 v140, v6, v7
	v_cvt_pk_bf16_f32 v141, v8, v9
	v_mul_f32_e32 v142, v6, v6
	v_fmac_f32_e32 v142, v7, v7
	v_fmac_f32_e32 v142, v8, v8
	v_fmac_f32_e32 v142, v9, v9
	s_waitcnt vmcnt(13) lgkmcnt(13)
	v_pk_add_f32 v[10:11], v[10:11], v[144:145]
	v_pk_add_f32 v[12:13], v[12:13], v[146:147]
	v_cvt_pk_bf16_f32 v144, v10, v11
	v_cvt_pk_bf16_f32 v145, v12, v13
	v_mul_f32_e32 v146, v10, v10
	v_fmac_f32_e32 v146, v11, v11
	v_fmac_f32_e32 v146, v12, v12
	v_fmac_f32_e32 v146, v13, v13
	s_waitcnt vmcnt(12) lgkmcnt(12)
	v_pk_add_f32 v[14:15], v[14:15], v[148:149]
	v_pk_add_f32 v[16:17], v[16:17], v[150:151]
	v_cvt_pk_bf16_f32 v148, v14, v15
	v_cvt_pk_bf16_f32 v149, v16, v17
	v_mul_f32_e32 v150, v14, v14
	v_fmac_f32_e32 v150, v15, v15
	v_fmac_f32_e32 v150, v16, v16
	v_fmac_f32_e32 v150, v17, v17
	s_waitcnt vmcnt(11) lgkmcnt(11)
	v_pk_add_f32 v[18:19], v[18:19], v[172:173]
	v_pk_add_f32 v[20:21], v[20:21], v[174:175]
	v_cvt_pk_bf16_f32 v172, v18, v19
	v_cvt_pk_bf16_f32 v173, v20, v21
	v_mul_f32_e32 v174, v18, v18
	v_fmac_f32_e32 v174, v19, v19
	v_fmac_f32_e32 v174, v20, v20
	v_fmac_f32_e32 v174, v21, v21
	s_waitcnt vmcnt(10) lgkmcnt(10)
	v_pk_add_f32 v[22:23], v[22:23], v[176:177]
	v_pk_add_f32 v[24:25], v[24:25], v[178:179]
	v_cvt_pk_bf16_f32 v176, v22, v23
	v_cvt_pk_bf16_f32 v177, v24, v25
	v_mul_f32_e32 v178, v22, v22
	v_fmac_f32_e32 v178, v23, v23
	v_fmac_f32_e32 v178, v24, v24
	v_fmac_f32_e32 v178, v25, v25
	s_waitcnt vmcnt(9) lgkmcnt(9)
	v_pk_add_f32 v[26:27], v[26:27], v[180:181]
	v_pk_add_f32 v[28:29], v[28:29], v[182:183]
	v_cvt_pk_bf16_f32 v180, v26, v27
	v_cvt_pk_bf16_f32 v181, v28, v29
	v_mul_f32_e32 v182, v26, v26
	v_fmac_f32_e32 v182, v27, v27
	v_fmac_f32_e32 v182, v28, v28
	v_fmac_f32_e32 v182, v29, v29
	s_waitcnt vmcnt(8) lgkmcnt(8)
	v_pk_add_f32 v[30:31], v[30:31], v[184:185]
	v_pk_add_f32 v[32:33], v[32:33], v[186:187]
	v_cvt_pk_bf16_f32 v184, v30, v31
	v_cvt_pk_bf16_f32 v185, v32, v33
	v_mul_f32_e32 v186, v30, v30
	v_fmac_f32_e32 v186, v31, v31
	v_fmac_f32_e32 v186, v32, v32
	v_fmac_f32_e32 v186, v33, v33
	s_waitcnt vmcnt(7) lgkmcnt(7)
	v_pk_add_f32 v[34:35], v[34:35], v[188:189]
	v_pk_add_f32 v[36:37], v[36:37], v[190:191]
	v_cvt_pk_bf16_f32 v188, v34, v35
	v_cvt_pk_bf16_f32 v189, v36, v37
	v_mul_f32_e32 v190, v34, v34
	v_fmac_f32_e32 v190, v35, v35
	v_fmac_f32_e32 v190, v36, v36
	v_fmac_f32_e32 v190, v37, v37
	s_waitcnt vmcnt(6) lgkmcnt(6)
	v_pk_add_f32 v[38:39], v[38:39], v[196:197]
	v_pk_add_f32 v[40:41], v[40:41], v[198:199]
	v_cvt_pk_bf16_f32 v196, v38, v39
	v_cvt_pk_bf16_f32 v197, v40, v41
	v_mul_f32_e32 v198, v38, v38
	v_fmac_f32_e32 v198, v39, v39
	v_fmac_f32_e32 v198, v40, v40
	v_fmac_f32_e32 v198, v41, v41
	s_waitcnt vmcnt(5) lgkmcnt(5)
	v_pk_add_f32 v[42:43], v[42:43], v[200:201]
	v_pk_add_f32 v[44:45], v[44:45], v[202:203]
	v_cvt_pk_bf16_f32 v200, v42, v43
	v_cvt_pk_bf16_f32 v201, v44, v45
	v_mul_f32_e32 v202, v42, v42
	v_fmac_f32_e32 v202, v43, v43
	v_fmac_f32_e32 v202, v44, v44
	v_fmac_f32_e32 v202, v45, v45
	s_waitcnt vmcnt(4) lgkmcnt(4)
	v_pk_add_f32 v[46:47], v[46:47], v[204:205]
	v_pk_add_f32 v[48:49], v[48:49], v[206:207]
	v_cvt_pk_bf16_f32 v204, v46, v47
	v_cvt_pk_bf16_f32 v205, v48, v49
	v_mul_f32_e32 v206, v46, v46
	v_fmac_f32_e32 v206, v47, v47
	v_fmac_f32_e32 v206, v48, v48
	v_fmac_f32_e32 v206, v49, v49
	s_waitcnt vmcnt(3) lgkmcnt(3)
	v_pk_add_f32 v[50:51], v[50:51], v[212:213]
	v_pk_add_f32 v[52:53], v[52:53], v[214:215]
	v_cvt_pk_bf16_f32 v212, v50, v51
	v_cvt_pk_bf16_f32 v213, v52, v53
	v_mul_f32_e32 v214, v50, v50
	v_fmac_f32_e32 v214, v51, v51
	v_fmac_f32_e32 v214, v52, v52
	v_fmac_f32_e32 v214, v53, v53
	s_waitcnt vmcnt(2) lgkmcnt(2)
	v_pk_add_f32 v[54:55], v[54:55], v[216:217]
	v_pk_add_f32 v[56:57], v[56:57], v[218:219]
	v_cvt_pk_bf16_f32 v216, v54, v55
	v_cvt_pk_bf16_f32 v217, v56, v57
	v_mul_f32_e32 v218, v54, v54
	v_fmac_f32_e32 v218, v55, v55
	v_fmac_f32_e32 v218, v56, v56
	v_fmac_f32_e32 v218, v57, v57
	s_waitcnt vmcnt(1) lgkmcnt(1)
	v_pk_add_f32 v[58:59], v[58:59], v[220:221]
	v_pk_add_f32 v[60:61], v[60:61], v[222:223]
	v_cvt_pk_bf16_f32 v220, v58, v59
	v_cvt_pk_bf16_f32 v221, v60, v61
	v_mul_f32_e32 v222, v58, v58
	v_fmac_f32_e32 v222, v59, v59
	v_fmac_f32_e32 v222, v60, v60
	v_fmac_f32_e32 v222, v61, v61
	s_waitcnt vmcnt(0) lgkmcnt(0)
	v_pk_add_f32 v[62:63], v[62:63], v[224:225]
	v_pk_add_f32 v[64:65], v[64:65], v[226:227]
	v_cvt_pk_bf16_f32 v224, v62, v63
	v_cvt_pk_bf16_f32 v225, v64, v65
	v_mul_f32_e32 v226, v62, v62
	v_fmac_f32_e32 v226, v63, v63
	v_fmac_f32_e32 v226, v64, v64
	v_fmac_f32_e32 v226, v65, v65
	s_mov_b32 s56, s58
	s_mov_b32 s57, s59
	s_mov_b32 s40, s46
	s_mov_b32 s41, s47
	global_store_dwordx4 v240, v[2:5], s[56:57]
	global_store_dwordx2 v244, v[136:137], s[40:41]
	s_add_u32 s56, s56, 0x10000
	s_addc_u32 s57, s57, 0
	s_add_u32 s40, s40, 0x8400
	s_addc_u32 s41, s41, 0
	global_store_dwordx4 v240, v[6:9], s[56:57]
	global_store_dwordx2 v244, v[140:141], s[40:41]
	s_add_u32 s56, s56, 0x10000
	s_addc_u32 s57, s57, 0
	s_add_u32 s40, s40, 0x8400
	s_addc_u32 s41, s41, 0
	global_store_dwordx4 v240, v[10:13], s[56:57]
	global_store_dwordx2 v244, v[144:145], s[40:41]
	s_add_u32 s56, s56, 0x10000
	s_addc_u32 s57, s57, 0
	s_add_u32 s40, s40, 0x8400
	s_addc_u32 s41, s41, 0
	global_store_dwordx4 v240, v[14:17], s[56:57]
	global_store_dwordx2 v244, v[148:149], s[40:41]
	s_add_u32 s56, s56, 0x10000
	s_addc_u32 s57, s57, 0
	s_add_u32 s40, s40, 0x8400
	s_addc_u32 s41, s41, 0
	global_store_dwordx4 v240, v[18:21], s[56:57]
	global_store_dwordx2 v244, v[172:173], s[40:41]
	s_add_u32 s56, s56, 0x10000
	s_addc_u32 s57, s57, 0
	s_add_u32 s40, s40, 0x8400
	s_addc_u32 s41, s41, 0
	global_store_dwordx4 v240, v[22:25], s[56:57]
	global_store_dwordx2 v244, v[176:177], s[40:41]
	s_add_u32 s56, s56, 0x10000
	s_addc_u32 s57, s57, 0
	s_add_u32 s40, s40, 0x8400
	s_addc_u32 s41, s41, 0
	global_store_dwordx4 v240, v[26:29], s[56:57]
	global_store_dwordx2 v244, v[180:181], s[40:41]
	s_add_u32 s56, s56, 0x10000
	s_addc_u32 s57, s57, 0
	s_add_u32 s40, s40, 0x8400
	s_addc_u32 s41, s41, 0
	global_store_dwordx4 v240, v[30:33], s[56:57]
	global_store_dwordx2 v244, v[184:185], s[40:41]
	s_add_u32 s56, s56, 0x10000
	s_addc_u32 s57, s57, 0
	s_add_u32 s40, s40, 0x8400
	s_addc_u32 s41, s41, 0
	global_store_dwordx4 v240, v[34:37], s[56:57]
	global_store_dwordx2 v244, v[188:189], s[40:41]
	s_add_u32 s56, s56, 0x10000
	s_addc_u32 s57, s57, 0
	s_add_u32 s40, s40, 0x8400
	s_addc_u32 s41, s41, 0
	global_store_dwordx4 v240, v[38:41], s[56:57]
	global_store_dwordx2 v244, v[196:197], s[40:41]
	s_add_u32 s56, s56, 0x10000
	s_addc_u32 s57, s57, 0
	s_add_u32 s40, s40, 0x8400
	s_addc_u32 s41, s41, 0
	global_store_dwordx4 v240, v[42:45], s[56:57]
	global_store_dwordx2 v244, v[200:201], s[40:41]
	s_add_u32 s56, s56, 0x10000
	s_addc_u32 s57, s57, 0
	s_add_u32 s40, s40, 0x8400
	s_addc_u32 s41, s41, 0
	global_store_dwordx4 v240, v[46:49], s[56:57]
	global_store_dwordx2 v244, v[204:205], s[40:41]
	s_add_u32 s56, s56, 0x10000
	s_addc_u32 s57, s57, 0
	s_add_u32 s40, s40, 0x8400
	s_addc_u32 s41, s41, 0
	global_store_dwordx4 v240, v[50:53], s[56:57]
	global_store_dwordx2 v244, v[212:213], s[40:41]
	s_add_u32 s56, s56, 0x10000
	s_addc_u32 s57, s57, 0
	s_add_u32 s40, s40, 0x8400
	s_addc_u32 s41, s41, 0
	global_store_dwordx4 v240, v[54:57], s[56:57]
	global_store_dwordx2 v244, v[216:217], s[40:41]
	s_add_u32 s56, s56, 0x10000
	s_addc_u32 s57, s57, 0
	s_add_u32 s40, s40, 0x8400
	s_addc_u32 s41, s41, 0
	global_store_dwordx4 v240, v[58:61], s[56:57]
	global_store_dwordx2 v244, v[220:221], s[40:41]
	s_add_u32 s56, s56, 0x10000
	s_addc_u32 s57, s57, 0
	s_add_u32 s40, s40, 0x8400
	s_addc_u32 s41, s41, 0
	global_store_dwordx4 v240, v[62:65], s[56:57]
	global_store_dwordx2 v244, v[224:225], s[40:41]
	v_add_f32_dpp v138, v138, v138 quad_perm:[1,0,3,2] row_mask:0xf bank_mask:0xf
	v_add_f32_dpp v142, v142, v142 quad_perm:[1,0,3,2] row_mask:0xf bank_mask:0xf
	v_add_f32_dpp v146, v146, v146 quad_perm:[1,0,3,2] row_mask:0xf bank_mask:0xf
	v_add_f32_dpp v150, v150, v150 quad_perm:[1,0,3,2] row_mask:0xf bank_mask:0xf
	v_add_f32_dpp v174, v174, v174 quad_perm:[1,0,3,2] row_mask:0xf bank_mask:0xf
	v_add_f32_dpp v178, v178, v178 quad_perm:[1,0,3,2] row_mask:0xf bank_mask:0xf
	v_add_f32_dpp v182, v182, v182 quad_perm:[1,0,3,2] row_mask:0xf bank_mask:0xf
	v_add_f32_dpp v186, v186, v186 quad_perm:[1,0,3,2] row_mask:0xf bank_mask:0xf
	v_add_f32_dpp v190, v190, v190 quad_perm:[1,0,3,2] row_mask:0xf bank_mask:0xf
	v_add_f32_dpp v198, v198, v198 quad_perm:[1,0,3,2] row_mask:0xf bank_mask:0xf
	v_add_f32_dpp v202, v202, v202 quad_perm:[1,0,3,2] row_mask:0xf bank_mask:0xf
	v_add_f32_dpp v206, v206, v206 quad_perm:[1,0,3,2] row_mask:0xf bank_mask:0xf
	v_add_f32_dpp v214, v214, v214 quad_perm:[1,0,3,2] row_mask:0xf bank_mask:0xf
	v_add_f32_dpp v218, v218, v218 quad_perm:[1,0,3,2] row_mask:0xf bank_mask:0xf
	v_add_f32_dpp v222, v222, v222 quad_perm:[1,0,3,2] row_mask:0xf bank_mask:0xf
	v_add_f32_dpp v226, v226, v226 quad_perm:[1,0,3,2] row_mask:0xf bank_mask:0xf
	v_add_f32_dpp v138, v138, v138 quad_perm:[2,3,0,1] row_mask:0xf bank_mask:0xf
	v_add_f32_dpp v142, v142, v142 quad_perm:[2,3,0,1] row_mask:0xf bank_mask:0xf
	v_add_f32_dpp v146, v146, v146 quad_perm:[2,3,0,1] row_mask:0xf bank_mask:0xf
	v_add_f32_dpp v150, v150, v150 quad_perm:[2,3,0,1] row_mask:0xf bank_mask:0xf
	v_add_f32_dpp v174, v174, v174 quad_perm:[2,3,0,1] row_mask:0xf bank_mask:0xf
	v_add_f32_dpp v178, v178, v178 quad_perm:[2,3,0,1] row_mask:0xf bank_mask:0xf
	v_add_f32_dpp v182, v182, v182 quad_perm:[2,3,0,1] row_mask:0xf bank_mask:0xf
	v_add_f32_dpp v186, v186, v186 quad_perm:[2,3,0,1] row_mask:0xf bank_mask:0xf
	v_add_f32_dpp v190, v190, v190 quad_perm:[2,3,0,1] row_mask:0xf bank_mask:0xf
	v_add_f32_dpp v198, v198, v198 quad_perm:[2,3,0,1] row_mask:0xf bank_mask:0xf
	v_add_f32_dpp v202, v202, v202 quad_perm:[2,3,0,1] row_mask:0xf bank_mask:0xf
	v_add_f32_dpp v206, v206, v206 quad_perm:[2,3,0,1] row_mask:0xf bank_mask:0xf
	v_add_f32_dpp v214, v214, v214 quad_perm:[2,3,0,1] row_mask:0xf bank_mask:0xf
	v_add_f32_dpp v218, v218, v218 quad_perm:[2,3,0,1] row_mask:0xf bank_mask:0xf
	v_add_f32_dpp v222, v222, v222 quad_perm:[2,3,0,1] row_mask:0xf bank_mask:0xf
	v_add_f32_dpp v226, v226, v226 quad_perm:[2,3,0,1] row_mask:0xf bank_mask:0xf
	v_add_f32_dpp v138, v138, v138 row_half_mirror row_mask:0xf bank_mask:0xf
	v_add_f32_dpp v142, v142, v142 row_half_mirror row_mask:0xf bank_mask:0xf
	v_add_f32_dpp v146, v146, v146 row_half_mirror row_mask:0xf bank_mask:0xf
	v_add_f32_dpp v150, v150, v150 row_half_mirror row_mask:0xf bank_mask:0xf
	v_add_f32_dpp v174, v174, v174 row_half_mirror row_mask:0xf bank_mask:0xf
	v_add_f32_dpp v178, v178, v178 row_half_mirror row_mask:0xf bank_mask:0xf
	v_add_f32_dpp v182, v182, v182 row_half_mirror row_mask:0xf bank_mask:0xf
	v_add_f32_dpp v186, v186, v186 row_half_mirror row_mask:0xf bank_mask:0xf
	v_add_f32_dpp v190, v190, v190 row_half_mirror row_mask:0xf bank_mask:0xf
	v_add_f32_dpp v198, v198, v198 row_half_mirror row_mask:0xf bank_mask:0xf
	v_add_f32_dpp v202, v202, v202 row_half_mirror row_mask:0xf bank_mask:0xf
	v_add_f32_dpp v206, v206, v206 row_half_mirror row_mask:0xf bank_mask:0xf
	v_add_f32_dpp v214, v214, v214 row_half_mirror row_mask:0xf bank_mask:0xf
	v_add_f32_dpp v218, v218, v218 row_half_mirror row_mask:0xf bank_mask:0xf
	v_add_f32_dpp v222, v222, v222 row_half_mirror row_mask:0xf bank_mask:0xf
	v_add_f32_dpp v226, v226, v226 row_half_mirror row_mask:0xf bank_mask:0xf
	v_add_f32_dpp v138, v138, v138 row_mirror row_mask:0xf bank_mask:0xf
	v_add_f32_dpp v142, v142, v142 row_mirror row_mask:0xf bank_mask:0xf
	v_add_f32_dpp v146, v146, v146 row_mirror row_mask:0xf bank_mask:0xf
	v_add_f32_dpp v150, v150, v150 row_mirror row_mask:0xf bank_mask:0xf
	v_add_f32_dpp v174, v174, v174 row_mirror row_mask:0xf bank_mask:0xf
	v_add_f32_dpp v178, v178, v178 row_mirror row_mask:0xf bank_mask:0xf
	v_add_f32_dpp v182, v182, v182 row_mirror row_mask:0xf bank_mask:0xf
	v_add_f32_dpp v186, v186, v186 row_mirror row_mask:0xf bank_mask:0xf
	v_add_f32_dpp v190, v190, v190 row_mirror row_mask:0xf bank_mask:0xf
	v_add_f32_dpp v198, v198, v198 row_mirror row_mask:0xf bank_mask:0xf
	v_add_f32_dpp v202, v202, v202 row_mirror row_mask:0xf bank_mask:0xf
	v_add_f32_dpp v206, v206, v206 row_mirror row_mask:0xf bank_mask:0xf
	v_add_f32_dpp v214, v214, v214 row_mirror row_mask:0xf bank_mask:0xf
	v_add_f32_dpp v218, v218, v218 row_mirror row_mask:0xf bank_mask:0xf
	v_add_f32_dpp v222, v222, v222 row_mirror row_mask:0xf bank_mask:0xf
	v_add_f32_dpp v226, v226, v226 row_mirror row_mask:0xf bank_mask:0xf
	v_add_f32_dpp v138, v138, v138 row_bcast:15 row_mask:0xa bank_mask:0xf
	v_add_f32_dpp v142, v142, v142 row_bcast:15 row_mask:0xa bank_mask:0xf
	v_add_f32_dpp v146, v146, v146 row_bcast:15 row_mask:0xa bank_mask:0xf
	v_add_f32_dpp v150, v150, v150 row_bcast:15 row_mask:0xa bank_mask:0xf
	v_add_f32_dpp v174, v174, v174 row_bcast:15 row_mask:0xa bank_mask:0xf
	v_add_f32_dpp v178, v178, v178 row_bcast:15 row_mask:0xa bank_mask:0xf
	v_add_f32_dpp v182, v182, v182 row_bcast:15 row_mask:0xa bank_mask:0xf
	v_add_f32_dpp v186, v186, v186 row_bcast:15 row_mask:0xa bank_mask:0xf
	v_add_f32_dpp v190, v190, v190 row_bcast:15 row_mask:0xa bank_mask:0xf
	v_add_f32_dpp v198, v198, v198 row_bcast:15 row_mask:0xa bank_mask:0xf
	v_add_f32_dpp v202, v202, v202 row_bcast:15 row_mask:0xa bank_mask:0xf
	v_add_f32_dpp v206, v206, v206 row_bcast:15 row_mask:0xa bank_mask:0xf
	v_add_f32_dpp v214, v214, v214 row_bcast:15 row_mask:0xa bank_mask:0xf
	v_add_f32_dpp v218, v218, v218 row_bcast:15 row_mask:0xa bank_mask:0xf
	v_add_f32_dpp v222, v222, v222 row_bcast:15 row_mask:0xa bank_mask:0xf
	v_add_f32_dpp v226, v226, v226 row_bcast:15 row_mask:0xa bank_mask:0xf
	s_mov_b32 exec_lo, 0x10000
	s_mov_b32 exec_hi, 0x10000
	global_atomic_add_f32 v245, v138, s[48:49]
	global_atomic_add_f32 v245, v142, s[48:49] offset:32
	global_atomic_add_f32 v245, v146, s[48:49] offset:64
	global_atomic_add_f32 v245, v150, s[48:49] offset:96
	global_atomic_add_f32 v245, v174, s[48:49] offset:128
	global_atomic_add_f32 v245, v178, s[48:49] offset:160
	global_atomic_add_f32 v245, v182, s[48:49] offset:192
	global_atomic_add_f32 v245, v186, s[48:49] offset:224
	global_atomic_add_f32 v245, v190, s[48:49] offset:256
	global_atomic_add_f32 v245, v198, s[48:49] offset:288
	global_atomic_add_f32 v245, v202, s[48:49] offset:320
	global_atomic_add_f32 v245, v206, s[48:49] offset:352
	global_atomic_add_f32 v245, v214, s[48:49] offset:384
	global_atomic_add_f32 v245, v218, s[48:49] offset:416
	global_atomic_add_f32 v245, v222, s[48:49] offset:448
	global_atomic_add_f32 v245, v226, s[48:49] offset:480
	s_mov_b64 exec, -1
	s_add_u32 s44, s44, 0x1000
	s_addc_u32 s45, s45, 0
	s_add_u32 s58, s58, 0x1000
	s_addc_u32 s59, s59, 0
	s_add_u32 s46, s46, 0x800
	s_addc_u32 s47, s47, 0
	s_waitcnt lgkmcnt(0)
	s_barrier
	s_mov_b32 s56, s44
	s_mov_b32 s57, s45
	global_load_dwordx4 v[136:139], v240, s[56:57]
	s_add_u32 s56, s56, 0x10000
	s_addc_u32 s57, s57, 0
	global_load_dwordx4 v[140:143], v240, s[56:57]
	s_add_u32 s56, s56, 0x10000
	s_addc_u32 s57, s57, 0
	global_load_dwordx4 v[144:147], v240, s[56:57]
	s_add_u32 s56, s56, 0x10000
	s_addc_u32 s57, s57, 0
	global_load_dwordx4 v[148:151], v240, s[56:57]
	s_add_u32 s56, s56, 0x10000
	s_addc_u32 s57, s57, 0
	global_load_dwordx4 v[172:175], v240, s[56:57]
	s_add_u32 s56, s56, 0x10000
	s_addc_u32 s57, s57, 0
	global_load_dwordx4 v[176:179], v240, s[56:57]
	s_add_u32 s56, s56, 0x10000
	s_addc_u32 s57, s57, 0
	global_load_dwordx4 v[180:183], v240, s[56:57]
	s_add_u32 s56, s56, 0x10000
	s_addc_u32 s57, s57, 0
	global_load_dwordx4 v[184:187], v240, s[56:57]
	s_add_u32 s56, s56, 0x10000
	s_addc_u32 s57, s57, 0
	global_load_dwordx4 v[188:191], v240, s[56:57]
	s_add_u32 s56, s56, 0x10000
	s_addc_u32 s57, s57, 0
	global_load_dwordx4 v[196:199], v240, s[56:57]
	s_add_u32 s56, s56, 0x10000
	s_addc_u32 s57, s57, 0
	global_load_dwordx4 v[200:203], v240, s[56:57]
	s_add_u32 s56, s56, 0x10000
	s_addc_u32 s57, s57, 0
	global_load_dwordx4 v[204:207], v240, s[56:57]
	s_add_u32 s56, s56, 0x10000
	s_addc_u32 s57, s57, 0
	global_load_dwordx4 v[212:215], v240, s[56:57]
	s_add_u32 s56, s56, 0x10000
	s_addc_u32 s57, s57, 0
	global_load_dwordx4 v[216:219], v240, s[56:57]
	s_add_u32 s56, s56, 0x10000
	s_addc_u32 s57, s57, 0
	global_load_dwordx4 v[220:223], v240, s[56:57]
	s_add_u32 s56, s56, 0x10000
	s_addc_u32 s57, s57, 0
	global_load_dwordx4 v[224:227], v240, s[56:57]
	ds_write_b32 v238, v66
	ds_write_b32 v238, v67 offset:528
	ds_write_b32 v238, v68 offset:1056
	ds_write_b32 v238, v69 offset:1584
	ds_write_b32 v238, v70 offset:64
	ds_write_b32 v238, v71 offset:592
	ds_write_b32 v238, v72 offset:1120
	ds_write_b32 v238, v73 offset:1648
	ds_write_b32 v238, v74 offset:128
	ds_write_b32 v238, v75 offset:656
	ds_write_b32 v238, v76 offset:1184
	ds_write_b32 v238, v77 offset:1712
	ds_write_b32 v238, v78 offset:192
	ds_write_b32 v238, v79 offset:720
	ds_write_b32 v238, v80 offset:1248
	ds_write_b32 v238, v81 offset:1776
	ds_write_b32 v238, v82 offset:8448
	ds_write_b32 v238, v83 offset:8976
	ds_write_b32 v238, v84 offset:9504
	ds_write_b32 v238, v85 offset:10032
	ds_write_b32 v238, v86 offset:8512
	ds_write_b32 v238, v87 offset:9040
	ds_write_b32 v238, v88 offset:9568
	ds_write_b32 v238, v89 offset:10096
	ds_write_b32 v238, v90 offset:8576
	ds_write_b32 v238, v91 offset:9104
	ds_write_b32 v238, v92 offset:9632
	ds_write_b32 v238, v93 offset:10160
	ds_write_b32 v238, v94 offset:8640
	ds_write_b32 v238, v95 offset:9168
	ds_write_b32 v238, v96 offset:9696
	ds_write_b32 v238, v97 offset:10224
	ds_write_b32 v238, v98 offset:16896
	ds_write_b32 v238, v99 offset:17424
	ds_write_b32 v238, v100 offset:17952
	ds_write_b32 v238, v101 offset:18480
	ds_write_b32 v238, v102 offset:16960
	ds_write_b32 v238, v103 offset:17488
	ds_write_b32 v238, v104 offset:18016
	ds_write_b32 v238, v105 offset:18544
	ds_write_b32 v238, v106 offset:17024
	ds_write_b32 v238, v107 offset:17552
	ds_write_b32 v238, v108 offset:18080
	ds_write_b32 v238, v109 offset:18608
	ds_write_b32 v238, v110 offset:17088
	ds_write_b32 v238, v111 offset:17616
	ds_write_b32 v238, v112 offset:18144
	ds_write_b32 v238, v113 offset:18672
	ds_write_b32 v238, v114 offset:25344
	ds_write_b32 v238, v115 offset:25872
	ds_write_b32 v238, v116 offset:26400
	ds_write_b32 v238, v117 offset:26928
	ds_write_b32 v238, v118 offset:25408
	ds_write_b32 v238, v119 offset:25936
	ds_write_b32 v238, v120 offset:26464
	ds_write_b32 v238, v121 offset:26992
	ds_write_b32 v238, v122 offset:25472
	ds_write_b32 v238, v123 offset:26000
	ds_write_b32 v238, v124 offset:26528
	ds_write_b32 v238, v125 offset:27056
	ds_write_b32 v238, v126 offset:25536
	ds_write_b32 v238, v127 offset:26064
	ds_write_b32 v238, v128 offset:26592
	ds_write_b32 v238, v129 offset:27120
	s_waitcnt lgkmcnt(0)
	s_barrier
	ds_read_b128 v[66:69], v239
	ds_read_b128 v[70:73], v239 offset:4224
	ds_read_b128 v[74:77], v239 offset:8448
	ds_read_b128 v[78:81], v239 offset:12672
	ds_read_b128 v[82:85], v239 offset:16896
	ds_read_b128 v[86:89], v239 offset:21120
	ds_read_b128 v[90:93], v239 offset:25344
	ds_read_b128 v[94:97], v239 offset:29568
	ds_read_b128 v[98:101], v239 offset:33792
	ds_read_b128 v[102:105], v239 offset:38016
	ds_read_b128 v[106:109], v239 offset:42240
	ds_read_b128 v[110:113], v239 offset:46464
	ds_read_b128 v[114:117], v239 offset:50688
	ds_read_b128 v[118:121], v239 offset:54912
	ds_read_b128 v[122:125], v239 offset:59136
	ds_read_b128 v[126:129], v239 offset:63360
	s_waitcnt vmcnt(15) lgkmcnt(15)
	v_pk_add_f32 v[66:67], v[66:67], v[136:137]
	v_pk_add_f32 v[68:69], v[68:69], v[138:139]
	v_cvt_pk_bf16_f32 v136, v66, v67
	v_cvt_pk_bf16_f32 v137, v68, v69
	v_mul_f32_e32 v138, v66, v66
	v_fmac_f32_e32 v138, v67, v67
	v_fmac_f32_e32 v138, v68, v68
	v_fmac_f32_e32 v138, v69, v69
	s_waitcnt vmcnt(14) lgkmcnt(14)
	v_pk_add_f32 v[70:71], v[70:71], v[140:141]
	v_pk_add_f32 v[72:73], v[72:73], v[142:143]
	v_cvt_pk_bf16_f32 v140, v70, v71
	v_cvt_pk_bf16_f32 v141, v72, v73
	v_mul_f32_e32 v142, v70, v70
	v_fmac_f32_e32 v142, v71, v71
	v_fmac_f32_e32 v142, v72, v72
	v_fmac_f32_e32 v142, v73, v73
	s_waitcnt vmcnt(13) lgkmcnt(13)
	v_pk_add_f32 v[74:75], v[74:75], v[144:145]
	v_pk_add_f32 v[76:77], v[76:77], v[146:147]
	v_cvt_pk_bf16_f32 v144, v74, v75
	v_cvt_pk_bf16_f32 v145, v76, v77
	v_mul_f32_e32 v146, v74, v74
	v_fmac_f32_e32 v146, v75, v75
	v_fmac_f32_e32 v146, v76, v76
	v_fmac_f32_e32 v146, v77, v77
	s_waitcnt vmcnt(12) lgkmcnt(12)
	v_pk_add_f32 v[78:79], v[78:79], v[148:149]
	v_pk_add_f32 v[80:81], v[80:81], v[150:151]
	v_cvt_pk_bf16_f32 v148, v78, v79
	v_cvt_pk_bf16_f32 v149, v80, v81
	v_mul_f32_e32 v150, v78, v78
	v_fmac_f32_e32 v150, v79, v79
	v_fmac_f32_e32 v150, v80, v80
	v_fmac_f32_e32 v150, v81, v81
	s_waitcnt vmcnt(11) lgkmcnt(11)
	v_pk_add_f32 v[82:83], v[82:83], v[172:173]
	v_pk_add_f32 v[84:85], v[84:85], v[174:175]
	v_cvt_pk_bf16_f32 v172, v82, v83
	v_cvt_pk_bf16_f32 v173, v84, v85
	v_mul_f32_e32 v174, v82, v82
	v_fmac_f32_e32 v174, v83, v83
	v_fmac_f32_e32 v174, v84, v84
	v_fmac_f32_e32 v174, v85, v85
	s_waitcnt vmcnt(10) lgkmcnt(10)
	v_pk_add_f32 v[86:87], v[86:87], v[176:177]
	v_pk_add_f32 v[88:89], v[88:89], v[178:179]
	v_cvt_pk_bf16_f32 v176, v86, v87
	v_cvt_pk_bf16_f32 v177, v88, v89
	v_mul_f32_e32 v178, v86, v86
	v_fmac_f32_e32 v178, v87, v87
	v_fmac_f32_e32 v178, v88, v88
	v_fmac_f32_e32 v178, v89, v89
	s_waitcnt vmcnt(9) lgkmcnt(9)
	v_pk_add_f32 v[90:91], v[90:91], v[180:181]
	v_pk_add_f32 v[92:93], v[92:93], v[182:183]
	v_cvt_pk_bf16_f32 v180, v90, v91
	v_cvt_pk_bf16_f32 v181, v92, v93
	v_mul_f32_e32 v182, v90, v90
	v_fmac_f32_e32 v182, v91, v91
	v_fmac_f32_e32 v182, v92, v92
	v_fmac_f32_e32 v182, v93, v93
	s_waitcnt vmcnt(8) lgkmcnt(8)
	v_pk_add_f32 v[94:95], v[94:95], v[184:185]
	v_pk_add_f32 v[96:97], v[96:97], v[186:187]
	v_cvt_pk_bf16_f32 v184, v94, v95
	v_cvt_pk_bf16_f32 v185, v96, v97
	v_mul_f32_e32 v186, v94, v94
	v_fmac_f32_e32 v186, v95, v95
	v_fmac_f32_e32 v186, v96, v96
	v_fmac_f32_e32 v186, v97, v97
	s_waitcnt vmcnt(7) lgkmcnt(7)
	v_pk_add_f32 v[98:99], v[98:99], v[188:189]
	v_pk_add_f32 v[100:101], v[100:101], v[190:191]
	v_cvt_pk_bf16_f32 v188, v98, v99
	v_cvt_pk_bf16_f32 v189, v100, v101
	v_mul_f32_e32 v190, v98, v98
	v_fmac_f32_e32 v190, v99, v99
	v_fmac_f32_e32 v190, v100, v100
	v_fmac_f32_e32 v190, v101, v101
	s_waitcnt vmcnt(6) lgkmcnt(6)
	v_pk_add_f32 v[102:103], v[102:103], v[196:197]
	v_pk_add_f32 v[104:105], v[104:105], v[198:199]
	v_cvt_pk_bf16_f32 v196, v102, v103
	v_cvt_pk_bf16_f32 v197, v104, v105
	v_mul_f32_e32 v198, v102, v102
	v_fmac_f32_e32 v198, v103, v103
	v_fmac_f32_e32 v198, v104, v104
	v_fmac_f32_e32 v198, v105, v105
	s_waitcnt vmcnt(5) lgkmcnt(5)
	v_pk_add_f32 v[106:107], v[106:107], v[200:201]
	v_pk_add_f32 v[108:109], v[108:109], v[202:203]
	v_cvt_pk_bf16_f32 v200, v106, v107
	v_cvt_pk_bf16_f32 v201, v108, v109
	v_mul_f32_e32 v202, v106, v106
	v_fmac_f32_e32 v202, v107, v107
	v_fmac_f32_e32 v202, v108, v108
	v_fmac_f32_e32 v202, v109, v109
	s_waitcnt vmcnt(4) lgkmcnt(4)
	v_pk_add_f32 v[110:111], v[110:111], v[204:205]
	v_pk_add_f32 v[112:113], v[112:113], v[206:207]
	v_cvt_pk_bf16_f32 v204, v110, v111
	v_cvt_pk_bf16_f32 v205, v112, v113
	v_mul_f32_e32 v206, v110, v110
	v_fmac_f32_e32 v206, v111, v111
	v_fmac_f32_e32 v206, v112, v112
	v_fmac_f32_e32 v206, v113, v113
	s_waitcnt vmcnt(3) lgkmcnt(3)
	v_pk_add_f32 v[114:115], v[114:115], v[212:213]
	v_pk_add_f32 v[116:117], v[116:117], v[214:215]
	v_cvt_pk_bf16_f32 v212, v114, v115
	v_cvt_pk_bf16_f32 v213, v116, v117
	v_mul_f32_e32 v214, v114, v114
	v_fmac_f32_e32 v214, v115, v115
	v_fmac_f32_e32 v214, v116, v116
	v_fmac_f32_e32 v214, v117, v117
	s_waitcnt vmcnt(2) lgkmcnt(2)
	v_pk_add_f32 v[118:119], v[118:119], v[216:217]
	v_pk_add_f32 v[120:121], v[120:121], v[218:219]
	v_cvt_pk_bf16_f32 v216, v118, v119
	v_cvt_pk_bf16_f32 v217, v120, v121
	v_mul_f32_e32 v218, v118, v118
	v_fmac_f32_e32 v218, v119, v119
	v_fmac_f32_e32 v218, v120, v120
	v_fmac_f32_e32 v218, v121, v121
	s_waitcnt vmcnt(1) lgkmcnt(1)
	v_pk_add_f32 v[122:123], v[122:123], v[220:221]
	v_pk_add_f32 v[124:125], v[124:125], v[222:223]
	v_cvt_pk_bf16_f32 v220, v122, v123
	v_cvt_pk_bf16_f32 v221, v124, v125
	v_mul_f32_e32 v222, v122, v122
	v_fmac_f32_e32 v222, v123, v123
	v_fmac_f32_e32 v222, v124, v124
	v_fmac_f32_e32 v222, v125, v125
	s_waitcnt vmcnt(0) lgkmcnt(0)
	v_pk_add_f32 v[126:127], v[126:127], v[224:225]
	v_pk_add_f32 v[128:129], v[128:129], v[226:227]
	v_cvt_pk_bf16_f32 v224, v126, v127
	v_cvt_pk_bf16_f32 v225, v128, v129
	v_mul_f32_e32 v226, v126, v126
	v_fmac_f32_e32 v226, v127, v127
	v_fmac_f32_e32 v226, v128, v128
	v_fmac_f32_e32 v226, v129, v129
	s_mov_b32 s56, s58
	s_mov_b32 s57, s59
	s_mov_b32 s40, s46
	s_mov_b32 s41, s47
	global_store_dwordx4 v240, v[66:69], s[56:57]
	global_store_dwordx2 v244, v[136:137], s[40:41]
	s_add_u32 s56, s56, 0x10000
	s_addc_u32 s57, s57, 0
	s_add_u32 s40, s40, 0x8400
	s_addc_u32 s41, s41, 0
	global_store_dwordx4 v240, v[70:73], s[56:57]
	global_store_dwordx2 v244, v[140:141], s[40:41]
	s_add_u32 s56, s56, 0x10000
	s_addc_u32 s57, s57, 0
	s_add_u32 s40, s40, 0x8400
	s_addc_u32 s41, s41, 0
	global_store_dwordx4 v240, v[74:77], s[56:57]
	global_store_dwordx2 v244, v[144:145], s[40:41]
	s_add_u32 s56, s56, 0x10000
	s_addc_u32 s57, s57, 0
	s_add_u32 s40, s40, 0x8400
	s_addc_u32 s41, s41, 0
	global_store_dwordx4 v240, v[78:81], s[56:57]
	global_store_dwordx2 v244, v[148:149], s[40:41]
	s_add_u32 s56, s56, 0x10000
	s_addc_u32 s57, s57, 0
	s_add_u32 s40, s40, 0x8400
	s_addc_u32 s41, s41, 0
	global_store_dwordx4 v240, v[82:85], s[56:57]
	global_store_dwordx2 v244, v[172:173], s[40:41]
	s_add_u32 s56, s56, 0x10000
	s_addc_u32 s57, s57, 0
	s_add_u32 s40, s40, 0x8400
	s_addc_u32 s41, s41, 0
	global_store_dwordx4 v240, v[86:89], s[56:57]
	global_store_dwordx2 v244, v[176:177], s[40:41]
	s_add_u32 s56, s56, 0x10000
	s_addc_u32 s57, s57, 0
	s_add_u32 s40, s40, 0x8400
	s_addc_u32 s41, s41, 0
	global_store_dwordx4 v240, v[90:93], s[56:57]
	global_store_dwordx2 v244, v[180:181], s[40:41]
	s_add_u32 s56, s56, 0x10000
	s_addc_u32 s57, s57, 0
	s_add_u32 s40, s40, 0x8400
	s_addc_u32 s41, s41, 0
	global_store_dwordx4 v240, v[94:97], s[56:57]
	global_store_dwordx2 v244, v[184:185], s[40:41]
	s_add_u32 s56, s56, 0x10000
	s_addc_u32 s57, s57, 0
	s_add_u32 s40, s40, 0x8400
	s_addc_u32 s41, s41, 0
	global_store_dwordx4 v240, v[98:101], s[56:57]
	global_store_dwordx2 v244, v[188:189], s[40:41]
	s_add_u32 s56, s56, 0x10000
	s_addc_u32 s57, s57, 0
	s_add_u32 s40, s40, 0x8400
	s_addc_u32 s41, s41, 0
	global_store_dwordx4 v240, v[102:105], s[56:57]
	global_store_dwordx2 v244, v[196:197], s[40:41]
	s_add_u32 s56, s56, 0x10000
	s_addc_u32 s57, s57, 0
	s_add_u32 s40, s40, 0x8400
	s_addc_u32 s41, s41, 0
	global_store_dwordx4 v240, v[106:109], s[56:57]
	global_store_dwordx2 v244, v[200:201], s[40:41]
	s_add_u32 s56, s56, 0x10000
	s_addc_u32 s57, s57, 0
	s_add_u32 s40, s40, 0x8400
	s_addc_u32 s41, s41, 0
	global_store_dwordx4 v240, v[110:113], s[56:57]
	global_store_dwordx2 v244, v[204:205], s[40:41]
	s_add_u32 s56, s56, 0x10000
	s_addc_u32 s57, s57, 0
	s_add_u32 s40, s40, 0x8400
	s_addc_u32 s41, s41, 0
	global_store_dwordx4 v240, v[114:117], s[56:57]
	global_store_dwordx2 v244, v[212:213], s[40:41]
	s_add_u32 s56, s56, 0x10000
	s_addc_u32 s57, s57, 0
	s_add_u32 s40, s40, 0x8400
	s_addc_u32 s41, s41, 0
	global_store_dwordx4 v240, v[118:121], s[56:57]
	global_store_dwordx2 v244, v[216:217], s[40:41]
	s_add_u32 s56, s56, 0x10000
	s_addc_u32 s57, s57, 0
	s_add_u32 s40, s40, 0x8400
	s_addc_u32 s41, s41, 0
	global_store_dwordx4 v240, v[122:125], s[56:57]
	global_store_dwordx2 v244, v[220:221], s[40:41]
	s_add_u32 s56, s56, 0x10000
	s_addc_u32 s57, s57, 0
	s_add_u32 s40, s40, 0x8400
	s_addc_u32 s41, s41, 0
	global_store_dwordx4 v240, v[126:129], s[56:57]
	global_store_dwordx2 v244, v[224:225], s[40:41]
	v_add_f32_dpp v138, v138, v138 quad_perm:[1,0,3,2] row_mask:0xf bank_mask:0xf
	v_add_f32_dpp v142, v142, v142 quad_perm:[1,0,3,2] row_mask:0xf bank_mask:0xf
	v_add_f32_dpp v146, v146, v146 quad_perm:[1,0,3,2] row_mask:0xf bank_mask:0xf
	v_add_f32_dpp v150, v150, v150 quad_perm:[1,0,3,2] row_mask:0xf bank_mask:0xf
	v_add_f32_dpp v174, v174, v174 quad_perm:[1,0,3,2] row_mask:0xf bank_mask:0xf
	v_add_f32_dpp v178, v178, v178 quad_perm:[1,0,3,2] row_mask:0xf bank_mask:0xf
	v_add_f32_dpp v182, v182, v182 quad_perm:[1,0,3,2] row_mask:0xf bank_mask:0xf
	v_add_f32_dpp v186, v186, v186 quad_perm:[1,0,3,2] row_mask:0xf bank_mask:0xf
	v_add_f32_dpp v190, v190, v190 quad_perm:[1,0,3,2] row_mask:0xf bank_mask:0xf
	v_add_f32_dpp v198, v198, v198 quad_perm:[1,0,3,2] row_mask:0xf bank_mask:0xf
	v_add_f32_dpp v202, v202, v202 quad_perm:[1,0,3,2] row_mask:0xf bank_mask:0xf
	v_add_f32_dpp v206, v206, v206 quad_perm:[1,0,3,2] row_mask:0xf bank_mask:0xf
	v_add_f32_dpp v214, v214, v214 quad_perm:[1,0,3,2] row_mask:0xf bank_mask:0xf
	v_add_f32_dpp v218, v218, v218 quad_perm:[1,0,3,2] row_mask:0xf bank_mask:0xf
	v_add_f32_dpp v222, v222, v222 quad_perm:[1,0,3,2] row_mask:0xf bank_mask:0xf
	v_add_f32_dpp v226, v226, v226 quad_perm:[1,0,3,2] row_mask:0xf bank_mask:0xf
	v_add_f32_dpp v138, v138, v138 quad_perm:[2,3,0,1] row_mask:0xf bank_mask:0xf
	v_add_f32_dpp v142, v142, v142 quad_perm:[2,3,0,1] row_mask:0xf bank_mask:0xf
	v_add_f32_dpp v146, v146, v146 quad_perm:[2,3,0,1] row_mask:0xf bank_mask:0xf
	v_add_f32_dpp v150, v150, v150 quad_perm:[2,3,0,1] row_mask:0xf bank_mask:0xf
	v_add_f32_dpp v174, v174, v174 quad_perm:[2,3,0,1] row_mask:0xf bank_mask:0xf
	v_add_f32_dpp v178, v178, v178 quad_perm:[2,3,0,1] row_mask:0xf bank_mask:0xf
	v_add_f32_dpp v182, v182, v182 quad_perm:[2,3,0,1] row_mask:0xf bank_mask:0xf
	v_add_f32_dpp v186, v186, v186 quad_perm:[2,3,0,1] row_mask:0xf bank_mask:0xf
	v_add_f32_dpp v190, v190, v190 quad_perm:[2,3,0,1] row_mask:0xf bank_mask:0xf
	v_add_f32_dpp v198, v198, v198 quad_perm:[2,3,0,1] row_mask:0xf bank_mask:0xf
	v_add_f32_dpp v202, v202, v202 quad_perm:[2,3,0,1] row_mask:0xf bank_mask:0xf
	v_add_f32_dpp v206, v206, v206 quad_perm:[2,3,0,1] row_mask:0xf bank_mask:0xf
	v_add_f32_dpp v214, v214, v214 quad_perm:[2,3,0,1] row_mask:0xf bank_mask:0xf
	v_add_f32_dpp v218, v218, v218 quad_perm:[2,3,0,1] row_mask:0xf bank_mask:0xf
	v_add_f32_dpp v222, v222, v222 quad_perm:[2,3,0,1] row_mask:0xf bank_mask:0xf
	v_add_f32_dpp v226, v226, v226 quad_perm:[2,3,0,1] row_mask:0xf bank_mask:0xf
	v_add_f32_dpp v138, v138, v138 row_half_mirror row_mask:0xf bank_mask:0xf
	v_add_f32_dpp v142, v142, v142 row_half_mirror row_mask:0xf bank_mask:0xf
	v_add_f32_dpp v146, v146, v146 row_half_mirror row_mask:0xf bank_mask:0xf
	v_add_f32_dpp v150, v150, v150 row_half_mirror row_mask:0xf bank_mask:0xf
	v_add_f32_dpp v174, v174, v174 row_half_mirror row_mask:0xf bank_mask:0xf
	v_add_f32_dpp v178, v178, v178 row_half_mirror row_mask:0xf bank_mask:0xf
	v_add_f32_dpp v182, v182, v182 row_half_mirror row_mask:0xf bank_mask:0xf
	v_add_f32_dpp v186, v186, v186 row_half_mirror row_mask:0xf bank_mask:0xf
	v_add_f32_dpp v190, v190, v190 row_half_mirror row_mask:0xf bank_mask:0xf
	v_add_f32_dpp v198, v198, v198 row_half_mirror row_mask:0xf bank_mask:0xf
	v_add_f32_dpp v202, v202, v202 row_half_mirror row_mask:0xf bank_mask:0xf
	v_add_f32_dpp v206, v206, v206 row_half_mirror row_mask:0xf bank_mask:0xf
	v_add_f32_dpp v214, v214, v214 row_half_mirror row_mask:0xf bank_mask:0xf
	v_add_f32_dpp v218, v218, v218 row_half_mirror row_mask:0xf bank_mask:0xf
	v_add_f32_dpp v222, v222, v222 row_half_mirror row_mask:0xf bank_mask:0xf
	v_add_f32_dpp v226, v226, v226 row_half_mirror row_mask:0xf bank_mask:0xf
	v_add_f32_dpp v138, v138, v138 row_mirror row_mask:0xf bank_mask:0xf
	v_add_f32_dpp v142, v142, v142 row_mirror row_mask:0xf bank_mask:0xf
	v_add_f32_dpp v146, v146, v146 row_mirror row_mask:0xf bank_mask:0xf
	v_add_f32_dpp v150, v150, v150 row_mirror row_mask:0xf bank_mask:0xf
	v_add_f32_dpp v174, v174, v174 row_mirror row_mask:0xf bank_mask:0xf
	v_add_f32_dpp v178, v178, v178 row_mirror row_mask:0xf bank_mask:0xf
	v_add_f32_dpp v182, v182, v182 row_mirror row_mask:0xf bank_mask:0xf
	v_add_f32_dpp v186, v186, v186 row_mirror row_mask:0xf bank_mask:0xf
	v_add_f32_dpp v190, v190, v190 row_mirror row_mask:0xf bank_mask:0xf
	v_add_f32_dpp v198, v198, v198 row_mirror row_mask:0xf bank_mask:0xf
	v_add_f32_dpp v202, v202, v202 row_mirror row_mask:0xf bank_mask:0xf
	v_add_f32_dpp v206, v206, v206 row_mirror row_mask:0xf bank_mask:0xf
	v_add_f32_dpp v214, v214, v214 row_mirror row_mask:0xf bank_mask:0xf
	v_add_f32_dpp v218, v218, v218 row_mirror row_mask:0xf bank_mask:0xf
	v_add_f32_dpp v222, v222, v222 row_mirror row_mask:0xf bank_mask:0xf
	v_add_f32_dpp v226, v226, v226 row_mirror row_mask:0xf bank_mask:0xf
	v_add_f32_dpp v138, v138, v138 row_bcast:15 row_mask:0xa bank_mask:0xf
	v_add_f32_dpp v142, v142, v142 row_bcast:15 row_mask:0xa bank_mask:0xf
	v_add_f32_dpp v146, v146, v146 row_bcast:15 row_mask:0xa bank_mask:0xf
	v_add_f32_dpp v150, v150, v150 row_bcast:15 row_mask:0xa bank_mask:0xf
	v_add_f32_dpp v174, v174, v174 row_bcast:15 row_mask:0xa bank_mask:0xf
	v_add_f32_dpp v178, v178, v178 row_bcast:15 row_mask:0xa bank_mask:0xf
	v_add_f32_dpp v182, v182, v182 row_bcast:15 row_mask:0xa bank_mask:0xf
	v_add_f32_dpp v186, v186, v186 row_bcast:15 row_mask:0xa bank_mask:0xf
	v_add_f32_dpp v190, v190, v190 row_bcast:15 row_mask:0xa bank_mask:0xf
	v_add_f32_dpp v198, v198, v198 row_bcast:15 row_mask:0xa bank_mask:0xf
	v_add_f32_dpp v202, v202, v202 row_bcast:15 row_mask:0xa bank_mask:0xf
	v_add_f32_dpp v206, v206, v206 row_bcast:15 row_mask:0xa bank_mask:0xf
	v_add_f32_dpp v214, v214, v214 row_bcast:15 row_mask:0xa bank_mask:0xf
	v_add_f32_dpp v218, v218, v218 row_bcast:15 row_mask:0xa bank_mask:0xf
	v_add_f32_dpp v222, v222, v222 row_bcast:15 row_mask:0xa bank_mask:0xf
	v_add_f32_dpp v226, v226, v226 row_bcast:15 row_mask:0xa bank_mask:0xf
	s_mov_b32 exec_lo, 0x10000
	s_mov_b32 exec_hi, 0x10000
	global_atomic_add_f32 v245, v138, s[48:49]
	global_atomic_add_f32 v245, v142, s[48:49] offset:32
	global_atomic_add_f32 v245, v146, s[48:49] offset:64
	global_atomic_add_f32 v245, v150, s[48:49] offset:96
	global_atomic_add_f32 v245, v174, s[48:49] offset:128
	global_atomic_add_f32 v245, v178, s[48:49] offset:160
	global_atomic_add_f32 v245, v182, s[48:49] offset:192
	global_atomic_add_f32 v245, v186, s[48:49] offset:224
	global_atomic_add_f32 v245, v190, s[48:49] offset:256
	global_atomic_add_f32 v245, v198, s[48:49] offset:288
	global_atomic_add_f32 v245, v202, s[48:49] offset:320
	global_atomic_add_f32 v245, v206, s[48:49] offset:352
	global_atomic_add_f32 v245, v214, s[48:49] offset:384
	global_atomic_add_f32 v245, v218, s[48:49] offset:416
	global_atomic_add_f32 v245, v222, s[48:49] offset:448
	global_atomic_add_f32 v245, v226, s[48:49] offset:480
	s_mov_b64 exec, -1
	s_add_i32 s21, s21, s72
	s_cmpk_lt_i32 s21, 0x200
	s_waitcnt lgkmcnt(0)
	s_barrier
	s_cbranch_scc1 .Lres1_tile
.Lres1_done:
.LBB0_225:
	s_mov_b64 s[40:41], 0
.LBB0_226:
	s_andn2_b64 vcc, exec, s[40:41]
	s_cbranch_vccnz .LBB0_7
	v_readlane_b32 s0, v209, 43
	s_cmp_lt_i32 s0, 2
	s_mov_b64 s[40:41], -1
	s_cbranch_scc1 .LBB0_358
	v_readlane_b32 s0, v209, 43
	s_cmp_gt_i32 s0, 2
	s_cbranch_scc0 .LBB0_231
	v_readlane_b32 s0, v209, 19
	s_andn2_b64 vcc, exec, s[62:63]
	s_mov_b32 s8, s61
	s_mov_b32 s78, s0
	v_readlane_b32 s20, v209, 18
	s_mov_b32 s21, s60
	s_cbranch_vccz .LBB0_299
